# Oacc_nmajor
# speedup vs baseline: 1.0159x; 1.0060x over previous
;     __device__ bool next(int i, Unit& u) const { if (!base.next(i >> 1, u)) return false; u.sub = i & 1; return true; }
; #define PG8_STAGE(bufoff, gbase, voff) do { _Pragma("unroll") for (int _i = 0; _i < 2; ++_i) \
;         __builtin_amdgcn_global_load_lds((const unsigned*)((const char*)(gbase) + (voff)[_i]), (PG8_LAS unsigned*)(lds + (bufoff) + ldsw + _i * 8192), 16, 0, 0); } while (0)
; #define PG8_LDA(dst, b, h) do { _Pragma("unroll") for (int m = 0; m < 4; ++m) _Pragma("unroll") for (int k = 0; k < 2; ++k) dst[m][k] = *(const PG8_LAS bf16x8*)(lds + PG8_SA(b, h) + aoff + m * 2048 + k * 1024); } while (0)
; #define PG8_LDB(dst, b, h) do { _Pragma("unroll") for (int n = 0; n < 2; ++n) _Pragma("unroll") for (int k = 0; k < 2; ++k) dst[n][k] = *(const PG8_LAS bf16x8*)(lds + PG8_SB(b, h) + boff + n * 2048 + k * 1024); } while (0)
; #define PG8_WAIT_V(n) asm volatile("s_waitcnt vmcnt(" #n ")" ::: "memory")
; template <class Epi, class Sched, bool ALIGN_EPI = false, bool SP2 = false, bool DUAL = false>
; __device__ __forceinline__ void gemm_phase(PG8_LAS unsigned char* lds, const Gemm g, const Sched& S, const Epi& E) {
;     ...
;         const bool has_next = S.next(ui + 1, nxt);
;         const char* nA = has_next ? (const char*)((DUAL && nxt.sub) ? g.A2 : g.A) + (size_t)nxt.pm * tstep : cA; const char* nB = has_next ? (const char*)((DUAL && nxt.sub) ? g.Bt2 : g.Bt) + (size_t)nxt.pn * tstep : cB;
;         for (int t = 0; t < nt; t += 2) {
;             const bool last = (t == nt - 2);
;             const char* a1 = cA + (size_t)(t + 1) * kstep;
;             const char* a2 = last ? nA : cA + (size_t)(t + 2) * kstep; const char* b2 = last ? nB : cB + (size_t)(t + 2) * kstep;
;             const char* a3 = a2 + kstep; const char* b3 = b2 + kstep;
;             if (last && has_next) S.a_ready(nxt);
;             if constexpr (SP2) {
;             PG8_LDB(B0, 0, 0); PG8_LDB(B1, 0, 1); PG8_SCHED; PG8_LDA(At, 0, 0); PG8_STAGE(PG8_SA(1, 1), a1 + hstep, voffA);
;             PG8_WAIT_V(8); PG8_WAIT_L(0); PG8_BAR; PG8_MMA(0, 0, At, B0); PG8_MMA(0, 1, At, B1); PG8_BAR; PG8_SCHED;
;             PG8_LDA(At, 0, 1); PG8_STAGE(PG8_SB(0, 0), b2, voffB); PG8_STAGE(PG8_SB(0, 1), b2 + hstep, voffB); PG8_STAGE(PG8_SA(0, 0), a2, voffA);
;             PG8_WAIT_V(8); PG8_WAIT_L(0); PG8_BAR; PG8_MMA(1, 0, At, B0); PG8_MMA(1, 1, At, B1); PG8_BAR; PG8_SCHED;
.LBB0_251:
	s_ashr_i32 s87, s86, 31
	s_lshl_b64 s[16:17], s[86:87], 20
	s_add_u32 s92, s58, s16
	s_addc_u32 s93, s59, s17
	s_and_b64 s[16:17], s[4:5], exec
	s_cselect_b32 s7, s93, s11
	s_cselect_b32 s9, s92, s10
	s_ashr_i32 s1, s0, 31
	s_lshl_b64 s[16:17], s[0:1], 20
	s_add_u32 s88, s90, s16
	s_addc_u32 s89, s91, s17
	s_and_b64 s[16:17], s[4:5], exec
	s_cselect_b32 s1, s89, s15
	s_cselect_b32 s45, s88, s14
	s_add_u32 s10, s10, 0x80080
	s_addc_u32 s11, s11, 0
	s_add_u32 s46, s14, 0x100
	s_addc_u32 s47, s15, 0
	s_mov_b32 s48, -2
	s_add_u32 s14, s10, 0xfff80080
	s_addc_u32 s15, s11, -1
	s_cmp_eq_u32 s48, 28
	s_cselect_b32 s17, s7, s15
	s_cselect_b32 s16, s9, s14
	s_cselect_b32 s15, s1, s47
	s_cselect_b32 s14, s45, s46
	s_waitcnt vmcnt(8)
	s_waitcnt lgkmcnt(0)
	s_setprio 1
	s_barrier
	v_mfma_f32_16x16x32_bf16 v[140:143], v[80:83], v[208:211], 0
	v_mfma_f32_16x16x32_bf16 v[140:143], v[84:87], v[212:215], v[140:143]
	v_mfma_f32_16x16x32_bf16 v[124:127], v[80:83], v[216:219], 0
	v_mfma_f32_16x16x32_bf16 v[124:127], v[84:87], v[220:223], v[124:127]
	v_mfma_f32_16x16x32_bf16 v[108:111], v[80:83], v[232:235], 0
	v_mfma_f32_16x16x32_bf16 v[108:111], v[84:87], v[236:239], v[108:111]
	v_mfma_f32_16x16x32_bf16 v[76:79], v[80:83], v[240:243], 0
	v_mfma_f32_16x16x32_bf16 v[76:79], v[84:87], v[244:247], v[76:79]
	v_mfma_f32_16x16x32_bf16 v[132:135], v[88:91], v[208:211], 0
	v_mfma_f32_16x16x32_bf16 v[132:135], v[92:95], v[212:215], v[132:135]
	v_mfma_f32_16x16x32_bf16 v[120:123], v[88:91], v[216:219], 0
	v_mfma_f32_16x16x32_bf16 v[120:123], v[92:95], v[220:223], v[120:123]
	v_mfma_f32_16x16x32_bf16 v[104:107], v[88:91], v[232:235], 0
	v_mfma_f32_16x16x32_bf16 v[104:107], v[92:95], v[236:239], v[104:107]
	v_mfma_f32_16x16x32_bf16 v[72:75], v[88:91], v[240:243], 0
	v_mfma_f32_16x16x32_bf16 v[72:75], v[92:95], v[244:247], v[72:75]
	s_setprio 0
	s_setprio 1
	v_mfma_f32_16x16x32_bf16 v[136:139], v[144:147], v[208:211], 0
	v_mfma_f32_16x16x32_bf16 v[136:139], v[148:151], v[212:215], v[136:139]
	v_mfma_f32_16x16x32_bf16 v[116:119], v[144:147], v[216:219], 0
	v_mfma_f32_16x16x32_bf16 v[116:119], v[148:151], v[220:223], v[116:119]
	v_mfma_f32_16x16x32_bf16 v[100:103], v[144:147], v[232:235], 0
	v_mfma_f32_16x16x32_bf16 v[100:103], v[148:151], v[236:239], v[100:103]
	v_mfma_f32_16x16x32_bf16 v[68:71], v[144:147], v[240:243], 0
	v_mfma_f32_16x16x32_bf16 v[68:71], v[148:151], v[244:247], v[68:71]
	v_mfma_f32_16x16x32_bf16 v[128:131], v[152:155], v[208:211], 0
	v_mfma_f32_16x16x32_bf16 v[128:131], v[156:159], v[212:215], v[128:131]
	v_mfma_f32_16x16x32_bf16 v[112:115], v[152:155], v[216:219], 0
	v_mfma_f32_16x16x32_bf16 v[112:115], v[156:159], v[220:223], v[112:115]
	v_mfma_f32_16x16x32_bf16 v[96:99], v[152:155], v[232:235], 0
	v_mfma_f32_16x16x32_bf16 v[96:99], v[156:159], v[236:239], v[96:99]
	v_mfma_f32_16x16x32_bf16 v[64:67], v[152:155], v[240:243], 0
	v_mfma_f32_16x16x32_bf16 v[64:67], v[156:159], v[244:247], v[64:67]
	s_barrier
	s_setprio 0
	v_lshl_add_u64 v[192:193], s[10:11], 0, v[186:187]
	s_add_i32 m0, s19, 0xc000
	s_nop 0
	global_load_lds_dwordx4 v[192:193], off
	v_lshl_add_u64 v[192:193], s[10:11], 0, v[188:189]
	s_add_i32 m0, s19, 0xe000
	s_nop 0
	global_load_lds_dwordx4 v[192:193], off
	s_add_i32 s49, s31, s18
	v_lshl_add_u64 v[192:193], s[14:15], 0, v[166:167]
	s_mov_b32 m0, s49
	ds_read_b128 v[208:211], v203 offset:16384
	ds_read_b128 v[212:215], v203 offset:17408
	ds_read_b128 v[216:219], v203 offset:18432
	ds_read_b128 v[220:223], v203 offset:19456
	ds_read_b128 v[232:235], v203 offset:20480
	ds_read_b128 v[236:239], v203 offset:21504
	ds_read_b128 v[240:243], v203 offset:22528
	ds_read_b128 v[244:247], v203 offset:23552
	global_load_lds_dwordx4 v[192:193], off
	s_add_i32 m0, s49, 0x2000
	s_add_u32 s50, s14, 0x80000
	v_lshl_add_u64 v[248:249], s[14:15], 0, v[170:171]
	s_addc_u32 s51, s15, 0
	s_add_i32 s49, s34, s18
	global_load_lds_dwordx4 v[248:249], off
	v_lshl_add_u64 v[250:251], s[50:51], 0, v[166:167]
	s_mov_b32 m0, s49
	v_lshl_add_u64 v[252:253], s[16:17], 0, v[168:169]
	global_load_lds_dwordx4 v[250:251], off
	v_lshl_add_u64 v[250:251], s[50:51], 0, v[170:171]
	s_add_i32 m0, s49, 0x2000
	s_nop 0
	global_load_lds_dwordx4 v[250:251], off
	v_lshl_add_u64 v[250:251], s[16:17], 0, v[164:165]
	s_mov_b32 m0, s19
	s_nop 0
	global_load_lds_dwordx4 v[250:251], off
	s_mov_b32 m0, s20
	s_nop 0
	global_load_lds_dwordx4 v[252:253], off
	s_waitcnt vmcnt(8)
	s_waitcnt lgkmcnt(0)
	s_setprio 1
	s_barrier
	v_mfma_f32_16x16x32_bf16 v[60:63], v[80:83], v[208:211], 0
	v_mfma_f32_16x16x32_bf16 v[60:63], v[84:87], v[212:215], v[60:63]
	v_mfma_f32_16x16x32_bf16 v[44:47], v[80:83], v[216:219], 0
	v_mfma_f32_16x16x32_bf16 v[44:47], v[84:87], v[220:223], v[44:47]
	v_mfma_f32_16x16x32_bf16 v[28:31], v[80:83], v[232:235], 0
	v_mfma_f32_16x16x32_bf16 v[28:31], v[84:87], v[236:239], v[28:31]
	v_mfma_f32_16x16x32_bf16 v[12:15], v[80:83], v[240:243], 0
	v_mfma_f32_16x16x32_bf16 v[12:15], v[84:87], v[244:247], v[12:15]
	v_mfma_f32_16x16x32_bf16 v[56:59], v[88:91], v[208:211], 0
	v_mfma_f32_16x16x32_bf16 v[56:59], v[92:95], v[212:215], v[56:59]
	v_mfma_f32_16x16x32_bf16 v[40:43], v[88:91], v[216:219], 0
	v_mfma_f32_16x16x32_bf16 v[40:43], v[92:95], v[220:223], v[40:43]
	v_mfma_f32_16x16x32_bf16 v[24:27], v[88:91], v[232:235], 0
	v_mfma_f32_16x16x32_bf16 v[24:27], v[92:95], v[236:239], v[24:27]
	v_mfma_f32_16x16x32_bf16 v[8:11], v[88:91], v[240:243], 0
	v_mfma_f32_16x16x32_bf16 v[8:11], v[92:95], v[244:247], v[8:11]
	s_setprio 0
	s_setprio 1
	v_mfma_f32_16x16x32_bf16 v[52:55], v[144:147], v[208:211], 0
	v_mfma_f32_16x16x32_bf16 v[52:55], v[148:151], v[212:215], v[52:55]
	v_mfma_f32_16x16x32_bf16 v[36:39], v[144:147], v[216:219], 0
	v_mfma_f32_16x16x32_bf16 v[36:39], v[148:151], v[220:223], v[36:39]
	v_mfma_f32_16x16x32_bf16 v[20:23], v[144:147], v[232:235], 0
	v_mfma_f32_16x16x32_bf16 v[20:23], v[148:151], v[236:239], v[20:23]
	v_mfma_f32_16x16x32_bf16 v[4:7], v[144:147], v[240:243], 0
	v_mfma_f32_16x16x32_bf16 v[4:7], v[148:151], v[244:247], v[4:7]
	v_mfma_f32_16x16x32_bf16 v[48:51], v[152:155], v[208:211], 0
	v_mfma_f32_16x16x32_bf16 v[48:51], v[156:159], v[212:215], v[48:51]
	v_mfma_f32_16x16x32_bf16 v[32:35], v[152:155], v[216:219], 0
	v_mfma_f32_16x16x32_bf16 v[32:35], v[156:159], v[220:223], v[32:35]
	v_mfma_f32_16x16x32_bf16 v[16:19], v[152:155], v[232:235], 0
	v_mfma_f32_16x16x32_bf16 v[16:19], v[156:159], v[236:239], v[16:19]
	v_mfma_f32_16x16x32_bf16 v[0:3], v[152:155], v[240:243], 0
	v_mfma_f32_16x16x32_bf16 v[0:3], v[156:159], v[244:247], v[0:3]
	s_barrier
; #define PG8_STAGE(bufoff, gbase, voff) do { _Pragma("unroll") for (int _i = 0; _i < 2; ++_i) \
;         __builtin_amdgcn_global_load_lds((const unsigned*)((const char*)(gbase) + (voff)[_i]), (PG8_LAS unsigned*)(lds + (bufoff) + ldsw + _i * 8192), 16, 0, 0); } while (0)
; #define PG8_LDA(dst, b, h) do { _Pragma("unroll") for (int m = 0; m < 4; ++m) _Pragma("unroll") for (int k = 0; k < 2; ++k) dst[m][k] = *(const PG8_LAS bf16x8*)(lds + PG8_SA(b, h) + aoff + m * 2048 + k * 1024); } while (0)
; #define PG8_LDB(dst, b, h) do { _Pragma("unroll") for (int n = 0; n < 2; ++n) _Pragma("unroll") for (int k = 0; k < 2; ++k) dst[n][k] = *(const PG8_LAS bf16x8*)(lds + PG8_SB(b, h) + boff + n * 2048 + k * 1024); } while (0)
; #define PG8_MMA(ai, bj, At, Bt) do { __builtin_amdgcn_s_setprio(1); _Pragma("unroll") for (int m = 0; m < 4; ++m) _Pragma("unroll") for (int n = 0; n < 2; ++n) _Pragma("unroll") for (int k = 0; k < 2; ++k) \
;         acc[ai][bj][m][n] = __builtin_amdgcn_mfma_f32_16x16x32_bf16(Bt[n][k], At[m][k], acc[ai][bj][m][n], 0, 0, 0); __builtin_amdgcn_s_setprio(0); } while (0)
; #define PG8_WAIT_V(n) asm volatile("s_waitcnt vmcnt(" #n ")" ::: "memory")
; #define PG8_WAIT_L(n) asm volatile("s_waitcnt lgkmcnt(" #n ")" ::: "memory")
; #define PG8_BAR __builtin_amdgcn_s_barrier()
; #define PG8_SCHED __builtin_amdgcn_sched_barrier(0)
; template <class Epi, class Sched, bool ALIGN_EPI = false, bool SP2 = false, bool DUAL = false>
; __device__ __forceinline__ void gemm_phase(PG8_LAS unsigned char* lds, const Gemm g, const Sched& S, const Epi& E) {
;     ...
;             PG8_LDB(B0, 1, 0); PG8_LDB(B1, 1, 1); PG8_SCHED; PG8_LDA(At, 1, 0); PG8_STAGE(PG8_SA(0, 1), a2 + hstep, voffA);
;             PG8_WAIT_V(8); PG8_WAIT_L(0); PG8_BAR; PG8_MMA(0, 0, At, B0); PG8_MMA(0, 1, At, B1); PG8_BAR; PG8_SCHED;
;             PG8_LDA(At, 1, 1); PG8_STAGE(PG8_SB(1, 0), b3, voffB); PG8_STAGE(PG8_SB(1, 1), b3 + hstep, voffB); PG8_STAGE(PG8_SA(1, 0), a3, voffA);
;             PG8_WAIT_V(8); PG8_WAIT_L(0); PG8_BAR; PG8_MMA(1, 0, At, B0); PG8_MMA(1, 1, At, B1); PG8_BAR; PG8_SCHED;
	s_setprio 0
	s_add_i32 s49, 0, 0x18000
	s_add_i32 s50, 0, 0x1c000
	v_add_u32_e32 v92, s49, v196
	v_add_u32_e32 v156, s50, v196
	ds_read_b128 v[80:83], v92
	ds_read_b128 v[84:87], v92 offset:1024
	ds_read_b128 v[88:91], v92 offset:2048
	ds_read_b128 v[92:95], v92 offset:3072
	ds_read_b128 v[144:147], v156
	ds_read_b128 v[148:151], v156 offset:1024
	ds_read_b128 v[152:155], v156 offset:2048
	ds_read_b128 v[156:159], v156 offset:3072
	s_add_u32 s16, s16, 0x80000
	s_addc_u32 s17, s17, 0
	s_mov_b32 m0, s21
	v_lshl_add_u64 v[228:229], s[16:17], 0, v[164:165]
	ds_read_b128 v[208:211], v203 offset:32768
	ds_read_b128 v[212:215], v203 offset:33792
	ds_read_b128 v[216:219], v203 offset:34816
	ds_read_b128 v[220:223], v203 offset:35840
	ds_read_b128 v[232:235], v203 offset:36864
	ds_read_b128 v[236:239], v203 offset:37888
	ds_read_b128 v[240:243], v203 offset:38912
	ds_read_b128 v[244:247], v203 offset:39936
	global_load_lds_dwordx4 v[228:229], off
	v_lshl_add_u64 v[228:229], s[16:17], 0, v[168:169]
	s_mov_b32 m0, s22
	s_nop 0
	global_load_lds_dwordx4 v[228:229], off
	s_waitcnt vmcnt(8)
	s_waitcnt lgkmcnt(0)
	s_setprio 1
	s_barrier
	v_mfma_f32_16x16x32_bf16 v[140:143], v[80:83], v[208:211], v[140:143]
	v_mfma_f32_16x16x32_bf16 v[140:143], v[84:87], v[212:215], v[140:143]
	v_mfma_f32_16x16x32_bf16 v[124:127], v[80:83], v[216:219], v[124:127]
	v_mfma_f32_16x16x32_bf16 v[124:127], v[84:87], v[220:223], v[124:127]
	v_mfma_f32_16x16x32_bf16 v[108:111], v[80:83], v[232:235], v[108:111]
	v_mfma_f32_16x16x32_bf16 v[108:111], v[84:87], v[236:239], v[108:111]
	v_mfma_f32_16x16x32_bf16 v[76:79], v[80:83], v[240:243], v[76:79]
	v_mfma_f32_16x16x32_bf16 v[76:79], v[84:87], v[244:247], v[76:79]
	v_mfma_f32_16x16x32_bf16 v[132:135], v[88:91], v[208:211], v[132:135]
	v_mfma_f32_16x16x32_bf16 v[132:135], v[92:95], v[212:215], v[132:135]
	v_mfma_f32_16x16x32_bf16 v[120:123], v[88:91], v[216:219], v[120:123]
	v_mfma_f32_16x16x32_bf16 v[120:123], v[92:95], v[220:223], v[120:123]
	v_mfma_f32_16x16x32_bf16 v[104:107], v[88:91], v[232:235], v[104:107]
	v_mfma_f32_16x16x32_bf16 v[104:107], v[92:95], v[236:239], v[104:107]
	v_mfma_f32_16x16x32_bf16 v[72:75], v[88:91], v[240:243], v[72:75]
	v_mfma_f32_16x16x32_bf16 v[72:75], v[92:95], v[244:247], v[72:75]
	s_setprio 0
	s_setprio 1
	v_mfma_f32_16x16x32_bf16 v[136:139], v[144:147], v[208:211], v[136:139]
	v_mfma_f32_16x16x32_bf16 v[136:139], v[148:151], v[212:215], v[136:139]
	v_mfma_f32_16x16x32_bf16 v[116:119], v[144:147], v[216:219], v[116:119]
	v_mfma_f32_16x16x32_bf16 v[116:119], v[148:151], v[220:223], v[116:119]
	v_mfma_f32_16x16x32_bf16 v[100:103], v[144:147], v[232:235], v[100:103]
	v_mfma_f32_16x16x32_bf16 v[100:103], v[148:151], v[236:239], v[100:103]
	v_mfma_f32_16x16x32_bf16 v[68:71], v[144:147], v[240:243], v[68:71]
	v_mfma_f32_16x16x32_bf16 v[68:71], v[148:151], v[244:247], v[68:71]
	v_mfma_f32_16x16x32_bf16 v[128:131], v[152:155], v[208:211], v[128:131]
	v_mfma_f32_16x16x32_bf16 v[128:131], v[156:159], v[212:215], v[128:131]
	v_mfma_f32_16x16x32_bf16 v[112:115], v[152:155], v[216:219], v[112:115]
	v_mfma_f32_16x16x32_bf16 v[112:115], v[156:159], v[220:223], v[112:115]
	v_mfma_f32_16x16x32_bf16 v[96:99], v[152:155], v[232:235], v[96:99]
	v_mfma_f32_16x16x32_bf16 v[96:99], v[156:159], v[236:239], v[96:99]
	v_mfma_f32_16x16x32_bf16 v[64:67], v[152:155], v[240:243], v[64:67]
	v_mfma_f32_16x16x32_bf16 v[64:67], v[156:159], v[244:247], v[64:67]
	s_barrier
	s_setprio 0
	s_add_i32 s16, s49, s18
	v_lshl_add_u64 v[192:193], v[192:193], 0, s[76:77]
	s_mov_b32 m0, s16
	ds_read_b128 v[208:211], v203 offset:49152
	ds_read_b128 v[212:215], v203 offset:50176
	ds_read_b128 v[216:219], v203 offset:51200
	ds_read_b128 v[220:223], v203 offset:52224
	ds_read_b128 v[232:235], v203 offset:53248
	ds_read_b128 v[236:239], v203 offset:54272
	ds_read_b128 v[240:243], v203 offset:55296
	ds_read_b128 v[244:247], v203 offset:56320
	global_load_lds_dwordx4 v[192:193], off
	s_add_i32 m0, s16, 0x2000
	s_add_u32 s14, s14, 0x80080
	v_lshl_add_u64 v[192:193], v[248:249], 0, s[76:77]
	s_addc_u32 s15, s15, 0
	s_add_i32 s16, s50, s18
	global_load_lds_dwordx4 v[192:193], off
	v_lshl_add_u64 v[192:193], s[14:15], 0, v[166:167]
	s_mov_b32 m0, s16
	s_nop 0
	global_load_lds_dwordx4 v[192:193], off
	v_lshl_add_u64 v[192:193], s[14:15], 0, v[170:171]
	s_add_i32 m0, s16, 0x2000
	s_nop 0
	global_load_lds_dwordx4 v[192:193], off
	v_lshl_add_u64 v[192:193], v[250:251], 0, s[76:77]
	s_mov_b32 m0, s27
	s_nop 0
	global_load_lds_dwordx4 v[192:193], off
	v_lshl_add_u64 v[192:193], v[252:253], 0, s[76:77]
	s_mov_b32 m0, s28
	s_nop 0
	global_load_lds_dwordx4 v[192:193], off
	s_waitcnt vmcnt(8)
	s_waitcnt lgkmcnt(0)
	s_setprio 1
	s_barrier
	v_mfma_f32_16x16x32_bf16 v[60:63], v[80:83], v[208:211], v[60:63]
	v_mfma_f32_16x16x32_bf16 v[60:63], v[84:87], v[212:215], v[60:63]
	v_mfma_f32_16x16x32_bf16 v[44:47], v[80:83], v[216:219], v[44:47]
	v_mfma_f32_16x16x32_bf16 v[44:47], v[84:87], v[220:223], v[44:47]
	v_mfma_f32_16x16x32_bf16 v[28:31], v[80:83], v[232:235], v[28:31]
	v_mfma_f32_16x16x32_bf16 v[28:31], v[84:87], v[236:239], v[28:31]
	v_mfma_f32_16x16x32_bf16 v[12:15], v[80:83], v[240:243], v[12:15]
	v_mfma_f32_16x16x32_bf16 v[12:15], v[84:87], v[244:247], v[12:15]
	v_mfma_f32_16x16x32_bf16 v[56:59], v[88:91], v[208:211], v[56:59]
	v_mfma_f32_16x16x32_bf16 v[56:59], v[92:95], v[212:215], v[56:59]
	v_mfma_f32_16x16x32_bf16 v[40:43], v[88:91], v[216:219], v[40:43]
	v_mfma_f32_16x16x32_bf16 v[40:43], v[92:95], v[220:223], v[40:43]
	v_mfma_f32_16x16x32_bf16 v[24:27], v[88:91], v[232:235], v[24:27]
	v_mfma_f32_16x16x32_bf16 v[24:27], v[92:95], v[236:239], v[24:27]
	v_mfma_f32_16x16x32_bf16 v[8:11], v[88:91], v[240:243], v[8:11]
	v_mfma_f32_16x16x32_bf16 v[8:11], v[92:95], v[244:247], v[8:11]
	s_setprio 0
	s_setprio 1
	v_mfma_f32_16x16x32_bf16 v[52:55], v[144:147], v[208:211], v[52:55]
	v_mfma_f32_16x16x32_bf16 v[52:55], v[148:151], v[212:215], v[52:55]
	v_mfma_f32_16x16x32_bf16 v[36:39], v[144:147], v[216:219], v[36:39]
	v_mfma_f32_16x16x32_bf16 v[36:39], v[148:151], v[220:223], v[36:39]
	v_mfma_f32_16x16x32_bf16 v[20:23], v[144:147], v[232:235], v[20:23]
	v_mfma_f32_16x16x32_bf16 v[20:23], v[148:151], v[236:239], v[20:23]
	v_mfma_f32_16x16x32_bf16 v[4:7], v[144:147], v[240:243], v[4:7]
	v_mfma_f32_16x16x32_bf16 v[4:7], v[148:151], v[244:247], v[4:7]
	v_mfma_f32_16x16x32_bf16 v[48:51], v[152:155], v[208:211], v[48:51]
	v_mfma_f32_16x16x32_bf16 v[48:51], v[156:159], v[212:215], v[48:51]
	v_mfma_f32_16x16x32_bf16 v[32:35], v[152:155], v[216:219], v[32:35]
	v_mfma_f32_16x16x32_bf16 v[32:35], v[156:159], v[220:223], v[32:35]
	v_mfma_f32_16x16x32_bf16 v[16:19], v[152:155], v[232:235], v[16:19]
	v_mfma_f32_16x16x32_bf16 v[16:19], v[156:159], v[236:239], v[16:19]
	v_mfma_f32_16x16x32_bf16 v[0:3], v[152:155], v[240:243], v[0:3]
	v_mfma_f32_16x16x32_bf16 v[0:3], v[156:159], v[244:247], v[0:3]
	s_barrier
	s_setprio 0
	s_add_i32 s48, s48, 2
	s_add_u32 s10, s10, 0x100
	s_addc_u32 s11, s11, 0
	s_add_u32 s46, s46, 0x100
	s_addc_u32 s47, s47, 0
; #define PG8_STAGE(bufoff, gbase, voff) do { _Pragma("unroll") for (int _i = 0; _i < 2; ++_i) \
;         __builtin_amdgcn_global_load_lds((const unsigned*)((const char*)(gbase) + (voff)[_i]), (PG8_LAS unsigned*)(lds + (bufoff) + ldsw + _i * 8192), 16, 0, 0); } while (0)
; #define PG8_LDA(dst, b, h) do { _Pragma("unroll") for (int m = 0; m < 4; ++m) _Pragma("unroll") for (int k = 0; k < 2; ++k) dst[m][k] = *(const PG8_LAS bf16x8*)(lds + PG8_SA(b, h) + aoff + m * 2048 + k * 1024); } while (0)
; #define PG8_LDB(dst, b, h) do { _Pragma("unroll") for (int n = 0; n < 2; ++n) _Pragma("unroll") for (int k = 0; k < 2; ++k) dst[n][k] = *(const PG8_LAS bf16x8*)(lds + PG8_SB(b, h) + boff + n * 2048 + k * 1024); } while (0)
; #define PG8_MMA(ai, bj, At, Bt) do { __builtin_amdgcn_s_setprio(1); _Pragma("unroll") for (int m = 0; m < 4; ++m) _Pragma("unroll") for (int n = 0; n < 2; ++n) _Pragma("unroll") for (int k = 0; k < 2; ++k) \
;         acc[ai][bj][m][n] = __builtin_amdgcn_mfma_f32_16x16x32_bf16(Bt[n][k], At[m][k], acc[ai][bj][m][n], 0, 0, 0); __builtin_amdgcn_s_setprio(0); } while (0)
; #define PG8_WAIT_V(n) asm volatile("s_waitcnt vmcnt(" #n ")" ::: "memory")
; #define PG8_WAIT_L(n) asm volatile("s_waitcnt lgkmcnt(" #n ")" ::: "memory")
; #define PG8_BAR __builtin_amdgcn_s_barrier()
; #define PG8_SCHED __builtin_amdgcn_sched_barrier(0)
; template <class Epi, class Sched, bool ALIGN_EPI = false, bool SP2 = false, bool DUAL = false>
; __device__ __forceinline__ void gemm_phase(PG8_LAS unsigned char* lds, const Gemm g, const Sched& S, const Epi& E) {
;     ...
;             PG8_LDB(B0, 0, 0); PG8_LDB(B1, 0, 1); PG8_SCHED; PG8_LDA(At, 0, 0); PG8_STAGE(PG8_SA(1, 1), a1 + hstep, voffA);
;             PG8_WAIT_V(8); PG8_WAIT_L(0); PG8_BAR; PG8_MMA(0, 0, At, B0); PG8_MMA(0, 1, At, B1); PG8_BAR; PG8_SCHED;
;             PG8_LDA(At, 0, 1); PG8_STAGE(PG8_SB(0, 0), b2, voffB); PG8_STAGE(PG8_SB(0, 1), b2 + hstep, voffB); PG8_STAGE(PG8_SA(0, 0), a2, voffA);
;             PG8_WAIT_V(8); PG8_WAIT_L(0); PG8_BAR; PG8_MMA(1, 0, At, B0); PG8_MMA(1, 1, At, B1); PG8_BAR; PG8_SCHED;
.LBB0_252:
	ds_read_b128 v[80:83], v199
	ds_read_b128 v[84:87], v199 offset:1024
	ds_read_b128 v[88:91], v199 offset:2048
	ds_read_b128 v[92:95], v199 offset:3072
	ds_read_b128 v[144:147], v202
	ds_read_b128 v[148:151], v202 offset:1024
	ds_read_b128 v[152:155], v202 offset:2048
	ds_read_b128 v[156:159], v202 offset:3072
	s_add_u32 s14, s10, 0xfff80080
	s_addc_u32 s15, s11, -1
	s_cmp_eq_u32 s48, 28
	s_cselect_b32 s17, s7, s15
	s_cselect_b32 s16, s9, s14
	s_cselect_b32 s15, s1, s47
	s_cselect_b32 s14, s45, s46
	v_lshl_add_u64 v[192:193], s[10:11], 0, v[186:187]
	s_add_i32 m0, s19, 0xc000
	ds_read_b128 v[208:211], v203
	ds_read_b128 v[212:215], v203 offset:1024
	ds_read_b128 v[216:219], v203 offset:2048
	ds_read_b128 v[220:223], v203 offset:3072
	ds_read_b128 v[232:235], v203 offset:4096
	ds_read_b128 v[236:239], v203 offset:5120
	ds_read_b128 v[240:243], v203 offset:6144
	ds_read_b128 v[244:247], v203 offset:7168
	global_load_lds_dwordx4 v[192:193], off
	v_lshl_add_u64 v[192:193], s[10:11], 0, v[188:189]
	s_add_i32 m0, s19, 0xe000
	s_nop 0
	global_load_lds_dwordx4 v[192:193], off
	s_waitcnt vmcnt(8)
	s_waitcnt lgkmcnt(0)
	s_setprio 1
	s_barrier
	v_mfma_f32_16x16x32_bf16 v[140:143], v[80:83], v[208:211], v[140:143]
	v_mfma_f32_16x16x32_bf16 v[140:143], v[84:87], v[212:215], v[140:143]
	v_mfma_f32_16x16x32_bf16 v[124:127], v[80:83], v[216:219], v[124:127]
	v_mfma_f32_16x16x32_bf16 v[124:127], v[84:87], v[220:223], v[124:127]
	v_mfma_f32_16x16x32_bf16 v[108:111], v[80:83], v[232:235], v[108:111]
	v_mfma_f32_16x16x32_bf16 v[108:111], v[84:87], v[236:239], v[108:111]
	v_mfma_f32_16x16x32_bf16 v[76:79], v[80:83], v[240:243], v[76:79]
	v_mfma_f32_16x16x32_bf16 v[76:79], v[84:87], v[244:247], v[76:79]
	v_mfma_f32_16x16x32_bf16 v[132:135], v[88:91], v[208:211], v[132:135]
	v_mfma_f32_16x16x32_bf16 v[132:135], v[92:95], v[212:215], v[132:135]
	v_mfma_f32_16x16x32_bf16 v[120:123], v[88:91], v[216:219], v[120:123]
	v_mfma_f32_16x16x32_bf16 v[120:123], v[92:95], v[220:223], v[120:123]
	v_mfma_f32_16x16x32_bf16 v[104:107], v[88:91], v[232:235], v[104:107]
	v_mfma_f32_16x16x32_bf16 v[104:107], v[92:95], v[236:239], v[104:107]
	v_mfma_f32_16x16x32_bf16 v[72:75], v[88:91], v[240:243], v[72:75]
	v_mfma_f32_16x16x32_bf16 v[72:75], v[92:95], v[244:247], v[72:75]
	s_setprio 0
	s_setprio 1
	v_mfma_f32_16x16x32_bf16 v[136:139], v[144:147], v[208:211], v[136:139]
	v_mfma_f32_16x16x32_bf16 v[136:139], v[148:151], v[212:215], v[136:139]
	v_mfma_f32_16x16x32_bf16 v[116:119], v[144:147], v[216:219], v[116:119]
	v_mfma_f32_16x16x32_bf16 v[116:119], v[148:151], v[220:223], v[116:119]
	v_mfma_f32_16x16x32_bf16 v[100:103], v[144:147], v[232:235], v[100:103]
	v_mfma_f32_16x16x32_bf16 v[100:103], v[148:151], v[236:239], v[100:103]
	v_mfma_f32_16x16x32_bf16 v[68:71], v[144:147], v[240:243], v[68:71]
	v_mfma_f32_16x16x32_bf16 v[68:71], v[148:151], v[244:247], v[68:71]
	v_mfma_f32_16x16x32_bf16 v[128:131], v[152:155], v[208:211], v[128:131]
	v_mfma_f32_16x16x32_bf16 v[128:131], v[156:159], v[212:215], v[128:131]
	v_mfma_f32_16x16x32_bf16 v[112:115], v[152:155], v[216:219], v[112:115]
	v_mfma_f32_16x16x32_bf16 v[112:115], v[156:159], v[220:223], v[112:115]
	v_mfma_f32_16x16x32_bf16 v[96:99], v[152:155], v[232:235], v[96:99]
	v_mfma_f32_16x16x32_bf16 v[96:99], v[156:159], v[236:239], v[96:99]
	v_mfma_f32_16x16x32_bf16 v[64:67], v[152:155], v[240:243], v[64:67]
	v_mfma_f32_16x16x32_bf16 v[64:67], v[156:159], v[244:247], v[64:67]
	s_barrier
	s_setprio 0
	s_add_i32 s49, s31, s18
	v_lshl_add_u64 v[192:193], s[14:15], 0, v[166:167]
	s_mov_b32 m0, s49
	ds_read_b128 v[208:211], v203 offset:16384
	ds_read_b128 v[212:215], v203 offset:17408
	ds_read_b128 v[216:219], v203 offset:18432
	ds_read_b128 v[220:223], v203 offset:19456
	ds_read_b128 v[232:235], v203 offset:20480
	ds_read_b128 v[236:239], v203 offset:21504
	ds_read_b128 v[240:243], v203 offset:22528
	ds_read_b128 v[244:247], v203 offset:23552
	global_load_lds_dwordx4 v[192:193], off
	s_add_i32 m0, s49, 0x2000
	s_add_u32 s50, s14, 0x80000
	v_lshl_add_u64 v[248:249], s[14:15], 0, v[170:171]
	s_addc_u32 s51, s15, 0
	s_add_i32 s49, s34, s18
	global_load_lds_dwordx4 v[248:249], off
	v_lshl_add_u64 v[250:251], s[50:51], 0, v[166:167]
	s_mov_b32 m0, s49
	v_lshl_add_u64 v[252:253], s[16:17], 0, v[168:169]
	global_load_lds_dwordx4 v[250:251], off
	v_lshl_add_u64 v[250:251], s[50:51], 0, v[170:171]
	s_add_i32 m0, s49, 0x2000
	s_nop 0
	global_load_lds_dwordx4 v[250:251], off
	v_lshl_add_u64 v[250:251], s[16:17], 0, v[164:165]
	s_mov_b32 m0, s19
	s_nop 0
	global_load_lds_dwordx4 v[250:251], off
	s_mov_b32 m0, s20
	s_nop 0
	global_load_lds_dwordx4 v[252:253], off
	s_waitcnt vmcnt(8)
	s_waitcnt lgkmcnt(0)
	s_setprio 1
	s_barrier
; #define PG8_STAGE(bufoff, gbase, voff) do { _Pragma("unroll") for (int _i = 0; _i < 2; ++_i) \
;         __builtin_amdgcn_global_load_lds((const unsigned*)((const char*)(gbase) + (voff)[_i]), (PG8_LAS unsigned*)(lds + (bufoff) + ldsw + _i * 8192), 16, 0, 0); } while (0)
; #define PG8_LDA(dst, b, h) do { _Pragma("unroll") for (int m = 0; m < 4; ++m) _Pragma("unroll") for (int k = 0; k < 2; ++k) dst[m][k] = *(const PG8_LAS bf16x8*)(lds + PG8_SA(b, h) + aoff + m * 2048 + k * 1024); } while (0)
; #define PG8_LDB(dst, b, h) do { _Pragma("unroll") for (int n = 0; n < 2; ++n) _Pragma("unroll") for (int k = 0; k < 2; ++k) dst[n][k] = *(const PG8_LAS bf16x8*)(lds + PG8_SB(b, h) + boff + n * 2048 + k * 1024); } while (0)
; #define PG8_MMA(ai, bj, At, Bt) do { __builtin_amdgcn_s_setprio(1); _Pragma("unroll") for (int m = 0; m < 4; ++m) _Pragma("unroll") for (int n = 0; n < 2; ++n) _Pragma("unroll") for (int k = 0; k < 2; ++k) \
;         acc[ai][bj][m][n] = __builtin_amdgcn_mfma_f32_16x16x32_bf16(Bt[n][k], At[m][k], acc[ai][bj][m][n], 0, 0, 0); __builtin_amdgcn_s_setprio(0); } while (0)
; #define PG8_WAIT_V(n) asm volatile("s_waitcnt vmcnt(" #n ")" ::: "memory")
; #define PG8_WAIT_L(n) asm volatile("s_waitcnt lgkmcnt(" #n ")" ::: "memory")
; #define PG8_BAR __builtin_amdgcn_s_barrier()
; #define PG8_SCHED __builtin_amdgcn_sched_barrier(0)
; template <class Epi, class Sched, bool ALIGN_EPI = false, bool SP2 = false, bool DUAL = false>
; __device__ __forceinline__ void gemm_phase(PG8_LAS unsigned char* lds, const Gemm g, const Sched& S, const Epi& E) {
;     ...
;             PG8_WAIT_V(8); PG8_WAIT_L(0); PG8_BAR; PG8_MMA(1, 0, At, B0); PG8_MMA(1, 1, At, B1); PG8_BAR; PG8_SCHED;
;             PG8_LDB(B0, 1, 0); PG8_LDB(B1, 1, 1); PG8_SCHED; PG8_LDA(At, 1, 0); PG8_STAGE(PG8_SA(0, 1), a2 + hstep, voffA);
;             PG8_WAIT_V(8); PG8_WAIT_L(0); PG8_BAR; PG8_MMA(0, 0, At, B0); PG8_MMA(0, 1, At, B1); PG8_BAR; PG8_SCHED;
	v_mfma_f32_16x16x32_bf16 v[60:63], v[80:83], v[208:211], v[60:63]
	v_mfma_f32_16x16x32_bf16 v[60:63], v[84:87], v[212:215], v[60:63]
	v_mfma_f32_16x16x32_bf16 v[44:47], v[80:83], v[216:219], v[44:47]
	v_mfma_f32_16x16x32_bf16 v[44:47], v[84:87], v[220:223], v[44:47]
	v_mfma_f32_16x16x32_bf16 v[28:31], v[80:83], v[232:235], v[28:31]
	v_mfma_f32_16x16x32_bf16 v[28:31], v[84:87], v[236:239], v[28:31]
	v_mfma_f32_16x16x32_bf16 v[12:15], v[80:83], v[240:243], v[12:15]
	v_mfma_f32_16x16x32_bf16 v[12:15], v[84:87], v[244:247], v[12:15]
	v_mfma_f32_16x16x32_bf16 v[56:59], v[88:91], v[208:211], v[56:59]
	v_mfma_f32_16x16x32_bf16 v[56:59], v[92:95], v[212:215], v[56:59]
	v_mfma_f32_16x16x32_bf16 v[40:43], v[88:91], v[216:219], v[40:43]
	v_mfma_f32_16x16x32_bf16 v[40:43], v[92:95], v[220:223], v[40:43]
	v_mfma_f32_16x16x32_bf16 v[24:27], v[88:91], v[232:235], v[24:27]
	v_mfma_f32_16x16x32_bf16 v[24:27], v[92:95], v[236:239], v[24:27]
	v_mfma_f32_16x16x32_bf16 v[8:11], v[88:91], v[240:243], v[8:11]
	v_mfma_f32_16x16x32_bf16 v[8:11], v[92:95], v[244:247], v[8:11]
	s_setprio 0
	s_setprio 1
	v_mfma_f32_16x16x32_bf16 v[52:55], v[144:147], v[208:211], v[52:55]
	v_mfma_f32_16x16x32_bf16 v[52:55], v[148:151], v[212:215], v[52:55]
	v_mfma_f32_16x16x32_bf16 v[36:39], v[144:147], v[216:219], v[36:39]
	v_mfma_f32_16x16x32_bf16 v[36:39], v[148:151], v[220:223], v[36:39]
	v_mfma_f32_16x16x32_bf16 v[20:23], v[144:147], v[232:235], v[20:23]
	v_mfma_f32_16x16x32_bf16 v[20:23], v[148:151], v[236:239], v[20:23]
	v_mfma_f32_16x16x32_bf16 v[4:7], v[144:147], v[240:243], v[4:7]
	v_mfma_f32_16x16x32_bf16 v[4:7], v[148:151], v[244:247], v[4:7]
	v_mfma_f32_16x16x32_bf16 v[48:51], v[152:155], v[208:211], v[48:51]
	v_mfma_f32_16x16x32_bf16 v[48:51], v[156:159], v[212:215], v[48:51]
	v_mfma_f32_16x16x32_bf16 v[32:35], v[152:155], v[216:219], v[32:35]
	v_mfma_f32_16x16x32_bf16 v[32:35], v[156:159], v[220:223], v[32:35]
	v_mfma_f32_16x16x32_bf16 v[16:19], v[152:155], v[232:235], v[16:19]
	v_mfma_f32_16x16x32_bf16 v[16:19], v[156:159], v[236:239], v[16:19]
	v_mfma_f32_16x16x32_bf16 v[0:3], v[152:155], v[240:243], v[0:3]
	v_mfma_f32_16x16x32_bf16 v[0:3], v[156:159], v[244:247], v[0:3]
	s_barrier
	s_setprio 0
	s_add_i32 s49, 0, 0x18000
	s_add_i32 s50, 0, 0x1c000
	v_add_u32_e32 v92, s49, v196
	v_add_u32_e32 v156, s50, v196
	ds_read_b128 v[80:83], v92
	ds_read_b128 v[84:87], v92 offset:1024
	ds_read_b128 v[88:91], v92 offset:2048
	ds_read_b128 v[92:95], v92 offset:3072
	ds_read_b128 v[144:147], v156
	ds_read_b128 v[148:151], v156 offset:1024
	ds_read_b128 v[152:155], v156 offset:2048
	ds_read_b128 v[156:159], v156 offset:3072
	s_add_u32 s16, s16, 0x80000
	s_addc_u32 s17, s17, 0
	s_mov_b32 m0, s21
	v_lshl_add_u64 v[228:229], s[16:17], 0, v[164:165]
	ds_read_b128 v[208:211], v203 offset:32768
	ds_read_b128 v[212:215], v203 offset:33792
	ds_read_b128 v[216:219], v203 offset:34816
	ds_read_b128 v[220:223], v203 offset:35840
	ds_read_b128 v[232:235], v203 offset:36864
	ds_read_b128 v[236:239], v203 offset:37888
	ds_read_b128 v[240:243], v203 offset:38912
	ds_read_b128 v[244:247], v203 offset:39936
	global_load_lds_dwordx4 v[228:229], off
	v_lshl_add_u64 v[228:229], s[16:17], 0, v[168:169]
	s_mov_b32 m0, s22
	s_nop 0
	global_load_lds_dwordx4 v[228:229], off
	s_waitcnt vmcnt(8)
	s_waitcnt lgkmcnt(0)
	s_setprio 1
	s_barrier
	v_mfma_f32_16x16x32_bf16 v[140:143], v[80:83], v[208:211], v[140:143]
	v_mfma_f32_16x16x32_bf16 v[140:143], v[84:87], v[212:215], v[140:143]
	v_mfma_f32_16x16x32_bf16 v[124:127], v[80:83], v[216:219], v[124:127]
	v_mfma_f32_16x16x32_bf16 v[124:127], v[84:87], v[220:223], v[124:127]
	v_mfma_f32_16x16x32_bf16 v[108:111], v[80:83], v[232:235], v[108:111]
	v_mfma_f32_16x16x32_bf16 v[108:111], v[84:87], v[236:239], v[108:111]
	v_mfma_f32_16x16x32_bf16 v[76:79], v[80:83], v[240:243], v[76:79]
	v_mfma_f32_16x16x32_bf16 v[76:79], v[84:87], v[244:247], v[76:79]
	v_mfma_f32_16x16x32_bf16 v[132:135], v[88:91], v[208:211], v[132:135]
	v_mfma_f32_16x16x32_bf16 v[132:135], v[92:95], v[212:215], v[132:135]
	v_mfma_f32_16x16x32_bf16 v[120:123], v[88:91], v[216:219], v[120:123]
	v_mfma_f32_16x16x32_bf16 v[120:123], v[92:95], v[220:223], v[120:123]
	v_mfma_f32_16x16x32_bf16 v[104:107], v[88:91], v[232:235], v[104:107]
	v_mfma_f32_16x16x32_bf16 v[104:107], v[92:95], v[236:239], v[104:107]
	v_mfma_f32_16x16x32_bf16 v[72:75], v[88:91], v[240:243], v[72:75]
	v_mfma_f32_16x16x32_bf16 v[72:75], v[92:95], v[244:247], v[72:75]
	s_setprio 0
	s_setprio 1
	v_mfma_f32_16x16x32_bf16 v[136:139], v[144:147], v[208:211], v[136:139]
	v_mfma_f32_16x16x32_bf16 v[136:139], v[148:151], v[212:215], v[136:139]
	v_mfma_f32_16x16x32_bf16 v[116:119], v[144:147], v[216:219], v[116:119]
	v_mfma_f32_16x16x32_bf16 v[116:119], v[148:151], v[220:223], v[116:119]
	v_mfma_f32_16x16x32_bf16 v[100:103], v[144:147], v[232:235], v[100:103]
	v_mfma_f32_16x16x32_bf16 v[100:103], v[148:151], v[236:239], v[100:103]
	v_mfma_f32_16x16x32_bf16 v[68:71], v[144:147], v[240:243], v[68:71]
	v_mfma_f32_16x16x32_bf16 v[68:71], v[148:151], v[244:247], v[68:71]
	v_mfma_f32_16x16x32_bf16 v[128:131], v[152:155], v[208:211], v[128:131]
	v_mfma_f32_16x16x32_bf16 v[128:131], v[156:159], v[212:215], v[128:131]
	v_mfma_f32_16x16x32_bf16 v[112:115], v[152:155], v[216:219], v[112:115]
	v_mfma_f32_16x16x32_bf16 v[112:115], v[156:159], v[220:223], v[112:115]
	v_mfma_f32_16x16x32_bf16 v[96:99], v[152:155], v[232:235], v[96:99]
	v_mfma_f32_16x16x32_bf16 v[96:99], v[156:159], v[236:239], v[96:99]
	v_mfma_f32_16x16x32_bf16 v[64:67], v[152:155], v[240:243], v[64:67]
	v_mfma_f32_16x16x32_bf16 v[64:67], v[156:159], v[244:247], v[64:67]
	s_barrier
; #define PG8_STAGE(bufoff, gbase, voff) do { _Pragma("unroll") for (int _i = 0; _i < 2; ++_i) \
;         __builtin_amdgcn_global_load_lds((const unsigned*)((const char*)(gbase) + (voff)[_i]), (PG8_LAS unsigned*)(lds + (bufoff) + ldsw + _i * 8192), 16, 0, 0); } while (0)
; #define PG8_LDA(dst, b, h) do { _Pragma("unroll") for (int m = 0; m < 4; ++m) _Pragma("unroll") for (int k = 0; k < 2; ++k) dst[m][k] = *(const PG8_LAS bf16x8*)(lds + PG8_SA(b, h) + aoff + m * 2048 + k * 1024); } while (0)
; #define PG8_MMA(ai, bj, At, Bt) do { __builtin_amdgcn_s_setprio(1); _Pragma("unroll") for (int m = 0; m < 4; ++m) _Pragma("unroll") for (int n = 0; n < 2; ++n) _Pragma("unroll") for (int k = 0; k < 2; ++k) \
;         acc[ai][bj][m][n] = __builtin_amdgcn_mfma_f32_16x16x32_bf16(Bt[n][k], At[m][k], acc[ai][bj][m][n], 0, 0, 0); __builtin_amdgcn_s_setprio(0); } while (0)
; #define PG8_WAIT_V(n) asm volatile("s_waitcnt vmcnt(" #n ")" ::: "memory")
; #define PG8_WAIT_L(n) asm volatile("s_waitcnt lgkmcnt(" #n ")" ::: "memory")
; #define PG8_BAR __builtin_amdgcn_s_barrier()
; #define PG8_SCHED __builtin_amdgcn_sched_barrier(0)
; template <class Epi, class Sched, bool ALIGN_EPI = false, bool SP2 = false, bool DUAL = false>
; __device__ __forceinline__ void gemm_phase(PG8_LAS unsigned char* lds, const Gemm g, const Sched& S, const Epi& E) {
;     ...
;             PG8_LDA(At, 1, 1); PG8_STAGE(PG8_SB(1, 0), b3, voffB); PG8_STAGE(PG8_SB(1, 1), b3 + hstep, voffB); PG8_STAGE(PG8_SA(1, 0), a3, voffA);
;             PG8_WAIT_V(8); PG8_WAIT_L(0); PG8_BAR; PG8_MMA(1, 0, At, B0); PG8_MMA(1, 1, At, B1); PG8_BAR; PG8_SCHED;
	s_setprio 0
	s_add_i32 s16, s49, s18
	v_lshl_add_u64 v[192:193], v[192:193], 0, s[76:77]
	s_mov_b32 m0, s16
	ds_read_b128 v[208:211], v203 offset:49152
	ds_read_b128 v[212:215], v203 offset:50176
	ds_read_b128 v[216:219], v203 offset:51200
	ds_read_b128 v[220:223], v203 offset:52224
	ds_read_b128 v[232:235], v203 offset:53248
	ds_read_b128 v[236:239], v203 offset:54272
	ds_read_b128 v[240:243], v203 offset:55296
	ds_read_b128 v[244:247], v203 offset:56320
	global_load_lds_dwordx4 v[192:193], off
	s_add_i32 m0, s16, 0x2000
	s_add_u32 s14, s14, 0x80080
	v_lshl_add_u64 v[192:193], v[248:249], 0, s[76:77]
	s_addc_u32 s15, s15, 0
	s_add_i32 s16, s50, s18
	global_load_lds_dwordx4 v[192:193], off
	v_lshl_add_u64 v[192:193], s[14:15], 0, v[166:167]
	s_mov_b32 m0, s16
	s_nop 0
	global_load_lds_dwordx4 v[192:193], off
	v_lshl_add_u64 v[192:193], s[14:15], 0, v[170:171]
	s_add_i32 m0, s16, 0x2000
	s_nop 0
	global_load_lds_dwordx4 v[192:193], off
	v_lshl_add_u64 v[192:193], v[250:251], 0, s[76:77]
	s_mov_b32 m0, s27
	s_nop 0
	global_load_lds_dwordx4 v[192:193], off
	v_lshl_add_u64 v[192:193], v[252:253], 0, s[76:77]
	s_mov_b32 m0, s28
	s_nop 0
	global_load_lds_dwordx4 v[192:193], off
	s_waitcnt vmcnt(8)
	s_waitcnt lgkmcnt(0)
	s_setprio 1
	s_barrier
	v_mfma_f32_16x16x32_bf16 v[60:63], v[80:83], v[208:211], v[60:63]
	v_mfma_f32_16x16x32_bf16 v[60:63], v[84:87], v[212:215], v[60:63]
	v_mfma_f32_16x16x32_bf16 v[44:47], v[80:83], v[216:219], v[44:47]
	v_mfma_f32_16x16x32_bf16 v[44:47], v[84:87], v[220:223], v[44:47]
	v_mfma_f32_16x16x32_bf16 v[28:31], v[80:83], v[232:235], v[28:31]
	v_mfma_f32_16x16x32_bf16 v[28:31], v[84:87], v[236:239], v[28:31]
	v_mfma_f32_16x16x32_bf16 v[12:15], v[80:83], v[240:243], v[12:15]
	v_mfma_f32_16x16x32_bf16 v[12:15], v[84:87], v[244:247], v[12:15]
	v_mfma_f32_16x16x32_bf16 v[56:59], v[88:91], v[208:211], v[56:59]
	v_mfma_f32_16x16x32_bf16 v[56:59], v[92:95], v[212:215], v[56:59]
	v_mfma_f32_16x16x32_bf16 v[40:43], v[88:91], v[216:219], v[40:43]
	v_mfma_f32_16x16x32_bf16 v[40:43], v[92:95], v[220:223], v[40:43]
	v_mfma_f32_16x16x32_bf16 v[24:27], v[88:91], v[232:235], v[24:27]
	v_mfma_f32_16x16x32_bf16 v[24:27], v[92:95], v[236:239], v[24:27]
	v_mfma_f32_16x16x32_bf16 v[8:11], v[88:91], v[240:243], v[8:11]
	v_mfma_f32_16x16x32_bf16 v[8:11], v[92:95], v[244:247], v[8:11]
	s_setprio 0
	s_setprio 1
	v_mfma_f32_16x16x32_bf16 v[52:55], v[144:147], v[208:211], v[52:55]
	v_mfma_f32_16x16x32_bf16 v[52:55], v[148:151], v[212:215], v[52:55]
	v_mfma_f32_16x16x32_bf16 v[36:39], v[144:147], v[216:219], v[36:39]
	v_mfma_f32_16x16x32_bf16 v[36:39], v[148:151], v[220:223], v[36:39]
	v_mfma_f32_16x16x32_bf16 v[20:23], v[144:147], v[232:235], v[20:23]
	v_mfma_f32_16x16x32_bf16 v[20:23], v[148:151], v[236:239], v[20:23]
	v_mfma_f32_16x16x32_bf16 v[4:7], v[144:147], v[240:243], v[4:7]
	v_mfma_f32_16x16x32_bf16 v[4:7], v[148:151], v[244:247], v[4:7]
	v_mfma_f32_16x16x32_bf16 v[48:51], v[152:155], v[208:211], v[48:51]
	v_mfma_f32_16x16x32_bf16 v[48:51], v[156:159], v[212:215], v[48:51]
	v_mfma_f32_16x16x32_bf16 v[32:35], v[152:155], v[216:219], v[32:35]
	v_mfma_f32_16x16x32_bf16 v[32:35], v[156:159], v[220:223], v[32:35]
	v_mfma_f32_16x16x32_bf16 v[16:19], v[152:155], v[232:235], v[16:19]
	v_mfma_f32_16x16x32_bf16 v[16:19], v[156:159], v[236:239], v[16:19]
	v_mfma_f32_16x16x32_bf16 v[0:3], v[152:155], v[240:243], v[0:3]
	v_mfma_f32_16x16x32_bf16 v[0:3], v[156:159], v[244:247], v[0:3]
	s_barrier
	s_setprio 0
	s_add_i32 s48, s48, 2
	s_add_u32 s10, s10, 0x100
	s_addc_u32 s11, s11, 0
	s_add_u32 s46, s46, 0x100
	s_addc_u32 s47, s47, 0
	s_cmp_gt_u32 s48, 29
	s_cbranch_scc0 .LBB0_252
	s_and_b64 vcc, exec, s[38:39]
	s_cbranch_vccz .LBB0_255
	s_barrier

; #define PG8_STAGE(bufoff, gbase, voff) do { _Pragma("unroll") for (int _i = 0; _i < 2; ++_i) \
;         __builtin_amdgcn_global_load_lds((const unsigned*)((const char*)(gbase) + (voff)[_i]), (PG8_LAS unsigned*)(lds + (bufoff) + ldsw + _i * 8192), 16, 0, 0); } while (0)
; #define PG8_LDA(dst, b, h) do { _Pragma("unroll") for (int m = 0; m < 4; ++m) _Pragma("unroll") for (int k = 0; k < 2; ++k) dst[m][k] = *(const PG8_LAS bf16x8*)(lds + PG8_SA(b, h) + aoff + m * 2048 + k * 1024); } while (0)
; #define PG8_LDB(dst, b, h) do { _Pragma("unroll") for (int n = 0; n < 2; ++n) _Pragma("unroll") for (int k = 0; k < 2; ++k) dst[n][k] = *(const PG8_LAS bf16x8*)(lds + PG8_SB(b, h) + boff + n * 2048 + k * 1024); } while (0)
; #define PG8_MMA(ai, bj, At, Bt) do { __builtin_amdgcn_s_setprio(1); _Pragma("unroll") for (int m = 0; m < 4; ++m) _Pragma("unroll") for (int n = 0; n < 2; ++n) _Pragma("unroll") for (int k = 0; k < 2; ++k) \
;         acc[ai][bj][m][n] = __builtin_amdgcn_mfma_f32_16x16x32_bf16(Bt[n][k], At[m][k], acc[ai][bj][m][n], 0, 0, 0); __builtin_amdgcn_s_setprio(0); } while (0)
; #define PG8_WAIT_V(n) asm volatile("s_waitcnt vmcnt(" #n ")" ::: "memory")
; #define PG8_WAIT_L(n) asm volatile("s_waitcnt lgkmcnt(" #n ")" ::: "memory")
; #define PG8_BAR __builtin_amdgcn_s_barrier()
; #define PG8_SCHED __builtin_amdgcn_sched_barrier(0)
; template <class Epi, class Sched, bool ALIGN_EPI = false, bool SP2 = false, bool DUAL = false>
; __device__ __forceinline__ void gemm_phase(PG8_LAS unsigned char* lds, const Gemm g, const Sched& S, const Epi& E) {
;     ...
;             PG8_LDB(B0, 0, 0); PG8_LDB(B1, 0, 1); PG8_SCHED; PG8_LDA(At, 0, 0); PG8_STAGE(PG8_SA(1, 1), a1 + hstep, voffA);
;             PG8_WAIT_V(8); PG8_WAIT_L(0); PG8_BAR; PG8_MMA(0, 0, At, B0); PG8_MMA(0, 1, At, B1); PG8_BAR; PG8_SCHED;
;             PG8_LDA(At, 0, 1); PG8_STAGE(PG8_SB(0, 0), b2, voffB); PG8_STAGE(PG8_SB(0, 1), b2 + hstep, voffB); PG8_STAGE(PG8_SA(0, 0), a2, voffA);
;             PG8_WAIT_V(8); PG8_WAIT_L(0); PG8_BAR; PG8_MMA(1, 0, At, B0); PG8_MMA(1, 1, At, B1); PG8_BAR; PG8_SCHED;
.LBB0_805:
	v_add_u32_e32 v1, s44, v235
	ds_read_b128 v[132:135], v1
	ds_read_b128 v[136:139], v1 offset:1024
	ds_read_b128 v[140:143], v1 offset:2048
	ds_read_b128 v[144:147], v1 offset:3072
	v_add_u32_e32 v1, s45, v235
	ds_read_b128 v[148:151], v1
	ds_read_b128 v[152:155], v1 offset:1024
	ds_read_b128 v[156:159], v1 offset:2048
	ds_read_b128 v[160:163], v1 offset:3072
	s_add_u32 s16, s14, 0xfff80080
	s_addc_u32 s17, s15, -1
	s_cmp_eq_u32 s75, 28
	s_cselect_b32 s19, s50, s17
	s_cselect_b32 s18, s51, s16
	s_cselect_b32 s17, s65, s73
	s_cselect_b32 s16, s67, s72
	v_lshl_add_u64 v[2:3], s[14:15], 0, v[192:193]
	s_add_i32 m0, s28, 0xc000
	ds_read_b128 v[164:167], v237
	ds_read_b128 v[168:171], v237 offset:1024
	ds_read_b128 v[172:175], v237 offset:2048
	ds_read_b128 v[176:179], v237 offset:3072
	ds_read_b128 v[180:183], v237 offset:4096
	ds_read_b128 v[202:205], v237 offset:5120
	ds_read_b128 v[206:209], v237 offset:6144
	ds_read_b128 v[210:213], v237 offset:7168
	global_load_lds_dwordx4 v[2:3], off
	v_lshl_add_u64 v[2:3], s[14:15], 0, v[194:195]
	s_add_i32 m0, s28, 0xe000
	s_nop 0
	global_load_lds_dwordx4 v[2:3], off
	s_waitcnt vmcnt(8)
	s_waitcnt lgkmcnt(0)
	s_setprio 1
	s_barrier
	v_mfma_f32_16x16x32_bf16 v[128:131], v[132:135], v[164:167], v[128:131]
	v_mfma_f32_16x16x32_bf16 v[128:131], v[136:139], v[168:171], v[128:131]
	v_mfma_f32_16x16x32_bf16 v[120:123], v[132:135], v[172:175], v[120:123]
	v_mfma_f32_16x16x32_bf16 v[120:123], v[136:139], v[176:179], v[120:123]
	v_mfma_f32_16x16x32_bf16 v[112:115], v[132:135], v[180:183], v[112:115]
	v_mfma_f32_16x16x32_bf16 v[112:115], v[136:139], v[202:205], v[112:115]
	v_mfma_f32_16x16x32_bf16 v[104:107], v[132:135], v[206:209], v[104:107]
	v_mfma_f32_16x16x32_bf16 v[104:107], v[136:139], v[210:213], v[104:107]
	v_mfma_f32_16x16x32_bf16 v[124:127], v[140:143], v[164:167], v[124:127]
	v_mfma_f32_16x16x32_bf16 v[124:127], v[144:147], v[168:171], v[124:127]
	v_mfma_f32_16x16x32_bf16 v[116:119], v[140:143], v[172:175], v[116:119]
	v_mfma_f32_16x16x32_bf16 v[116:119], v[144:147], v[176:179], v[116:119]
	v_mfma_f32_16x16x32_bf16 v[108:111], v[140:143], v[180:183], v[108:111]
	v_mfma_f32_16x16x32_bf16 v[108:111], v[144:147], v[202:205], v[108:111]
	v_mfma_f32_16x16x32_bf16 v[100:103], v[140:143], v[206:209], v[100:103]
	v_mfma_f32_16x16x32_bf16 v[100:103], v[144:147], v[210:213], v[100:103]
	s_setprio 0
	s_setprio 1
	v_mfma_f32_16x16x32_bf16 v[96:99], v[148:151], v[164:167], v[96:99]
	v_mfma_f32_16x16x32_bf16 v[96:99], v[152:155], v[168:171], v[96:99]
	v_mfma_f32_16x16x32_bf16 v[88:91], v[148:151], v[172:175], v[88:91]
	v_mfma_f32_16x16x32_bf16 v[88:91], v[152:155], v[176:179], v[88:91]
	v_mfma_f32_16x16x32_bf16 v[80:83], v[148:151], v[180:183], v[80:83]
	v_mfma_f32_16x16x32_bf16 v[80:83], v[152:155], v[202:205], v[80:83]
	v_mfma_f32_16x16x32_bf16 v[72:75], v[148:151], v[206:209], v[72:75]
	v_mfma_f32_16x16x32_bf16 v[72:75], v[152:155], v[210:213], v[72:75]
	v_mfma_f32_16x16x32_bf16 v[92:95], v[156:159], v[164:167], v[92:95]
	v_mfma_f32_16x16x32_bf16 v[92:95], v[160:163], v[168:171], v[92:95]
	v_mfma_f32_16x16x32_bf16 v[84:87], v[156:159], v[172:175], v[84:87]
	v_mfma_f32_16x16x32_bf16 v[84:87], v[160:163], v[176:179], v[84:87]
	v_mfma_f32_16x16x32_bf16 v[76:79], v[156:159], v[180:183], v[76:79]
	v_mfma_f32_16x16x32_bf16 v[76:79], v[160:163], v[202:205], v[76:79]
	v_mfma_f32_16x16x32_bf16 v[68:71], v[156:159], v[206:209], v[68:71]
	v_mfma_f32_16x16x32_bf16 v[68:71], v[160:163], v[210:213], v[68:71]
	s_barrier
	s_setprio 0
	s_add_i32 s76, s44, s27
	v_lshl_add_u64 v[214:215], s[16:17], 0, v[186:187]
	s_mov_b32 m0, s76
	ds_read_b128 v[164:167], v237 offset:16384
	ds_read_b128 v[168:171], v237 offset:17408
	ds_read_b128 v[172:175], v237 offset:18432
	ds_read_b128 v[176:179], v237 offset:19456
	ds_read_b128 v[180:183], v237 offset:20480
	ds_read_b128 v[202:205], v237 offset:21504
	ds_read_b128 v[206:209], v237 offset:22528
	ds_read_b128 v[210:213], v237 offset:23552
	global_load_lds_dwordx4 v[214:215], off
	s_add_i32 m0, s76, 0x2000
	s_add_u32 s76, s16, 0x80000
	v_lshl_add_u64 v[216:217], s[16:17], 0, v[190:191]
	s_addc_u32 s77, s17, 0
	s_add_i32 s78, s45, s27
	global_load_lds_dwordx4 v[216:217], off
	v_lshl_add_u64 v[2:3], s[76:77], 0, v[186:187]
	s_mov_b32 m0, s78
	v_lshl_add_u64 v[218:219], s[18:19], 0, v[184:185]
	global_load_lds_dwordx4 v[2:3], off
	v_lshl_add_u64 v[2:3], s[76:77], 0, v[190:191]
	s_add_i32 m0, s78, 0x2000
	v_lshl_add_u64 v[220:221], s[18:19], 0, v[188:189]
	global_load_lds_dwordx4 v[2:3], off
	s_mov_b32 m0, s28
	s_nop 0
	global_load_lds_dwordx4 v[218:219], off
	s_mov_b32 m0, s29
	s_nop 0
	global_load_lds_dwordx4 v[220:221], off
	s_waitcnt vmcnt(8)
	s_waitcnt lgkmcnt(0)
	s_setprio 1
	s_barrier
; #define PG8_STAGE(bufoff, gbase, voff) do { _Pragma("unroll") for (int _i = 0; _i < 2; ++_i) \
;         __builtin_amdgcn_global_load_lds((const unsigned*)((const char*)(gbase) + (voff)[_i]), (PG8_LAS unsigned*)(lds + (bufoff) + ldsw + _i * 8192), 16, 0, 0); } while (0)
; #define PG8_LDA(dst, b, h) do { _Pragma("unroll") for (int m = 0; m < 4; ++m) _Pragma("unroll") for (int k = 0; k < 2; ++k) dst[m][k] = *(const PG8_LAS bf16x8*)(lds + PG8_SA(b, h) + aoff + m * 2048 + k * 1024); } while (0)
; #define PG8_LDB(dst, b, h) do { _Pragma("unroll") for (int n = 0; n < 2; ++n) _Pragma("unroll") for (int k = 0; k < 2; ++k) dst[n][k] = *(const PG8_LAS bf16x8*)(lds + PG8_SB(b, h) + boff + n * 2048 + k * 1024); } while (0)
; #define PG8_MMA(ai, bj, At, Bt) do { __builtin_amdgcn_s_setprio(1); _Pragma("unroll") for (int m = 0; m < 4; ++m) _Pragma("unroll") for (int n = 0; n < 2; ++n) _Pragma("unroll") for (int k = 0; k < 2; ++k) \
;         acc[ai][bj][m][n] = __builtin_amdgcn_mfma_f32_16x16x32_bf16(Bt[n][k], At[m][k], acc[ai][bj][m][n], 0, 0, 0); __builtin_amdgcn_s_setprio(0); } while (0)
; #define PG8_WAIT_V(n) asm volatile("s_waitcnt vmcnt(" #n ")" ::: "memory")
; #define PG8_WAIT_L(n) asm volatile("s_waitcnt lgkmcnt(" #n ")" ::: "memory")
; #define PG8_BAR __builtin_amdgcn_s_barrier()
; #define PG8_SCHED __builtin_amdgcn_sched_barrier(0)
; template <class Epi, class Sched, bool ALIGN_EPI = false, bool SP2 = false, bool DUAL = false>
; __device__ __forceinline__ void gemm_phase(PG8_LAS unsigned char* lds, const Gemm g, const Sched& S, const Epi& E) {
;     ...
;             PG8_WAIT_V(8); PG8_WAIT_L(0); PG8_BAR; PG8_MMA(1, 0, At, B0); PG8_MMA(1, 1, At, B1); PG8_BAR; PG8_SCHED;
;             PG8_LDB(B0, 1, 0); PG8_LDB(B1, 1, 1); PG8_SCHED; PG8_LDA(At, 1, 0); PG8_STAGE(PG8_SA(0, 1), a2 + hstep, voffA);
;             PG8_WAIT_V(8); PG8_WAIT_L(0); PG8_BAR; PG8_MMA(0, 0, At, B0); PG8_MMA(0, 1, At, B1); PG8_BAR; PG8_SCHED;
	v_mfma_f32_16x16x32_bf16 v[64:67], v[132:135], v[164:167], v[64:67]
	v_mfma_f32_16x16x32_bf16 v[64:67], v[136:139], v[168:171], v[64:67]
	v_mfma_f32_16x16x32_bf16 v[56:59], v[132:135], v[172:175], v[56:59]
	v_mfma_f32_16x16x32_bf16 v[56:59], v[136:139], v[176:179], v[56:59]
	v_mfma_f32_16x16x32_bf16 v[48:51], v[132:135], v[180:183], v[48:51]
	v_mfma_f32_16x16x32_bf16 v[48:51], v[136:139], v[202:205], v[48:51]
	v_mfma_f32_16x16x32_bf16 v[40:43], v[132:135], v[206:209], v[40:43]
	v_mfma_f32_16x16x32_bf16 v[40:43], v[136:139], v[210:213], v[40:43]
	v_mfma_f32_16x16x32_bf16 v[60:63], v[140:143], v[164:167], v[60:63]
	v_mfma_f32_16x16x32_bf16 v[60:63], v[144:147], v[168:171], v[60:63]
	v_mfma_f32_16x16x32_bf16 v[52:55], v[140:143], v[172:175], v[52:55]
	v_mfma_f32_16x16x32_bf16 v[52:55], v[144:147], v[176:179], v[52:55]
	v_mfma_f32_16x16x32_bf16 v[44:47], v[140:143], v[180:183], v[44:47]
	v_mfma_f32_16x16x32_bf16 v[44:47], v[144:147], v[202:205], v[44:47]
	v_mfma_f32_16x16x32_bf16 v[36:39], v[140:143], v[206:209], v[36:39]
	v_mfma_f32_16x16x32_bf16 v[36:39], v[144:147], v[210:213], v[36:39]
	s_setprio 0
	s_setprio 1
	v_mfma_f32_16x16x32_bf16 v[32:35], v[148:151], v[164:167], v[32:35]
	v_mfma_f32_16x16x32_bf16 v[32:35], v[152:155], v[168:171], v[32:35]
	v_mfma_f32_16x16x32_bf16 v[24:27], v[148:151], v[172:175], v[24:27]
	v_mfma_f32_16x16x32_bf16 v[24:27], v[152:155], v[176:179], v[24:27]
	v_mfma_f32_16x16x32_bf16 v[16:19], v[148:151], v[180:183], v[16:19]
	v_mfma_f32_16x16x32_bf16 v[16:19], v[152:155], v[202:205], v[16:19]
	v_mfma_f32_16x16x32_bf16 v[8:11], v[148:151], v[206:209], v[8:11]
	v_mfma_f32_16x16x32_bf16 v[8:11], v[152:155], v[210:213], v[8:11]
	v_mfma_f32_16x16x32_bf16 v[28:31], v[156:159], v[164:167], v[28:31]
	v_mfma_f32_16x16x32_bf16 v[28:31], v[160:163], v[168:171], v[28:31]
	v_mfma_f32_16x16x32_bf16 v[20:23], v[156:159], v[172:175], v[20:23]
	v_mfma_f32_16x16x32_bf16 v[20:23], v[160:163], v[176:179], v[20:23]
	v_mfma_f32_16x16x32_bf16 v[12:15], v[156:159], v[180:183], v[12:15]
	v_mfma_f32_16x16x32_bf16 v[12:15], v[160:163], v[202:205], v[12:15]
	v_mfma_f32_16x16x32_bf16 v[2:5], v[156:159], v[206:209], v[4:7]
	v_mfma_f32_16x16x32_bf16 v[2:5], v[160:163], v[210:213], v[2:5]
	s_barrier
	s_setprio 0
	s_add_i32 s76, 0, 0x18000
	v_add_u32_e32 v1, s76, v235
	s_add_i32 s77, 0, 0x1c000
	ds_read_b128 v[132:135], v1
	ds_read_b128 v[136:139], v1 offset:1024
	ds_read_b128 v[140:143], v1 offset:2048
	ds_read_b128 v[144:147], v1 offset:3072
	v_add_u32_e32 v1, s77, v235
	ds_read_b128 v[148:151], v1
	ds_read_b128 v[152:155], v1 offset:1024
	ds_read_b128 v[156:159], v1 offset:2048
	ds_read_b128 v[160:163], v1 offset:3072
	s_add_u32 s18, s18, 0x80000
	s_addc_u32 s19, s19, 0
	s_mov_b32 m0, s34
	v_lshl_add_u64 v[6:7], s[18:19], 0, v[184:185]
	ds_read_b128 v[164:167], v237 offset:32768
	ds_read_b128 v[168:171], v237 offset:33792
	ds_read_b128 v[172:175], v237 offset:34816
	ds_read_b128 v[176:179], v237 offset:35840
	ds_read_b128 v[180:183], v237 offset:36864
	ds_read_b128 v[202:205], v237 offset:37888
	ds_read_b128 v[206:209], v237 offset:38912
	ds_read_b128 v[210:213], v237 offset:39936
	global_load_lds_dwordx4 v[6:7], off
	v_lshl_add_u64 v[6:7], s[18:19], 0, v[188:189]
	s_mov_b32 m0, s35
	s_nop 0
	global_load_lds_dwordx4 v[6:7], off
	s_waitcnt vmcnt(8)
	s_waitcnt lgkmcnt(0)
	s_setprio 1
	s_barrier
	v_mfma_f32_16x16x32_bf16 v[128:131], v[132:135], v[164:167], v[128:131]
	v_mfma_f32_16x16x32_bf16 v[128:131], v[136:139], v[168:171], v[128:131]
	v_mfma_f32_16x16x32_bf16 v[120:123], v[132:135], v[172:175], v[120:123]
	v_mfma_f32_16x16x32_bf16 v[120:123], v[136:139], v[176:179], v[120:123]
	v_mfma_f32_16x16x32_bf16 v[112:115], v[132:135], v[180:183], v[112:115]
	v_mfma_f32_16x16x32_bf16 v[112:115], v[136:139], v[202:205], v[112:115]
	v_mfma_f32_16x16x32_bf16 v[104:107], v[132:135], v[206:209], v[104:107]
	v_mfma_f32_16x16x32_bf16 v[104:107], v[136:139], v[210:213], v[104:107]
	v_mfma_f32_16x16x32_bf16 v[124:127], v[140:143], v[164:167], v[124:127]
	v_mfma_f32_16x16x32_bf16 v[124:127], v[144:147], v[168:171], v[124:127]
	v_mfma_f32_16x16x32_bf16 v[116:119], v[140:143], v[172:175], v[116:119]
	v_mfma_f32_16x16x32_bf16 v[116:119], v[144:147], v[176:179], v[116:119]
	v_mfma_f32_16x16x32_bf16 v[108:111], v[140:143], v[180:183], v[108:111]
	v_mfma_f32_16x16x32_bf16 v[108:111], v[144:147], v[202:205], v[108:111]
	v_mfma_f32_16x16x32_bf16 v[100:103], v[140:143], v[206:209], v[100:103]
	v_mfma_f32_16x16x32_bf16 v[100:103], v[144:147], v[210:213], v[100:103]
	s_setprio 0
	s_setprio 1
	v_mfma_f32_16x16x32_bf16 v[96:99], v[148:151], v[164:167], v[96:99]
	v_mfma_f32_16x16x32_bf16 v[96:99], v[152:155], v[168:171], v[96:99]
	v_mfma_f32_16x16x32_bf16 v[88:91], v[148:151], v[172:175], v[88:91]
	v_mfma_f32_16x16x32_bf16 v[88:91], v[152:155], v[176:179], v[88:91]
	v_mfma_f32_16x16x32_bf16 v[80:83], v[148:151], v[180:183], v[80:83]
	v_mfma_f32_16x16x32_bf16 v[80:83], v[152:155], v[202:205], v[80:83]
	v_mfma_f32_16x16x32_bf16 v[72:75], v[148:151], v[206:209], v[72:75]
	v_mfma_f32_16x16x32_bf16 v[72:75], v[152:155], v[210:213], v[72:75]
	v_mfma_f32_16x16x32_bf16 v[92:95], v[156:159], v[164:167], v[92:95]
	v_mfma_f32_16x16x32_bf16 v[92:95], v[160:163], v[168:171], v[92:95]
	v_mfma_f32_16x16x32_bf16 v[84:87], v[156:159], v[172:175], v[84:87]
	v_mfma_f32_16x16x32_bf16 v[84:87], v[160:163], v[176:179], v[84:87]
	v_mfma_f32_16x16x32_bf16 v[76:79], v[156:159], v[180:183], v[76:79]
	v_mfma_f32_16x16x32_bf16 v[76:79], v[160:163], v[202:205], v[76:79]
	v_mfma_f32_16x16x32_bf16 v[68:71], v[156:159], v[206:209], v[68:71]
	v_mfma_f32_16x16x32_bf16 v[68:71], v[160:163], v[210:213], v[68:71]
	s_barrier
; #define PG8_STAGE(bufoff, gbase, voff) do { _Pragma("unroll") for (int _i = 0; _i < 2; ++_i) \
;         __builtin_amdgcn_global_load_lds((const unsigned*)((const char*)(gbase) + (voff)[_i]), (PG8_LAS unsigned*)(lds + (bufoff) + ldsw + _i * 8192), 16, 0, 0); } while (0)
; #define PG8_LDA(dst, b, h) do { _Pragma("unroll") for (int m = 0; m < 4; ++m) _Pragma("unroll") for (int k = 0; k < 2; ++k) dst[m][k] = *(const PG8_LAS bf16x8*)(lds + PG8_SA(b, h) + aoff + m * 2048 + k * 1024); } while (0)
; #define PG8_MMA(ai, bj, At, Bt) do { __builtin_amdgcn_s_setprio(1); _Pragma("unroll") for (int m = 0; m < 4; ++m) _Pragma("unroll") for (int n = 0; n < 2; ++n) _Pragma("unroll") for (int k = 0; k < 2; ++k) \
;         acc[ai][bj][m][n] = __builtin_amdgcn_mfma_f32_16x16x32_bf16(Bt[n][k], At[m][k], acc[ai][bj][m][n], 0, 0, 0); __builtin_amdgcn_s_setprio(0); } while (0)
; #define PG8_WAIT_V(n) asm volatile("s_waitcnt vmcnt(" #n ")" ::: "memory")
; #define PG8_WAIT_L(n) asm volatile("s_waitcnt lgkmcnt(" #n ")" ::: "memory")
; #define PG8_BAR __builtin_amdgcn_s_barrier()
; #define PG8_SCHED __builtin_amdgcn_sched_barrier(0)
; template <class Epi, class Sched, bool ALIGN_EPI = false, bool SP2 = false, bool DUAL = false>
; __device__ __forceinline__ void gemm_phase(PG8_LAS unsigned char* lds, const Gemm g, const Sched& S, const Epi& E) {
;     ...
;             PG8_LDA(At, 1, 1); PG8_STAGE(PG8_SB(1, 0), b3, voffB); PG8_STAGE(PG8_SB(1, 1), b3 + hstep, voffB); PG8_STAGE(PG8_SA(1, 0), a3, voffA);
;             PG8_WAIT_V(8); PG8_WAIT_L(0); PG8_BAR; PG8_MMA(1, 0, At, B0); PG8_MMA(1, 1, At, B1); PG8_BAR; PG8_SCHED;
	s_setprio 0
	s_add_i32 s18, s76, s27
	v_lshl_add_u64 v[6:7], v[214:215], 0, s[36:37]
	s_mov_b32 m0, s18
	ds_read_b128 v[164:167], v237 offset:49152
	ds_read_b128 v[168:171], v237 offset:50176
	ds_read_b128 v[172:175], v237 offset:51200
	ds_read_b128 v[176:179], v237 offset:52224
	ds_read_b128 v[180:183], v237 offset:53248
	ds_read_b128 v[202:205], v237 offset:54272
	ds_read_b128 v[206:209], v237 offset:55296
	ds_read_b128 v[210:213], v237 offset:56320
	global_load_lds_dwordx4 v[6:7], off
	s_add_i32 m0, s18, 0x2000
	s_add_u32 s16, s16, 0x80080
	v_lshl_add_u64 v[6:7], v[216:217], 0, s[36:37]
	s_addc_u32 s17, s17, 0
	s_add_i32 s18, s77, s27
	global_load_lds_dwordx4 v[6:7], off
	v_lshl_add_u64 v[6:7], s[16:17], 0, v[186:187]
	s_mov_b32 m0, s18
	s_nop 0
	global_load_lds_dwordx4 v[6:7], off
	v_lshl_add_u64 v[6:7], s[16:17], 0, v[190:191]
	s_add_i32 m0, s18, 0x2000
	s_nop 0
	global_load_lds_dwordx4 v[6:7], off
	v_lshl_add_u64 v[6:7], v[218:219], 0, s[36:37]
	s_mov_b32 m0, s42
	s_nop 0
	global_load_lds_dwordx4 v[6:7], off
	v_lshl_add_u64 v[6:7], v[220:221], 0, s[36:37]
	s_mov_b32 m0, s43
	s_nop 0
	global_load_lds_dwordx4 v[6:7], off
	s_waitcnt vmcnt(8)
	s_waitcnt lgkmcnt(0)
	s_setprio 1
	s_barrier
	v_mfma_f32_16x16x32_bf16 v[64:67], v[132:135], v[164:167], v[64:67]
	v_mfma_f32_16x16x32_bf16 v[64:67], v[136:139], v[168:171], v[64:67]
	v_mfma_f32_16x16x32_bf16 v[56:59], v[132:135], v[172:175], v[56:59]
	v_mfma_f32_16x16x32_bf16 v[56:59], v[136:139], v[176:179], v[56:59]
	v_mfma_f32_16x16x32_bf16 v[48:51], v[132:135], v[180:183], v[48:51]
	v_mfma_f32_16x16x32_bf16 v[48:51], v[136:139], v[202:205], v[48:51]
	v_mfma_f32_16x16x32_bf16 v[40:43], v[132:135], v[206:209], v[40:43]
	v_mfma_f32_16x16x32_bf16 v[40:43], v[136:139], v[210:213], v[40:43]
	v_mfma_f32_16x16x32_bf16 v[60:63], v[140:143], v[164:167], v[60:63]
	v_mfma_f32_16x16x32_bf16 v[60:63], v[144:147], v[168:171], v[60:63]
	v_mfma_f32_16x16x32_bf16 v[52:55], v[140:143], v[172:175], v[52:55]
	v_mfma_f32_16x16x32_bf16 v[52:55], v[144:147], v[176:179], v[52:55]
	v_mfma_f32_16x16x32_bf16 v[44:47], v[140:143], v[180:183], v[44:47]
	v_mfma_f32_16x16x32_bf16 v[44:47], v[144:147], v[202:205], v[44:47]
	v_mfma_f32_16x16x32_bf16 v[36:39], v[140:143], v[206:209], v[36:39]
	v_mfma_f32_16x16x32_bf16 v[36:39], v[144:147], v[210:213], v[36:39]
	s_setprio 0
	s_setprio 1
	v_mfma_f32_16x16x32_bf16 v[32:35], v[148:151], v[164:167], v[32:35]
	v_mfma_f32_16x16x32_bf16 v[28:31], v[156:159], v[164:167], v[28:31]
	v_mfma_f32_16x16x32_bf16 v[24:27], v[148:151], v[172:175], v[24:27]
	v_mfma_f32_16x16x32_bf16 v[20:23], v[156:159], v[172:175], v[20:23]
	v_mfma_f32_16x16x32_bf16 v[16:19], v[148:151], v[180:183], v[16:19]
	v_mfma_f32_16x16x32_bf16 v[12:15], v[156:159], v[180:183], v[12:15]
	v_mfma_f32_16x16x32_bf16 v[6:9], v[148:151], v[206:209], v[8:11]
	v_mfma_f32_16x16x32_bf16 v[2:5], v[156:159], v[206:209], v[2:5]
	v_mfma_f32_16x16x32_bf16 v[32:35], v[152:155], v[168:171], v[32:35]
	v_mfma_f32_16x16x32_bf16 v[28:31], v[160:163], v[168:171], v[28:31]
	v_mfma_f32_16x16x32_bf16 v[24:27], v[152:155], v[176:179], v[24:27]
	v_mfma_f32_16x16x32_bf16 v[20:23], v[160:163], v[176:179], v[20:23]
	v_mfma_f32_16x16x32_bf16 v[16:19], v[152:155], v[202:205], v[16:19]
	v_mfma_f32_16x16x32_bf16 v[12:15], v[160:163], v[202:205], v[12:15]
	v_mfma_f32_16x16x32_bf16 v[8:11], v[152:155], v[210:213], v[6:9]
	v_mfma_f32_16x16x32_bf16 v[4:7], v[160:163], v[210:213], v[2:5]
	s_barrier
	s_setprio 0
	s_add_i32 s75, s75, 2
	s_add_u32 s14, s14, 0x100
	s_addc_u32 s15, s15, 0
	s_add_u32 s72, s72, 0x100
	s_addc_u32 s73, s73, 0
	s_cmp_gt_u32 s75, 29
	s_cbranch_scc0 .LBB0_805
	s_and_b64 vcc, exec, s[38:39]
	s_cbranch_vccz .LBB0_808
	s_barrier

;     __device__ bool next(int i, Unit& u) const { if (!base.next(i >> 1, u)) return false; u.sub = i & 1; return true; }
; #define PG8_STAGE(bufoff, gbase, voff) do { _Pragma("unroll") for (int _i = 0; _i < 2; ++_i) \
;         __builtin_amdgcn_global_load_lds((const unsigned*)((const char*)(gbase) + (voff)[_i]), (PG8_LAS unsigned*)(lds + (bufoff) + ldsw + _i * 8192), 16, 0, 0); } while (0)
; #define PG8_LDA(dst, b, h) do { _Pragma("unroll") for (int m = 0; m < 4; ++m) _Pragma("unroll") for (int k = 0; k < 2; ++k) dst[m][k] = *(const PG8_LAS bf16x8*)(lds + PG8_SA(b, h) + aoff + m * 2048 + k * 1024); } while (0)
; #define PG8_LDB(dst, b, h) do { _Pragma("unroll") for (int n = 0; n < 2; ++n) _Pragma("unroll") for (int k = 0; k < 2; ++k) dst[n][k] = *(const PG8_LAS bf16x8*)(lds + PG8_SB(b, h) + boff + n * 2048 + k * 1024); } while (0)
; #define PG8_WAIT_V(n) asm volatile("s_waitcnt vmcnt(" #n ")" ::: "memory")
; template <class Epi, class Sched, bool ALIGN_EPI = false, bool SP2 = false, bool DUAL = false>
; __device__ __forceinline__ void gemm_phase(PG8_LAS unsigned char* lds, const Gemm g, const Sched& S, const Epi& E) {
;     ...
;         const bool has_next = S.next(ui + 1, nxt);
;         const char* nA = has_next ? (const char*)((DUAL && nxt.sub) ? g.A2 : g.A) + (size_t)nxt.pm * tstep : cA; const char* nB = has_next ? (const char*)((DUAL && nxt.sub) ? g.Bt2 : g.Bt) + (size_t)nxt.pn * tstep : cB;
;         for (int t = 0; t < nt; t += 2) {
;             const bool last = (t == nt - 2);
;             const char* a1 = cA + (size_t)(t + 1) * kstep;
;             const char* a2 = last ? nA : cA + (size_t)(t + 2) * kstep; const char* b2 = last ? nB : cB + (size_t)(t + 2) * kstep;
;             const char* a3 = a2 + kstep; const char* b3 = b2 + kstep;
;             if (last && has_next) S.a_ready(nxt);
;             if constexpr (SP2) {
;             PG8_LDB(B0, 0, 0); PG8_LDB(B1, 0, 1); PG8_SCHED; PG8_LDA(At, 0, 0); PG8_STAGE(PG8_SA(1, 1), a1 + hstep, voffA);
;             PG8_WAIT_V(8); PG8_WAIT_L(0); PG8_BAR; PG8_MMA(0, 0, At, B0); PG8_MMA(0, 1, At, B1); PG8_BAR; PG8_SCHED;
;             PG8_LDA(At, 0, 1); PG8_STAGE(PG8_SB(0, 0), b2, voffB); PG8_STAGE(PG8_SB(0, 1), b2 + hstep, voffB); PG8_STAGE(PG8_SA(0, 0), a2, voffA);
;             PG8_WAIT_V(8); PG8_WAIT_L(0); PG8_BAR; PG8_MMA(1, 0, At, B0); PG8_MMA(1, 1, At, B1); PG8_BAR; PG8_SCHED;
.LBB0_895:
	s_ashr_i32 s61, s60, 31
	s_lshl_b64 s[18:19], s[60:61], 20
	s_add_u32 s62, s10, s18
	s_addc_u32 s63, s11, s19
	s_and_b64 s[18:19], s[6:7], exec
	s_cselect_b32 s18, s63, s17
	s_cselect_b32 s19, s62, s16
	s_ashr_i32 s41, s40, 31
	s_lshl_b64 s[64:65], s[40:41], 20
	s_add_u32 s64, s12, s64
	s_addc_u32 s65, s13, s65
	s_and_b64 s[68:69], s[6:7], exec
	s_cselect_b32 s41, s65, s15
	s_cselect_b32 s61, s64, s14
	s_add_u32 s68, s16, 0x80080
	s_addc_u32 s69, s17, 0
	s_add_u32 s67, s14, 0x100
	s_addc_u32 s70, s15, 0
	s_mov_b32 s71, -2
	s_waitcnt lgkmcnt(0)
	s_add_u32 s14, s68, 0xfff80080
	s_addc_u32 s15, s69, -1
	s_cmp_eq_u32 s71, 28
	s_cselect_b32 s17, s18, s15
	s_cselect_b32 s16, s19, s14
	s_cselect_b32 s15, s41, s70
	s_cselect_b32 s14, s61, s67
	s_waitcnt vmcnt(8)
	s_waitcnt lgkmcnt(0)
	s_setprio 1
	s_barrier
	v_mfma_f32_16x16x32_bf16 v[124:127], v[128:131], v[160:163], 0
	v_mfma_f32_16x16x32_bf16 v[124:127], v[132:135], v[164:167], v[124:127]
	v_mfma_f32_16x16x32_bf16 v[108:111], v[128:131], v[168:171], 0
	v_mfma_f32_16x16x32_bf16 v[108:111], v[132:135], v[172:175], v[108:111]
	v_mfma_f32_16x16x32_bf16 v[92:95], v[128:131], v[196:199], 0
	v_mfma_f32_16x16x32_bf16 v[92:95], v[132:135], v[202:205], v[92:95]
	v_mfma_f32_16x16x32_bf16 v[76:79], v[128:131], v[206:209], 0
	v_mfma_f32_16x16x32_bf16 v[76:79], v[132:135], v[232:235], v[76:79]
	v_mfma_f32_16x16x32_bf16 v[120:123], v[136:139], v[160:163], 0
	v_mfma_f32_16x16x32_bf16 v[120:123], v[140:143], v[164:167], v[120:123]
	v_mfma_f32_16x16x32_bf16 v[104:107], v[136:139], v[168:171], 0
	v_mfma_f32_16x16x32_bf16 v[104:107], v[140:143], v[172:175], v[104:107]
	v_mfma_f32_16x16x32_bf16 v[88:91], v[136:139], v[196:199], 0
	v_mfma_f32_16x16x32_bf16 v[88:91], v[140:143], v[202:205], v[88:91]
	v_mfma_f32_16x16x32_bf16 v[72:75], v[136:139], v[206:209], 0
	v_mfma_f32_16x16x32_bf16 v[72:75], v[140:143], v[232:235], v[72:75]
	s_setprio 0
	s_setprio 1
	v_mfma_f32_16x16x32_bf16 v[116:119], v[144:147], v[160:163], 0
	v_mfma_f32_16x16x32_bf16 v[116:119], v[148:151], v[164:167], v[116:119]
	v_mfma_f32_16x16x32_bf16 v[100:103], v[144:147], v[168:171], 0
	v_mfma_f32_16x16x32_bf16 v[100:103], v[148:151], v[172:175], v[100:103]
	v_mfma_f32_16x16x32_bf16 v[84:87], v[144:147], v[196:199], 0
	v_mfma_f32_16x16x32_bf16 v[84:87], v[148:151], v[202:205], v[84:87]
	v_mfma_f32_16x16x32_bf16 v[68:71], v[144:147], v[206:209], 0
	v_mfma_f32_16x16x32_bf16 v[68:71], v[148:151], v[232:235], v[68:71]
	v_mfma_f32_16x16x32_bf16 v[112:115], v[152:155], v[160:163], 0
	v_mfma_f32_16x16x32_bf16 v[112:115], v[156:159], v[164:167], v[112:115]
	v_mfma_f32_16x16x32_bf16 v[96:99], v[152:155], v[168:171], 0
	v_mfma_f32_16x16x32_bf16 v[96:99], v[156:159], v[172:175], v[96:99]
	v_mfma_f32_16x16x32_bf16 v[80:83], v[152:155], v[196:199], 0
	v_mfma_f32_16x16x32_bf16 v[80:83], v[156:159], v[202:205], v[80:83]
	v_mfma_f32_16x16x32_bf16 v[64:67], v[152:155], v[206:209], 0
	v_mfma_f32_16x16x32_bf16 v[64:67], v[156:159], v[232:235], v[64:67]
	s_barrier
	s_setprio 0
	v_lshl_add_u64 v[222:223], s[68:69], 0, v[188:189]
	s_add_i32 m0, s27, 0xc000
	s_nop 0
	global_load_lds_dwordx4 v[222:223], off
	v_lshl_add_u64 v[222:223], s[68:69], 0, v[190:191]
	s_add_i32 m0, s27, 0xe000
	s_nop 0
	global_load_lds_dwordx4 v[222:223], off
	s_add_i32 s72, s48, s26
	v_lshl_add_u64 v[222:223], s[14:15], 0, v[182:183]
	s_mov_b32 m0, s72
	ds_read_b128 v[160:163], v220 offset:16384
	ds_read_b128 v[164:167], v220 offset:17408
	ds_read_b128 v[168:171], v220 offset:18432
	ds_read_b128 v[172:175], v220 offset:19456
	ds_read_b128 v[196:199], v220 offset:20480
	ds_read_b128 v[202:205], v220 offset:21504
	ds_read_b128 v[206:209], v220 offset:22528
	ds_read_b128 v[232:235], v220 offset:23552
	global_load_lds_dwordx4 v[222:223], off
	s_add_i32 m0, s72, 0x2000
	s_add_u32 s72, s14, 0x80000
	v_lshl_add_u64 v[228:229], s[14:15], 0, v[186:187]
	s_addc_u32 s73, s15, 0
	s_add_i32 s74, s49, s26
	global_load_lds_dwordx4 v[228:229], off
	v_lshl_add_u64 v[236:237], s[72:73], 0, v[182:183]
	s_mov_b32 m0, s74
	v_lshl_add_u64 v[238:239], s[16:17], 0, v[184:185]
	global_load_lds_dwordx4 v[236:237], off
	v_lshl_add_u64 v[236:237], s[72:73], 0, v[186:187]
	s_add_i32 m0, s74, 0x2000
	s_nop 0
	global_load_lds_dwordx4 v[236:237], off
	v_lshl_add_u64 v[236:237], s[16:17], 0, v[180:181]
	s_mov_b32 m0, s27
	s_nop 0
	global_load_lds_dwordx4 v[236:237], off
	s_mov_b32 m0, s28
	s_nop 0
	global_load_lds_dwordx4 v[238:239], off
	s_waitcnt vmcnt(8)
	s_waitcnt lgkmcnt(0)
	s_setprio 1
	s_barrier
	v_mfma_f32_16x16x32_bf16 v[60:63], v[128:131], v[160:163], 0
	v_mfma_f32_16x16x32_bf16 v[60:63], v[132:135], v[164:167], v[60:63]
	v_mfma_f32_16x16x32_bf16 v[44:47], v[128:131], v[168:171], 0
	v_mfma_f32_16x16x32_bf16 v[44:47], v[132:135], v[172:175], v[44:47]
	v_mfma_f32_16x16x32_bf16 v[28:31], v[128:131], v[196:199], 0
	v_mfma_f32_16x16x32_bf16 v[28:31], v[132:135], v[202:205], v[28:31]
	v_mfma_f32_16x16x32_bf16 v[12:15], v[128:131], v[206:209], 0
	v_mfma_f32_16x16x32_bf16 v[12:15], v[132:135], v[232:235], v[12:15]
	v_mfma_f32_16x16x32_bf16 v[56:59], v[136:139], v[160:163], 0
	v_mfma_f32_16x16x32_bf16 v[56:59], v[140:143], v[164:167], v[56:59]
	v_mfma_f32_16x16x32_bf16 v[40:43], v[136:139], v[168:171], 0
	v_mfma_f32_16x16x32_bf16 v[40:43], v[140:143], v[172:175], v[40:43]
	v_mfma_f32_16x16x32_bf16 v[24:27], v[136:139], v[196:199], 0
	v_mfma_f32_16x16x32_bf16 v[24:27], v[140:143], v[202:205], v[24:27]
	v_mfma_f32_16x16x32_bf16 v[8:11], v[136:139], v[206:209], 0
	v_mfma_f32_16x16x32_bf16 v[8:11], v[140:143], v[232:235], v[8:11]
	s_setprio 0
	s_setprio 1
	v_mfma_f32_16x16x32_bf16 v[52:55], v[144:147], v[160:163], 0
	v_mfma_f32_16x16x32_bf16 v[52:55], v[148:151], v[164:167], v[52:55]
	v_mfma_f32_16x16x32_bf16 v[36:39], v[144:147], v[168:171], 0
	v_mfma_f32_16x16x32_bf16 v[36:39], v[148:151], v[172:175], v[36:39]
	v_mfma_f32_16x16x32_bf16 v[20:23], v[144:147], v[196:199], 0
	v_mfma_f32_16x16x32_bf16 v[20:23], v[148:151], v[202:205], v[20:23]
	v_mfma_f32_16x16x32_bf16 v[4:7], v[144:147], v[206:209], 0
	v_mfma_f32_16x16x32_bf16 v[4:7], v[148:151], v[232:235], v[4:7]
	v_mfma_f32_16x16x32_bf16 v[48:51], v[152:155], v[160:163], 0
	v_mfma_f32_16x16x32_bf16 v[48:51], v[156:159], v[164:167], v[48:51]
	v_mfma_f32_16x16x32_bf16 v[32:35], v[152:155], v[168:171], 0
	v_mfma_f32_16x16x32_bf16 v[32:35], v[156:159], v[172:175], v[32:35]
	v_mfma_f32_16x16x32_bf16 v[16:19], v[152:155], v[196:199], 0
	v_mfma_f32_16x16x32_bf16 v[16:19], v[156:159], v[202:205], v[16:19]
	v_mfma_f32_16x16x32_bf16 v[0:3], v[152:155], v[206:209], 0
	v_mfma_f32_16x16x32_bf16 v[0:3], v[156:159], v[232:235], v[0:3]
	s_barrier
; #define PG8_STAGE(bufoff, gbase, voff) do { _Pragma("unroll") for (int _i = 0; _i < 2; ++_i) \
;         __builtin_amdgcn_global_load_lds((const unsigned*)((const char*)(gbase) + (voff)[_i]), (PG8_LAS unsigned*)(lds + (bufoff) + ldsw + _i * 8192), 16, 0, 0); } while (0)
; #define PG8_LDA(dst, b, h) do { _Pragma("unroll") for (int m = 0; m < 4; ++m) _Pragma("unroll") for (int k = 0; k < 2; ++k) dst[m][k] = *(const PG8_LAS bf16x8*)(lds + PG8_SA(b, h) + aoff + m * 2048 + k * 1024); } while (0)
; #define PG8_LDB(dst, b, h) do { _Pragma("unroll") for (int n = 0; n < 2; ++n) _Pragma("unroll") for (int k = 0; k < 2; ++k) dst[n][k] = *(const PG8_LAS bf16x8*)(lds + PG8_SB(b, h) + boff + n * 2048 + k * 1024); } while (0)
; #define PG8_MMA(ai, bj, At, Bt) do { __builtin_amdgcn_s_setprio(1); _Pragma("unroll") for (int m = 0; m < 4; ++m) _Pragma("unroll") for (int n = 0; n < 2; ++n) _Pragma("unroll") for (int k = 0; k < 2; ++k) \
;         acc[ai][bj][m][n] = __builtin_amdgcn_mfma_f32_16x16x32_bf16(Bt[n][k], At[m][k], acc[ai][bj][m][n], 0, 0, 0); __builtin_amdgcn_s_setprio(0); } while (0)
; #define PG8_WAIT_V(n) asm volatile("s_waitcnt vmcnt(" #n ")" ::: "memory")
; #define PG8_WAIT_L(n) asm volatile("s_waitcnt lgkmcnt(" #n ")" ::: "memory")
; #define PG8_BAR __builtin_amdgcn_s_barrier()
; #define PG8_SCHED __builtin_amdgcn_sched_barrier(0)
; template <class Epi, class Sched, bool ALIGN_EPI = false, bool SP2 = false, bool DUAL = false>
; __device__ __forceinline__ void gemm_phase(PG8_LAS unsigned char* lds, const Gemm g, const Sched& S, const Epi& E) {
;     ...
;             PG8_LDB(B0, 1, 0); PG8_LDB(B1, 1, 1); PG8_SCHED; PG8_LDA(At, 1, 0); PG8_STAGE(PG8_SA(0, 1), a2 + hstep, voffA);
;             PG8_WAIT_V(8); PG8_WAIT_L(0); PG8_BAR; PG8_MMA(0, 0, At, B0); PG8_MMA(0, 1, At, B1); PG8_BAR; PG8_SCHED;
;             PG8_LDA(At, 1, 1); PG8_STAGE(PG8_SB(1, 0), b3, voffB); PG8_STAGE(PG8_SB(1, 1), b3 + hstep, voffB); PG8_STAGE(PG8_SA(1, 0), a3, voffA);
;             PG8_WAIT_V(8); PG8_WAIT_L(0); PG8_BAR; PG8_MMA(1, 0, At, B0); PG8_MMA(1, 1, At, B1); PG8_BAR; PG8_SCHED;
	s_setprio 0
	s_add_i32 s72, 0, 0x18000
	s_add_i32 s73, 0, 0x1c000
	v_add_u32_e32 v140, s72, v216
	v_add_u32_e32 v156, s73, v216
	ds_read_b128 v[128:131], v140
	ds_read_b128 v[132:135], v140 offset:1024
	ds_read_b128 v[136:139], v140 offset:2048
	ds_read_b128 v[140:143], v140 offset:3072
	ds_read_b128 v[144:147], v156
	ds_read_b128 v[148:151], v156 offset:1024
	ds_read_b128 v[152:155], v156 offset:2048
	ds_read_b128 v[156:159], v156 offset:3072
	s_add_u32 s16, s16, 0x80000
	s_addc_u32 s17, s17, 0
	s_mov_b32 m0, s29
	v_lshl_add_u64 v[240:241], s[16:17], 0, v[180:181]
	ds_read_b128 v[160:163], v220 offset:32768
	ds_read_b128 v[164:167], v220 offset:33792
	ds_read_b128 v[168:171], v220 offset:34816
	ds_read_b128 v[172:175], v220 offset:35840
	ds_read_b128 v[196:199], v220 offset:36864
	ds_read_b128 v[202:205], v220 offset:37888
	ds_read_b128 v[206:209], v220 offset:38912
	ds_read_b128 v[232:235], v220 offset:39936
	global_load_lds_dwordx4 v[240:241], off
	v_lshl_add_u64 v[240:241], s[16:17], 0, v[184:185]
	s_mov_b32 m0, s34
	s_nop 0
	global_load_lds_dwordx4 v[240:241], off
	s_waitcnt vmcnt(8)
	s_waitcnt lgkmcnt(0)
	s_setprio 1
	s_barrier
	v_mfma_f32_16x16x32_bf16 v[124:127], v[128:131], v[160:163], v[124:127]
	v_mfma_f32_16x16x32_bf16 v[124:127], v[132:135], v[164:167], v[124:127]
	v_mfma_f32_16x16x32_bf16 v[108:111], v[128:131], v[168:171], v[108:111]
	v_mfma_f32_16x16x32_bf16 v[108:111], v[132:135], v[172:175], v[108:111]
	v_mfma_f32_16x16x32_bf16 v[92:95], v[128:131], v[196:199], v[92:95]
	v_mfma_f32_16x16x32_bf16 v[92:95], v[132:135], v[202:205], v[92:95]
	v_mfma_f32_16x16x32_bf16 v[76:79], v[128:131], v[206:209], v[76:79]
	v_mfma_f32_16x16x32_bf16 v[76:79], v[132:135], v[232:235], v[76:79]
	v_mfma_f32_16x16x32_bf16 v[120:123], v[136:139], v[160:163], v[120:123]
	v_mfma_f32_16x16x32_bf16 v[120:123], v[140:143], v[164:167], v[120:123]
	v_mfma_f32_16x16x32_bf16 v[104:107], v[136:139], v[168:171], v[104:107]
	v_mfma_f32_16x16x32_bf16 v[104:107], v[140:143], v[172:175], v[104:107]
	v_mfma_f32_16x16x32_bf16 v[88:91], v[136:139], v[196:199], v[88:91]
	v_mfma_f32_16x16x32_bf16 v[88:91], v[140:143], v[202:205], v[88:91]
	v_mfma_f32_16x16x32_bf16 v[72:75], v[136:139], v[206:209], v[72:75]
	v_mfma_f32_16x16x32_bf16 v[72:75], v[140:143], v[232:235], v[72:75]
	s_setprio 0
	s_setprio 1
	v_mfma_f32_16x16x32_bf16 v[116:119], v[144:147], v[160:163], v[116:119]
	v_mfma_f32_16x16x32_bf16 v[116:119], v[148:151], v[164:167], v[116:119]
	v_mfma_f32_16x16x32_bf16 v[100:103], v[144:147], v[168:171], v[100:103]
	v_mfma_f32_16x16x32_bf16 v[100:103], v[148:151], v[172:175], v[100:103]
	v_mfma_f32_16x16x32_bf16 v[84:87], v[144:147], v[196:199], v[84:87]
	v_mfma_f32_16x16x32_bf16 v[84:87], v[148:151], v[202:205], v[84:87]
	v_mfma_f32_16x16x32_bf16 v[68:71], v[144:147], v[206:209], v[68:71]
	v_mfma_f32_16x16x32_bf16 v[68:71], v[148:151], v[232:235], v[68:71]
	v_mfma_f32_16x16x32_bf16 v[112:115], v[152:155], v[160:163], v[112:115]
	v_mfma_f32_16x16x32_bf16 v[112:115], v[156:159], v[164:167], v[112:115]
	v_mfma_f32_16x16x32_bf16 v[96:99], v[152:155], v[168:171], v[96:99]
	v_mfma_f32_16x16x32_bf16 v[96:99], v[156:159], v[172:175], v[96:99]
	v_mfma_f32_16x16x32_bf16 v[80:83], v[152:155], v[196:199], v[80:83]
	v_mfma_f32_16x16x32_bf16 v[80:83], v[156:159], v[202:205], v[80:83]
	v_mfma_f32_16x16x32_bf16 v[64:67], v[152:155], v[206:209], v[64:67]
	v_mfma_f32_16x16x32_bf16 v[64:67], v[156:159], v[232:235], v[64:67]
	s_barrier
	s_setprio 0
	s_add_i32 s16, s72, s26
	v_lshl_add_u64 v[222:223], v[222:223], 0, s[36:37]
	s_mov_b32 m0, s16
	ds_read_b128 v[160:163], v220 offset:49152
	ds_read_b128 v[164:167], v220 offset:50176
	ds_read_b128 v[168:171], v220 offset:51200
	ds_read_b128 v[172:175], v220 offset:52224
	ds_read_b128 v[196:199], v220 offset:53248
	ds_read_b128 v[202:205], v220 offset:54272
	ds_read_b128 v[206:209], v220 offset:55296
	ds_read_b128 v[232:235], v220 offset:56320
	global_load_lds_dwordx4 v[222:223], off
	s_add_i32 m0, s16, 0x2000
	s_add_u32 s14, s14, 0x80080
	v_lshl_add_u64 v[222:223], v[228:229], 0, s[36:37]
	s_addc_u32 s15, s15, 0
	s_add_i32 s16, s73, s26
	global_load_lds_dwordx4 v[222:223], off
	v_lshl_add_u64 v[222:223], s[14:15], 0, v[182:183]
	s_mov_b32 m0, s16
	s_nop 0
	global_load_lds_dwordx4 v[222:223], off
	v_lshl_add_u64 v[222:223], s[14:15], 0, v[186:187]
	s_add_i32 m0, s16, 0x2000
	s_nop 0
	global_load_lds_dwordx4 v[222:223], off
	v_lshl_add_u64 v[222:223], v[236:237], 0, s[36:37]
	s_mov_b32 m0, s44
	s_nop 0
	global_load_lds_dwordx4 v[222:223], off
	v_lshl_add_u64 v[222:223], v[238:239], 0, s[36:37]
	s_mov_b32 m0, s45
	s_nop 0
	global_load_lds_dwordx4 v[222:223], off
	s_waitcnt vmcnt(8)
	s_waitcnt lgkmcnt(0)
	s_setprio 1
	s_barrier
; #define PG8_STAGE(bufoff, gbase, voff) do { _Pragma("unroll") for (int _i = 0; _i < 2; ++_i) \
;         __builtin_amdgcn_global_load_lds((const unsigned*)((const char*)(gbase) + (voff)[_i]), (PG8_LAS unsigned*)(lds + (bufoff) + ldsw + _i * 8192), 16, 0, 0); } while (0)
; #define PG8_LDA(dst, b, h) do { _Pragma("unroll") for (int m = 0; m < 4; ++m) _Pragma("unroll") for (int k = 0; k < 2; ++k) dst[m][k] = *(const PG8_LAS bf16x8*)(lds + PG8_SA(b, h) + aoff + m * 2048 + k * 1024); } while (0)
; #define PG8_LDB(dst, b, h) do { _Pragma("unroll") for (int n = 0; n < 2; ++n) _Pragma("unroll") for (int k = 0; k < 2; ++k) dst[n][k] = *(const PG8_LAS bf16x8*)(lds + PG8_SB(b, h) + boff + n * 2048 + k * 1024); } while (0)
; #define PG8_MMA(ai, bj, At, Bt) do { __builtin_amdgcn_s_setprio(1); _Pragma("unroll") for (int m = 0; m < 4; ++m) _Pragma("unroll") for (int n = 0; n < 2; ++n) _Pragma("unroll") for (int k = 0; k < 2; ++k) \
;         acc[ai][bj][m][n] = __builtin_amdgcn_mfma_f32_16x16x32_bf16(Bt[n][k], At[m][k], acc[ai][bj][m][n], 0, 0, 0); __builtin_amdgcn_s_setprio(0); } while (0)
; #define PG8_BAR __builtin_amdgcn_s_barrier()
; template <class Epi, class Sched, bool ALIGN_EPI = false, bool SP2 = false, bool DUAL = false>
; __device__ __forceinline__ void gemm_phase(PG8_LAS unsigned char* lds, const Gemm g, const Sched& S, const Epi& E) {
;     ...
;             PG8_LDB(B0, 0, 0); PG8_LDB(B1, 0, 1); PG8_SCHED; PG8_LDA(At, 0, 0); PG8_STAGE(PG8_SA(1, 1), a1 + hstep, voffA);
;             PG8_WAIT_V(8); PG8_WAIT_L(0); PG8_BAR; PG8_MMA(0, 0, At, B0); PG8_MMA(0, 1, At, B1); PG8_BAR; PG8_SCHED;
;             PG8_LDA(At, 0, 1); PG8_STAGE(PG8_SB(0, 0), b2, voffB); PG8_STAGE(PG8_SB(0, 1), b2 + hstep, voffB); PG8_STAGE(PG8_SA(0, 0), a2, voffA);
;             PG8_WAIT_V(8); PG8_WAIT_L(0); PG8_BAR; PG8_MMA(1, 0, At, B0); PG8_MMA(1, 1, At, B1); PG8_BAR; PG8_SCHED;
;             PG8_LDB(B0, 1, 0); PG8_LDB(B1, 1, 1); PG8_SCHED; PG8_LDA(At, 1, 0); PG8_STAGE(PG8_SA(0, 1), a2 + hstep, voffA);
;             PG8_WAIT_V(8); PG8_WAIT_L(0); PG8_BAR; PG8_MMA(0, 0, At, B0); PG8_MMA(0, 1, At, B1); PG8_BAR; PG8_SCHED;
;             PG8_LDA(At, 1, 1); PG8_STAGE(PG8_SB(1, 0), b3, voffB); PG8_STAGE(PG8_SB(1, 1), b3 + hstep, voffB); PG8_STAGE(PG8_SA(1, 0), a3, voffA);
;             PG8_WAIT_V(8); PG8_WAIT_L(0); PG8_BAR; PG8_MMA(1, 0, At, B0); PG8_MMA(1, 1, At, B1); PG8_BAR; PG8_SCHED;
	v_mfma_f32_16x16x32_bf16 v[60:63], v[128:131], v[160:163], v[60:63]
	v_mfma_f32_16x16x32_bf16 v[60:63], v[132:135], v[164:167], v[60:63]
	v_mfma_f32_16x16x32_bf16 v[44:47], v[128:131], v[168:171], v[44:47]
	v_mfma_f32_16x16x32_bf16 v[44:47], v[132:135], v[172:175], v[44:47]
	v_mfma_f32_16x16x32_bf16 v[28:31], v[128:131], v[196:199], v[28:31]
	v_mfma_f32_16x16x32_bf16 v[28:31], v[132:135], v[202:205], v[28:31]
	v_mfma_f32_16x16x32_bf16 v[12:15], v[128:131], v[206:209], v[12:15]
	v_mfma_f32_16x16x32_bf16 v[12:15], v[132:135], v[232:235], v[12:15]
	v_mfma_f32_16x16x32_bf16 v[56:59], v[136:139], v[160:163], v[56:59]
	v_mfma_f32_16x16x32_bf16 v[56:59], v[140:143], v[164:167], v[56:59]
	v_mfma_f32_16x16x32_bf16 v[40:43], v[136:139], v[168:171], v[40:43]
	v_mfma_f32_16x16x32_bf16 v[40:43], v[140:143], v[172:175], v[40:43]
	v_mfma_f32_16x16x32_bf16 v[24:27], v[136:139], v[196:199], v[24:27]
	v_mfma_f32_16x16x32_bf16 v[24:27], v[140:143], v[202:205], v[24:27]
	v_mfma_f32_16x16x32_bf16 v[8:11], v[136:139], v[206:209], v[8:11]
	v_mfma_f32_16x16x32_bf16 v[8:11], v[140:143], v[232:235], v[8:11]
	s_setprio 0
	s_setprio 1
	v_mfma_f32_16x16x32_bf16 v[52:55], v[144:147], v[160:163], v[52:55]
	v_mfma_f32_16x16x32_bf16 v[52:55], v[148:151], v[164:167], v[52:55]
	v_mfma_f32_16x16x32_bf16 v[36:39], v[144:147], v[168:171], v[36:39]
	v_mfma_f32_16x16x32_bf16 v[36:39], v[148:151], v[172:175], v[36:39]
	v_mfma_f32_16x16x32_bf16 v[20:23], v[144:147], v[196:199], v[20:23]
	v_mfma_f32_16x16x32_bf16 v[20:23], v[148:151], v[202:205], v[20:23]
	v_mfma_f32_16x16x32_bf16 v[4:7], v[144:147], v[206:209], v[4:7]
	v_mfma_f32_16x16x32_bf16 v[4:7], v[148:151], v[232:235], v[4:7]
	v_mfma_f32_16x16x32_bf16 v[48:51], v[152:155], v[160:163], v[48:51]
	v_mfma_f32_16x16x32_bf16 v[48:51], v[156:159], v[164:167], v[48:51]
	v_mfma_f32_16x16x32_bf16 v[32:35], v[152:155], v[168:171], v[32:35]
	v_mfma_f32_16x16x32_bf16 v[32:35], v[156:159], v[172:175], v[32:35]
	v_mfma_f32_16x16x32_bf16 v[16:19], v[152:155], v[196:199], v[16:19]
	v_mfma_f32_16x16x32_bf16 v[16:19], v[156:159], v[202:205], v[16:19]
	v_mfma_f32_16x16x32_bf16 v[0:3], v[152:155], v[206:209], v[0:3]
	v_mfma_f32_16x16x32_bf16 v[0:3], v[156:159], v[232:235], v[0:3]
	s_barrier
	s_setprio 0
	s_add_i32 s71, s71, 2
	s_add_u32 s68, s68, 0x100
	s_addc_u32 s69, s69, 0
	s_add_u32 s67, s67, 0x100
	s_addc_u32 s70, s70, 0
.LBB0_896:
	ds_read_b128 v[128:131], v218
	ds_read_b128 v[132:135], v218 offset:1024
	ds_read_b128 v[136:139], v218 offset:2048
	ds_read_b128 v[140:143], v218 offset:3072
	ds_read_b128 v[144:147], v219
	ds_read_b128 v[148:151], v219 offset:1024
	ds_read_b128 v[152:155], v219 offset:2048
	ds_read_b128 v[156:159], v219 offset:3072
	s_add_u32 s14, s68, 0xfff80080
	s_addc_u32 s15, s69, -1
	s_cmp_eq_u32 s71, 28
	s_cselect_b32 s17, s18, s15
	s_cselect_b32 s16, s19, s14
	s_cselect_b32 s15, s41, s70
	s_cselect_b32 s14, s61, s67
	v_lshl_add_u64 v[222:223], s[68:69], 0, v[188:189]
	s_add_i32 m0, s27, 0xc000
	ds_read_b128 v[160:163], v220
	ds_read_b128 v[164:167], v220 offset:1024
	ds_read_b128 v[168:171], v220 offset:2048
	ds_read_b128 v[172:175], v220 offset:3072
	ds_read_b128 v[196:199], v220 offset:4096
	ds_read_b128 v[202:205], v220 offset:5120
	ds_read_b128 v[206:209], v220 offset:6144
	ds_read_b128 v[232:235], v220 offset:7168
	global_load_lds_dwordx4 v[222:223], off
	v_lshl_add_u64 v[222:223], s[68:69], 0, v[190:191]
	s_add_i32 m0, s27, 0xe000
	s_nop 0
	global_load_lds_dwordx4 v[222:223], off
	s_waitcnt vmcnt(8)
	s_waitcnt lgkmcnt(0)
	s_setprio 1
	s_barrier
	v_mfma_f32_16x16x32_bf16 v[124:127], v[128:131], v[160:163], v[124:127]
	v_mfma_f32_16x16x32_bf16 v[124:127], v[132:135], v[164:167], v[124:127]
	v_mfma_f32_16x16x32_bf16 v[108:111], v[128:131], v[168:171], v[108:111]
	v_mfma_f32_16x16x32_bf16 v[108:111], v[132:135], v[172:175], v[108:111]
	v_mfma_f32_16x16x32_bf16 v[92:95], v[128:131], v[196:199], v[92:95]
	v_mfma_f32_16x16x32_bf16 v[92:95], v[132:135], v[202:205], v[92:95]
	v_mfma_f32_16x16x32_bf16 v[76:79], v[128:131], v[206:209], v[76:79]
	v_mfma_f32_16x16x32_bf16 v[76:79], v[132:135], v[232:235], v[76:79]
	v_mfma_f32_16x16x32_bf16 v[120:123], v[136:139], v[160:163], v[120:123]
	v_mfma_f32_16x16x32_bf16 v[120:123], v[140:143], v[164:167], v[120:123]
	v_mfma_f32_16x16x32_bf16 v[104:107], v[136:139], v[168:171], v[104:107]
	v_mfma_f32_16x16x32_bf16 v[104:107], v[140:143], v[172:175], v[104:107]
	v_mfma_f32_16x16x32_bf16 v[88:91], v[136:139], v[196:199], v[88:91]
	v_mfma_f32_16x16x32_bf16 v[88:91], v[140:143], v[202:205], v[88:91]
	v_mfma_f32_16x16x32_bf16 v[72:75], v[136:139], v[206:209], v[72:75]
	v_mfma_f32_16x16x32_bf16 v[72:75], v[140:143], v[232:235], v[72:75]
	s_setprio 0
	s_setprio 1
	v_mfma_f32_16x16x32_bf16 v[116:119], v[144:147], v[160:163], v[116:119]
	v_mfma_f32_16x16x32_bf16 v[116:119], v[148:151], v[164:167], v[116:119]
	v_mfma_f32_16x16x32_bf16 v[100:103], v[144:147], v[168:171], v[100:103]
	v_mfma_f32_16x16x32_bf16 v[100:103], v[148:151], v[172:175], v[100:103]
	v_mfma_f32_16x16x32_bf16 v[84:87], v[144:147], v[196:199], v[84:87]
	v_mfma_f32_16x16x32_bf16 v[84:87], v[148:151], v[202:205], v[84:87]
	v_mfma_f32_16x16x32_bf16 v[68:71], v[144:147], v[206:209], v[68:71]
	v_mfma_f32_16x16x32_bf16 v[68:71], v[148:151], v[232:235], v[68:71]
	v_mfma_f32_16x16x32_bf16 v[112:115], v[152:155], v[160:163], v[112:115]
	v_mfma_f32_16x16x32_bf16 v[112:115], v[156:159], v[164:167], v[112:115]
	v_mfma_f32_16x16x32_bf16 v[96:99], v[152:155], v[168:171], v[96:99]
	v_mfma_f32_16x16x32_bf16 v[96:99], v[156:159], v[172:175], v[96:99]
	v_mfma_f32_16x16x32_bf16 v[80:83], v[152:155], v[196:199], v[80:83]
	v_mfma_f32_16x16x32_bf16 v[80:83], v[156:159], v[202:205], v[80:83]
	v_mfma_f32_16x16x32_bf16 v[64:67], v[152:155], v[206:209], v[64:67]
	v_mfma_f32_16x16x32_bf16 v[64:67], v[156:159], v[232:235], v[64:67]
	s_barrier
; #define PG8_STAGE(bufoff, gbase, voff) do { _Pragma("unroll") for (int _i = 0; _i < 2; ++_i) \
;         __builtin_amdgcn_global_load_lds((const unsigned*)((const char*)(gbase) + (voff)[_i]), (PG8_LAS unsigned*)(lds + (bufoff) + ldsw + _i * 8192), 16, 0, 0); } while (0)
; #define PG8_LDA(dst, b, h) do { _Pragma("unroll") for (int m = 0; m < 4; ++m) _Pragma("unroll") for (int k = 0; k < 2; ++k) dst[m][k] = *(const PG8_LAS bf16x8*)(lds + PG8_SA(b, h) + aoff + m * 2048 + k * 1024); } while (0)
; #define PG8_LDB(dst, b, h) do { _Pragma("unroll") for (int n = 0; n < 2; ++n) _Pragma("unroll") for (int k = 0; k < 2; ++k) dst[n][k] = *(const PG8_LAS bf16x8*)(lds + PG8_SB(b, h) + boff + n * 2048 + k * 1024); } while (0)
; #define PG8_MMA(ai, bj, At, Bt) do { __builtin_amdgcn_s_setprio(1); _Pragma("unroll") for (int m = 0; m < 4; ++m) _Pragma("unroll") for (int n = 0; n < 2; ++n) _Pragma("unroll") for (int k = 0; k < 2; ++k) \
;         acc[ai][bj][m][n] = __builtin_amdgcn_mfma_f32_16x16x32_bf16(Bt[n][k], At[m][k], acc[ai][bj][m][n], 0, 0, 0); __builtin_amdgcn_s_setprio(0); } while (0)
; #define PG8_WAIT_V(n) asm volatile("s_waitcnt vmcnt(" #n ")" ::: "memory")
; #define PG8_WAIT_L(n) asm volatile("s_waitcnt lgkmcnt(" #n ")" ::: "memory")
; #define PG8_BAR __builtin_amdgcn_s_barrier()
; #define PG8_SCHED __builtin_amdgcn_sched_barrier(0)
; template <class Epi, class Sched, bool ALIGN_EPI = false, bool SP2 = false, bool DUAL = false>
; __device__ __forceinline__ void gemm_phase(PG8_LAS unsigned char* lds, const Gemm g, const Sched& S, const Epi& E) {
;     ...
;             PG8_LDA(At, 0, 1); PG8_STAGE(PG8_SB(0, 0), b2, voffB); PG8_STAGE(PG8_SB(0, 1), b2 + hstep, voffB); PG8_STAGE(PG8_SA(0, 0), a2, voffA);
;             PG8_WAIT_V(8); PG8_WAIT_L(0); PG8_BAR; PG8_MMA(1, 0, At, B0); PG8_MMA(1, 1, At, B1); PG8_BAR; PG8_SCHED;
;             PG8_LDB(B0, 1, 0); PG8_LDB(B1, 1, 1); PG8_SCHED; PG8_LDA(At, 1, 0); PG8_STAGE(PG8_SA(0, 1), a2 + hstep, voffA);
;             PG8_WAIT_V(8); PG8_WAIT_L(0); PG8_BAR; PG8_MMA(0, 0, At, B0); PG8_MMA(0, 1, At, B1); PG8_BAR; PG8_SCHED;
	s_setprio 0
	s_add_i32 s72, s48, s26
	v_lshl_add_u64 v[222:223], s[14:15], 0, v[182:183]
	s_mov_b32 m0, s72
	ds_read_b128 v[160:163], v220 offset:16384
	ds_read_b128 v[164:167], v220 offset:17408
	ds_read_b128 v[168:171], v220 offset:18432
	ds_read_b128 v[172:175], v220 offset:19456
	ds_read_b128 v[196:199], v220 offset:20480
	ds_read_b128 v[202:205], v220 offset:21504
	ds_read_b128 v[206:209], v220 offset:22528
	ds_read_b128 v[232:235], v220 offset:23552
	global_load_lds_dwordx4 v[222:223], off
	s_add_i32 m0, s72, 0x2000
	s_add_u32 s72, s14, 0x80000
	v_lshl_add_u64 v[228:229], s[14:15], 0, v[186:187]
	s_addc_u32 s73, s15, 0
	s_add_i32 s74, s49, s26
	global_load_lds_dwordx4 v[228:229], off
	v_lshl_add_u64 v[236:237], s[72:73], 0, v[182:183]
	s_mov_b32 m0, s74
	v_lshl_add_u64 v[238:239], s[16:17], 0, v[184:185]
	global_load_lds_dwordx4 v[236:237], off
	v_lshl_add_u64 v[236:237], s[72:73], 0, v[186:187]
	s_add_i32 m0, s74, 0x2000
	s_nop 0
	global_load_lds_dwordx4 v[236:237], off
	v_lshl_add_u64 v[236:237], s[16:17], 0, v[180:181]
	s_mov_b32 m0, s27
	s_nop 0
	global_load_lds_dwordx4 v[236:237], off
	s_mov_b32 m0, s28
	s_nop 0
	global_load_lds_dwordx4 v[238:239], off
	s_waitcnt vmcnt(8)
	s_waitcnt lgkmcnt(0)
	s_setprio 1
	s_barrier
	v_mfma_f32_16x16x32_bf16 v[60:63], v[128:131], v[160:163], v[60:63]
	v_mfma_f32_16x16x32_bf16 v[60:63], v[132:135], v[164:167], v[60:63]
	v_mfma_f32_16x16x32_bf16 v[44:47], v[128:131], v[168:171], v[44:47]
	v_mfma_f32_16x16x32_bf16 v[44:47], v[132:135], v[172:175], v[44:47]
	v_mfma_f32_16x16x32_bf16 v[28:31], v[128:131], v[196:199], v[28:31]
	v_mfma_f32_16x16x32_bf16 v[28:31], v[132:135], v[202:205], v[28:31]
	v_mfma_f32_16x16x32_bf16 v[12:15], v[128:131], v[206:209], v[12:15]
	v_mfma_f32_16x16x32_bf16 v[12:15], v[132:135], v[232:235], v[12:15]
	v_mfma_f32_16x16x32_bf16 v[56:59], v[136:139], v[160:163], v[56:59]
	v_mfma_f32_16x16x32_bf16 v[56:59], v[140:143], v[164:167], v[56:59]
	v_mfma_f32_16x16x32_bf16 v[40:43], v[136:139], v[168:171], v[40:43]
	v_mfma_f32_16x16x32_bf16 v[40:43], v[140:143], v[172:175], v[40:43]
	v_mfma_f32_16x16x32_bf16 v[24:27], v[136:139], v[196:199], v[24:27]
	v_mfma_f32_16x16x32_bf16 v[24:27], v[140:143], v[202:205], v[24:27]
	v_mfma_f32_16x16x32_bf16 v[8:11], v[136:139], v[206:209], v[8:11]
	v_mfma_f32_16x16x32_bf16 v[8:11], v[140:143], v[232:235], v[8:11]
	s_setprio 0
	s_setprio 1
	v_mfma_f32_16x16x32_bf16 v[52:55], v[144:147], v[160:163], v[52:55]
	v_mfma_f32_16x16x32_bf16 v[52:55], v[148:151], v[164:167], v[52:55]
	v_mfma_f32_16x16x32_bf16 v[36:39], v[144:147], v[168:171], v[36:39]
	v_mfma_f32_16x16x32_bf16 v[36:39], v[148:151], v[172:175], v[36:39]
	v_mfma_f32_16x16x32_bf16 v[20:23], v[144:147], v[196:199], v[20:23]
	v_mfma_f32_16x16x32_bf16 v[20:23], v[148:151], v[202:205], v[20:23]
	v_mfma_f32_16x16x32_bf16 v[4:7], v[144:147], v[206:209], v[4:7]
	v_mfma_f32_16x16x32_bf16 v[4:7], v[148:151], v[232:235], v[4:7]
	v_mfma_f32_16x16x32_bf16 v[48:51], v[152:155], v[160:163], v[48:51]
	v_mfma_f32_16x16x32_bf16 v[48:51], v[156:159], v[164:167], v[48:51]
	v_mfma_f32_16x16x32_bf16 v[32:35], v[152:155], v[168:171], v[32:35]
	v_mfma_f32_16x16x32_bf16 v[32:35], v[156:159], v[172:175], v[32:35]
	v_mfma_f32_16x16x32_bf16 v[16:19], v[152:155], v[196:199], v[16:19]
	v_mfma_f32_16x16x32_bf16 v[16:19], v[156:159], v[202:205], v[16:19]
	v_mfma_f32_16x16x32_bf16 v[0:3], v[152:155], v[206:209], v[0:3]
	v_mfma_f32_16x16x32_bf16 v[0:3], v[156:159], v[232:235], v[0:3]
	s_barrier
	s_setprio 0
	s_add_i32 s72, 0, 0x18000
	s_add_i32 s73, 0, 0x1c000
	v_add_u32_e32 v140, s72, v216
	v_add_u32_e32 v156, s73, v216
	ds_read_b128 v[128:131], v140
	ds_read_b128 v[132:135], v140 offset:1024
	ds_read_b128 v[136:139], v140 offset:2048
	ds_read_b128 v[140:143], v140 offset:3072
	ds_read_b128 v[144:147], v156
	ds_read_b128 v[148:151], v156 offset:1024
	ds_read_b128 v[152:155], v156 offset:2048
	ds_read_b128 v[156:159], v156 offset:3072
	s_add_u32 s16, s16, 0x80000
	s_addc_u32 s17, s17, 0
	s_mov_b32 m0, s29
	v_lshl_add_u64 v[240:241], s[16:17], 0, v[180:181]
	ds_read_b128 v[160:163], v220 offset:32768
	ds_read_b128 v[164:167], v220 offset:33792
	ds_read_b128 v[168:171], v220 offset:34816
	ds_read_b128 v[172:175], v220 offset:35840
	ds_read_b128 v[196:199], v220 offset:36864
	ds_read_b128 v[202:205], v220 offset:37888
	ds_read_b128 v[206:209], v220 offset:38912
	ds_read_b128 v[232:235], v220 offset:39936
	global_load_lds_dwordx4 v[240:241], off
	v_lshl_add_u64 v[240:241], s[16:17], 0, v[184:185]
	s_mov_b32 m0, s34
	s_nop 0
	global_load_lds_dwordx4 v[240:241], off
	s_waitcnt vmcnt(8)
	s_waitcnt lgkmcnt(0)
	s_setprio 1
	s_barrier
; #define PG8_STAGE(bufoff, gbase, voff) do { _Pragma("unroll") for (int _i = 0; _i < 2; ++_i) \
;         __builtin_amdgcn_global_load_lds((const unsigned*)((const char*)(gbase) + (voff)[_i]), (PG8_LAS unsigned*)(lds + (bufoff) + ldsw + _i * 8192), 16, 0, 0); } while (0)
; #define PG8_LDA(dst, b, h) do { _Pragma("unroll") for (int m = 0; m < 4; ++m) _Pragma("unroll") for (int k = 0; k < 2; ++k) dst[m][k] = *(const PG8_LAS bf16x8*)(lds + PG8_SA(b, h) + aoff + m * 2048 + k * 1024); } while (0)
; #define PG8_MMA(ai, bj, At, Bt) do { __builtin_amdgcn_s_setprio(1); _Pragma("unroll") for (int m = 0; m < 4; ++m) _Pragma("unroll") for (int n = 0; n < 2; ++n) _Pragma("unroll") for (int k = 0; k < 2; ++k) \
;         acc[ai][bj][m][n] = __builtin_amdgcn_mfma_f32_16x16x32_bf16(Bt[n][k], At[m][k], acc[ai][bj][m][n], 0, 0, 0); __builtin_amdgcn_s_setprio(0); } while (0)
; #define PG8_WAIT_V(n) asm volatile("s_waitcnt vmcnt(" #n ")" ::: "memory")
; #define PG8_WAIT_L(n) asm volatile("s_waitcnt lgkmcnt(" #n ")" ::: "memory")
; #define PG8_BAR __builtin_amdgcn_s_barrier()
; #define PG8_SCHED __builtin_amdgcn_sched_barrier(0)
; template <class Epi, class Sched, bool ALIGN_EPI = false, bool SP2 = false, bool DUAL = false>
; __device__ __forceinline__ void gemm_phase(PG8_LAS unsigned char* lds, const Gemm g, const Sched& S, const Epi& E) {
;     ...
;             PG8_WAIT_V(8); PG8_WAIT_L(0); PG8_BAR; PG8_MMA(0, 0, At, B0); PG8_MMA(0, 1, At, B1); PG8_BAR; PG8_SCHED;
;             PG8_LDA(At, 1, 1); PG8_STAGE(PG8_SB(1, 0), b3, voffB); PG8_STAGE(PG8_SB(1, 1), b3 + hstep, voffB); PG8_STAGE(PG8_SA(1, 0), a3, voffA);
;             PG8_WAIT_V(8); PG8_WAIT_L(0); PG8_BAR; PG8_MMA(1, 0, At, B0); PG8_MMA(1, 1, At, B1); PG8_BAR; PG8_SCHED;
	v_mfma_f32_16x16x32_bf16 v[124:127], v[128:131], v[160:163], v[124:127]
	v_mfma_f32_16x16x32_bf16 v[124:127], v[132:135], v[164:167], v[124:127]
	v_mfma_f32_16x16x32_bf16 v[108:111], v[128:131], v[168:171], v[108:111]
	v_mfma_f32_16x16x32_bf16 v[108:111], v[132:135], v[172:175], v[108:111]
	v_mfma_f32_16x16x32_bf16 v[92:95], v[128:131], v[196:199], v[92:95]
	v_mfma_f32_16x16x32_bf16 v[92:95], v[132:135], v[202:205], v[92:95]
	v_mfma_f32_16x16x32_bf16 v[76:79], v[128:131], v[206:209], v[76:79]
	v_mfma_f32_16x16x32_bf16 v[76:79], v[132:135], v[232:235], v[76:79]
	v_mfma_f32_16x16x32_bf16 v[120:123], v[136:139], v[160:163], v[120:123]
	v_mfma_f32_16x16x32_bf16 v[120:123], v[140:143], v[164:167], v[120:123]
	v_mfma_f32_16x16x32_bf16 v[104:107], v[136:139], v[168:171], v[104:107]
	v_mfma_f32_16x16x32_bf16 v[104:107], v[140:143], v[172:175], v[104:107]
	v_mfma_f32_16x16x32_bf16 v[88:91], v[136:139], v[196:199], v[88:91]
	v_mfma_f32_16x16x32_bf16 v[88:91], v[140:143], v[202:205], v[88:91]
	v_mfma_f32_16x16x32_bf16 v[72:75], v[136:139], v[206:209], v[72:75]
	v_mfma_f32_16x16x32_bf16 v[72:75], v[140:143], v[232:235], v[72:75]
	s_setprio 0
	s_setprio 1
	v_mfma_f32_16x16x32_bf16 v[116:119], v[144:147], v[160:163], v[116:119]
	v_mfma_f32_16x16x32_bf16 v[116:119], v[148:151], v[164:167], v[116:119]
	v_mfma_f32_16x16x32_bf16 v[100:103], v[144:147], v[168:171], v[100:103]
	v_mfma_f32_16x16x32_bf16 v[100:103], v[148:151], v[172:175], v[100:103]
	v_mfma_f32_16x16x32_bf16 v[84:87], v[144:147], v[196:199], v[84:87]
	v_mfma_f32_16x16x32_bf16 v[84:87], v[148:151], v[202:205], v[84:87]
	v_mfma_f32_16x16x32_bf16 v[68:71], v[144:147], v[206:209], v[68:71]
	v_mfma_f32_16x16x32_bf16 v[68:71], v[148:151], v[232:235], v[68:71]
	v_mfma_f32_16x16x32_bf16 v[112:115], v[152:155], v[160:163], v[112:115]
	v_mfma_f32_16x16x32_bf16 v[112:115], v[156:159], v[164:167], v[112:115]
	v_mfma_f32_16x16x32_bf16 v[96:99], v[152:155], v[168:171], v[96:99]
	v_mfma_f32_16x16x32_bf16 v[96:99], v[156:159], v[172:175], v[96:99]
	v_mfma_f32_16x16x32_bf16 v[80:83], v[152:155], v[196:199], v[80:83]
	v_mfma_f32_16x16x32_bf16 v[80:83], v[156:159], v[202:205], v[80:83]
	v_mfma_f32_16x16x32_bf16 v[64:67], v[152:155], v[206:209], v[64:67]
	v_mfma_f32_16x16x32_bf16 v[64:67], v[156:159], v[232:235], v[64:67]
	s_barrier
	s_setprio 0
	s_add_i32 s16, s72, s26
	v_lshl_add_u64 v[222:223], v[222:223], 0, s[36:37]
	s_mov_b32 m0, s16
	ds_read_b128 v[160:163], v220 offset:49152
	ds_read_b128 v[164:167], v220 offset:50176
	ds_read_b128 v[168:171], v220 offset:51200
	ds_read_b128 v[172:175], v220 offset:52224
	ds_read_b128 v[196:199], v220 offset:53248
	ds_read_b128 v[202:205], v220 offset:54272
	ds_read_b128 v[206:209], v220 offset:55296
	ds_read_b128 v[232:235], v220 offset:56320
	global_load_lds_dwordx4 v[222:223], off
	s_add_i32 m0, s16, 0x2000
	s_add_u32 s14, s14, 0x80080
	v_lshl_add_u64 v[222:223], v[228:229], 0, s[36:37]
	s_addc_u32 s15, s15, 0
	s_add_i32 s16, s73, s26
	global_load_lds_dwordx4 v[222:223], off
	v_lshl_add_u64 v[222:223], s[14:15], 0, v[182:183]
	s_mov_b32 m0, s16
	s_nop 0
	global_load_lds_dwordx4 v[222:223], off
	v_lshl_add_u64 v[222:223], s[14:15], 0, v[186:187]
	s_add_i32 m0, s16, 0x2000
	s_nop 0
	global_load_lds_dwordx4 v[222:223], off
	v_lshl_add_u64 v[222:223], v[236:237], 0, s[36:37]
	s_mov_b32 m0, s44
	s_nop 0
	global_load_lds_dwordx4 v[222:223], off
	v_lshl_add_u64 v[222:223], v[238:239], 0, s[36:37]
	s_mov_b32 m0, s45
	s_nop 0
	global_load_lds_dwordx4 v[222:223], off
	s_waitcnt vmcnt(8)
	s_waitcnt lgkmcnt(0)
	s_setprio 1
	s_barrier
	v_mfma_f32_16x16x32_bf16 v[60:63], v[128:131], v[160:163], v[60:63]
	v_mfma_f32_16x16x32_bf16 v[60:63], v[132:135], v[164:167], v[60:63]
	v_mfma_f32_16x16x32_bf16 v[44:47], v[128:131], v[168:171], v[44:47]
	v_mfma_f32_16x16x32_bf16 v[44:47], v[132:135], v[172:175], v[44:47]
	v_mfma_f32_16x16x32_bf16 v[28:31], v[128:131], v[196:199], v[28:31]
	v_mfma_f32_16x16x32_bf16 v[28:31], v[132:135], v[202:205], v[28:31]
	v_mfma_f32_16x16x32_bf16 v[12:15], v[128:131], v[206:209], v[12:15]
	v_mfma_f32_16x16x32_bf16 v[12:15], v[132:135], v[232:235], v[12:15]
	v_mfma_f32_16x16x32_bf16 v[56:59], v[136:139], v[160:163], v[56:59]
	v_mfma_f32_16x16x32_bf16 v[56:59], v[140:143], v[164:167], v[56:59]
	v_mfma_f32_16x16x32_bf16 v[40:43], v[136:139], v[168:171], v[40:43]
	v_mfma_f32_16x16x32_bf16 v[40:43], v[140:143], v[172:175], v[40:43]
	v_mfma_f32_16x16x32_bf16 v[24:27], v[136:139], v[196:199], v[24:27]
	v_mfma_f32_16x16x32_bf16 v[24:27], v[140:143], v[202:205], v[24:27]
	v_mfma_f32_16x16x32_bf16 v[8:11], v[136:139], v[206:209], v[8:11]
	v_mfma_f32_16x16x32_bf16 v[8:11], v[140:143], v[232:235], v[8:11]
	s_setprio 0
	s_setprio 1
	v_mfma_f32_16x16x32_bf16 v[52:55], v[144:147], v[160:163], v[52:55]
	v_mfma_f32_16x16x32_bf16 v[52:55], v[148:151], v[164:167], v[52:55]
	v_mfma_f32_16x16x32_bf16 v[36:39], v[144:147], v[168:171], v[36:39]
	v_mfma_f32_16x16x32_bf16 v[36:39], v[148:151], v[172:175], v[36:39]
	v_mfma_f32_16x16x32_bf16 v[20:23], v[144:147], v[196:199], v[20:23]
	v_mfma_f32_16x16x32_bf16 v[20:23], v[148:151], v[202:205], v[20:23]
	v_mfma_f32_16x16x32_bf16 v[4:7], v[144:147], v[206:209], v[4:7]
	v_mfma_f32_16x16x32_bf16 v[4:7], v[148:151], v[232:235], v[4:7]
	v_mfma_f32_16x16x32_bf16 v[48:51], v[152:155], v[160:163], v[48:51]
	v_mfma_f32_16x16x32_bf16 v[48:51], v[156:159], v[164:167], v[48:51]
	v_mfma_f32_16x16x32_bf16 v[32:35], v[152:155], v[168:171], v[32:35]
	v_mfma_f32_16x16x32_bf16 v[32:35], v[156:159], v[172:175], v[32:35]
	v_mfma_f32_16x16x32_bf16 v[16:19], v[152:155], v[196:199], v[16:19]
	v_mfma_f32_16x16x32_bf16 v[16:19], v[156:159], v[202:205], v[16:19]
	v_mfma_f32_16x16x32_bf16 v[0:3], v[152:155], v[206:209], v[0:3]
	v_mfma_f32_16x16x32_bf16 v[0:3], v[156:159], v[232:235], v[0:3]
	s_barrier
	s_setprio 0
	s_add_i32 s71, s71, 2
	s_add_u32 s68, s68, 0x100
	s_addc_u32 s69, s69, 0
	s_add_u32 s67, s67, 0x100
	s_addc_u32 s70, s70, 0
	s_cmp_gt_u32 s71, 29
	s_cbranch_scc0 .LBB0_896
	s_and_b64 vcc, exec, s[38:39]
	s_cbranch_vccz .LBB0_899
	s_barrier

;     __device__ bool next(int i, Unit& u) const { if (!base.next(i >> 1, u)) return false; u.sub = i & 1; return true; }
; #define PG8_STAGE(bufoff, gbase, voff) do { _Pragma("unroll") for (int _i = 0; _i < 2; ++_i) \
;         __builtin_amdgcn_global_load_lds((const unsigned*)((const char*)(gbase) + (voff)[_i]), (PG8_LAS unsigned*)(lds + (bufoff) + ldsw + _i * 8192), 16, 0, 0); } while (0)
; #define PG8_LDA(dst, b, h) do { _Pragma("unroll") for (int m = 0; m < 4; ++m) _Pragma("unroll") for (int k = 0; k < 2; ++k) dst[m][k] = *(const PG8_LAS bf16x8*)(lds + PG8_SA(b, h) + aoff + m * 2048 + k * 1024); } while (0)
; #define PG8_LDB(dst, b, h) do { _Pragma("unroll") for (int n = 0; n < 2; ++n) _Pragma("unroll") for (int k = 0; k < 2; ++k) dst[n][k] = *(const PG8_LAS bf16x8*)(lds + PG8_SB(b, h) + boff + n * 2048 + k * 1024); } while (0)
; #define PG8_WAIT_V(n) asm volatile("s_waitcnt vmcnt(" #n ")" ::: "memory")
; template <class Epi, class Sched, bool ALIGN_EPI = false, bool SP2 = false, bool DUAL = false>
; __device__ __forceinline__ void gemm_phase(PG8_LAS unsigned char* lds, const Gemm g, const Sched& S, const Epi& E) {
;     ...
;         const bool has_next = S.next(ui + 1, nxt);
;         const char* nA = has_next ? (const char*)((DUAL && nxt.sub) ? g.A2 : g.A) + (size_t)nxt.pm * tstep : cA; const char* nB = has_next ? (const char*)((DUAL && nxt.sub) ? g.Bt2 : g.Bt) + (size_t)nxt.pn * tstep : cB;
;         for (int t = 0; t < nt; t += 2) {
;             const bool last = (t == nt - 2);
;             const char* a1 = cA + (size_t)(t + 1) * kstep;
;             const char* a2 = last ? nA : cA + (size_t)(t + 2) * kstep; const char* b2 = last ? nB : cB + (size_t)(t + 2) * kstep;
;             const char* a3 = a2 + kstep; const char* b3 = b2 + kstep;
;             if (last && has_next) S.a_ready(nxt);
;             if constexpr (SP2) {
;             PG8_LDB(B0, 0, 0); PG8_LDB(B1, 0, 1); PG8_SCHED; PG8_LDA(At, 0, 0); PG8_STAGE(PG8_SA(1, 1), a1 + hstep, voffA);
;             PG8_WAIT_V(8); PG8_WAIT_L(0); PG8_BAR; PG8_MMA(0, 0, At, B0); PG8_MMA(0, 1, At, B1); PG8_BAR; PG8_SCHED;
;             PG8_LDA(At, 0, 1); PG8_STAGE(PG8_SB(0, 0), b2, voffB); PG8_STAGE(PG8_SB(0, 1), b2 + hstep, voffB); PG8_STAGE(PG8_SA(0, 0), a2, voffA);
;             PG8_WAIT_V(8); PG8_WAIT_L(0); PG8_BAR; PG8_MMA(1, 0, At, B0); PG8_MMA(1, 1, At, B1); PG8_BAR; PG8_SCHED;
.LBB0_991:
	s_ashr_i32 s25, s24, 31
	s_lshl_b64 s[28:29], s[24:25], 20
	s_add_u32 s30, s19, s28
	s_addc_u32 s31, s21, s29
	s_and_b64 s[28:29], s[4:5], exec
	s_cselect_b32 s25, s31, s27
	s_cselect_b32 s28, s30, s26
	s_ashr_i32 s23, s22, 31
	s_lshl_b64 s[36:37], s[22:23], 20
	s_add_u32 s36, s8, s36
	s_addc_u32 s37, s9, s37
	s_and_b64 s[40:41], s[4:5], exec
	s_cselect_b32 s23, s37, s15
	s_cselect_b32 s29, s36, s14
	s_add_u32 s40, s26, 0x80080
	s_addc_u32 s41, s27, 0
	s_add_u32 s63, s14, 0x100
	s_addc_u32 s64, s15, 0
	s_mov_b32 s65, -2
	s_add_u32 s14, s40, 0xfff80080
	s_addc_u32 s15, s41, -1
	s_cmp_eq_u32 s65, 28
	s_cselect_b32 s27, s25, s15
	s_cselect_b32 s26, s28, s14
	s_cselect_b32 s15, s23, s64
	s_cselect_b32 s14, s29, s63
	s_waitcnt vmcnt(8)
	s_waitcnt lgkmcnt(0)
	s_setprio 1
	s_barrier
	v_mfma_f32_16x16x32_bf16 v[124:127], v[128:131], v[160:163], 0
	v_mfma_f32_16x16x32_bf16 v[124:127], v[132:135], v[164:167], v[124:127]
	v_mfma_f32_16x16x32_bf16 v[108:111], v[128:131], v[188:191], 0
	v_mfma_f32_16x16x32_bf16 v[108:111], v[132:135], v[192:195], v[108:111]
	v_mfma_f32_16x16x32_bf16 v[92:95], v[128:131], v[196:199], 0
	v_mfma_f32_16x16x32_bf16 v[92:95], v[132:135], v[202:205], v[92:95]
	v_mfma_f32_16x16x32_bf16 v[76:79], v[128:131], v[206:209], 0
	v_mfma_f32_16x16x32_bf16 v[76:79], v[132:135], v[220:223], v[76:79]
	v_mfma_f32_16x16x32_bf16 v[120:123], v[136:139], v[160:163], 0
	v_mfma_f32_16x16x32_bf16 v[120:123], v[140:143], v[164:167], v[120:123]
	v_mfma_f32_16x16x32_bf16 v[104:107], v[136:139], v[188:191], 0
	v_mfma_f32_16x16x32_bf16 v[104:107], v[140:143], v[192:195], v[104:107]
	v_mfma_f32_16x16x32_bf16 v[88:91], v[136:139], v[196:199], 0
	v_mfma_f32_16x16x32_bf16 v[88:91], v[140:143], v[202:205], v[88:91]
	v_mfma_f32_16x16x32_bf16 v[72:75], v[136:139], v[206:209], 0
	v_mfma_f32_16x16x32_bf16 v[72:75], v[140:143], v[220:223], v[72:75]
	s_setprio 0
	s_setprio 1
	v_mfma_f32_16x16x32_bf16 v[116:119], v[144:147], v[160:163], 0
	v_mfma_f32_16x16x32_bf16 v[116:119], v[148:151], v[164:167], v[116:119]
	v_mfma_f32_16x16x32_bf16 v[100:103], v[144:147], v[188:191], 0
	v_mfma_f32_16x16x32_bf16 v[100:103], v[148:151], v[192:195], v[100:103]
	v_mfma_f32_16x16x32_bf16 v[84:87], v[144:147], v[196:199], 0
	v_mfma_f32_16x16x32_bf16 v[84:87], v[148:151], v[202:205], v[84:87]
	v_mfma_f32_16x16x32_bf16 v[68:71], v[144:147], v[206:209], 0
	v_mfma_f32_16x16x32_bf16 v[68:71], v[148:151], v[220:223], v[68:71]
	v_mfma_f32_16x16x32_bf16 v[112:115], v[152:155], v[160:163], 0
	v_mfma_f32_16x16x32_bf16 v[112:115], v[156:159], v[164:167], v[112:115]
	v_mfma_f32_16x16x32_bf16 v[96:99], v[152:155], v[188:191], 0
	v_mfma_f32_16x16x32_bf16 v[96:99], v[156:159], v[192:195], v[96:99]
	v_mfma_f32_16x16x32_bf16 v[80:83], v[152:155], v[196:199], 0
	v_mfma_f32_16x16x32_bf16 v[80:83], v[156:159], v[202:205], v[80:83]
	v_mfma_f32_16x16x32_bf16 v[64:67], v[152:155], v[206:209], 0
	v_mfma_f32_16x16x32_bf16 v[64:67], v[156:159], v[220:223], v[64:67]
	s_barrier
	s_setprio 0
	v_lshl_add_u64 v[228:229], s[40:41], 0, v[180:181]
	s_add_i32 m0, s39, 0xc000
	s_nop 0
	global_load_lds_dwordx4 v[228:229], off
	v_lshl_add_u64 v[228:229], s[40:41], 0, v[182:183]
	s_add_i32 m0, s39, 0xe000
	s_nop 0
	global_load_lds_dwordx4 v[228:229], off
	s_add_i32 s66, s50, s34
	v_lshl_add_u64 v[228:229], s[14:15], 0, v[170:171]
	s_mov_b32 m0, s66
	ds_read_b128 v[160:163], v217 offset:16384
	ds_read_b128 v[164:167], v217 offset:17408
	ds_read_b128 v[188:191], v217 offset:18432
	ds_read_b128 v[192:195], v217 offset:19456
	ds_read_b128 v[196:199], v217 offset:20480
	ds_read_b128 v[202:205], v217 offset:21504
	ds_read_b128 v[206:209], v217 offset:22528
	ds_read_b128 v[220:223], v217 offset:23552
	global_load_lds_dwordx4 v[228:229], off
	s_add_i32 m0, s66, 0x2000
	s_add_u32 s66, s14, 0x80000
	v_lshl_add_u64 v[232:233], s[14:15], 0, v[174:175]
	s_addc_u32 s67, s15, 0
	s_add_i32 s68, s51, s34
	global_load_lds_dwordx4 v[232:233], off
	v_lshl_add_u64 v[234:235], s[66:67], 0, v[170:171]
	s_mov_b32 m0, s68
	v_lshl_add_u64 v[236:237], s[26:27], 0, v[172:173]
	global_load_lds_dwordx4 v[234:235], off
	v_lshl_add_u64 v[234:235], s[66:67], 0, v[174:175]
	s_add_i32 m0, s68, 0x2000
	s_nop 0
	global_load_lds_dwordx4 v[234:235], off
	v_lshl_add_u64 v[234:235], s[26:27], 0, v[168:169]
	s_mov_b32 m0, s39
	s_nop 0
	global_load_lds_dwordx4 v[234:235], off
	s_mov_b32 m0, s42
	s_nop 0
	global_load_lds_dwordx4 v[236:237], off
	s_waitcnt vmcnt(8)
	s_waitcnt lgkmcnt(0)
	s_setprio 1
	s_barrier
	v_mfma_f32_16x16x32_bf16 v[60:63], v[128:131], v[160:163], 0
	v_mfma_f32_16x16x32_bf16 v[60:63], v[132:135], v[164:167], v[60:63]
	v_mfma_f32_16x16x32_bf16 v[44:47], v[128:131], v[188:191], 0
	v_mfma_f32_16x16x32_bf16 v[44:47], v[132:135], v[192:195], v[44:47]
	v_mfma_f32_16x16x32_bf16 v[28:31], v[128:131], v[196:199], 0
	v_mfma_f32_16x16x32_bf16 v[28:31], v[132:135], v[202:205], v[28:31]
	v_mfma_f32_16x16x32_bf16 v[12:15], v[128:131], v[206:209], 0
	v_mfma_f32_16x16x32_bf16 v[12:15], v[132:135], v[220:223], v[12:15]
	v_mfma_f32_16x16x32_bf16 v[56:59], v[136:139], v[160:163], 0
	v_mfma_f32_16x16x32_bf16 v[56:59], v[140:143], v[164:167], v[56:59]
	v_mfma_f32_16x16x32_bf16 v[40:43], v[136:139], v[188:191], 0
	v_mfma_f32_16x16x32_bf16 v[40:43], v[140:143], v[192:195], v[40:43]
	v_mfma_f32_16x16x32_bf16 v[24:27], v[136:139], v[196:199], 0
	v_mfma_f32_16x16x32_bf16 v[24:27], v[140:143], v[202:205], v[24:27]
	v_mfma_f32_16x16x32_bf16 v[8:11], v[136:139], v[206:209], 0
	v_mfma_f32_16x16x32_bf16 v[8:11], v[140:143], v[220:223], v[8:11]
	s_setprio 0
	s_setprio 1
	v_mfma_f32_16x16x32_bf16 v[52:55], v[144:147], v[160:163], 0
	v_mfma_f32_16x16x32_bf16 v[52:55], v[148:151], v[164:167], v[52:55]
	v_mfma_f32_16x16x32_bf16 v[36:39], v[144:147], v[188:191], 0
	v_mfma_f32_16x16x32_bf16 v[36:39], v[148:151], v[192:195], v[36:39]
	v_mfma_f32_16x16x32_bf16 v[20:23], v[144:147], v[196:199], 0
	v_mfma_f32_16x16x32_bf16 v[20:23], v[148:151], v[202:205], v[20:23]
	v_mfma_f32_16x16x32_bf16 v[4:7], v[144:147], v[206:209], 0
	v_mfma_f32_16x16x32_bf16 v[4:7], v[148:151], v[220:223], v[4:7]
	v_mfma_f32_16x16x32_bf16 v[48:51], v[152:155], v[160:163], 0
	v_mfma_f32_16x16x32_bf16 v[48:51], v[156:159], v[164:167], v[48:51]
	v_mfma_f32_16x16x32_bf16 v[32:35], v[152:155], v[188:191], 0
	v_mfma_f32_16x16x32_bf16 v[32:35], v[156:159], v[192:195], v[32:35]
	v_mfma_f32_16x16x32_bf16 v[16:19], v[152:155], v[196:199], 0
	v_mfma_f32_16x16x32_bf16 v[16:19], v[156:159], v[202:205], v[16:19]
	v_mfma_f32_16x16x32_bf16 v[0:3], v[152:155], v[206:209], 0
	v_mfma_f32_16x16x32_bf16 v[0:3], v[156:159], v[220:223], v[0:3]
	s_barrier
; #define PG8_STAGE(bufoff, gbase, voff) do { _Pragma("unroll") for (int _i = 0; _i < 2; ++_i) \
;         __builtin_amdgcn_global_load_lds((const unsigned*)((const char*)(gbase) + (voff)[_i]), (PG8_LAS unsigned*)(lds + (bufoff) + ldsw + _i * 8192), 16, 0, 0); } while (0)
; #define PG8_LDA(dst, b, h) do { _Pragma("unroll") for (int m = 0; m < 4; ++m) _Pragma("unroll") for (int k = 0; k < 2; ++k) dst[m][k] = *(const PG8_LAS bf16x8*)(lds + PG8_SA(b, h) + aoff + m * 2048 + k * 1024); } while (0)
; #define PG8_LDB(dst, b, h) do { _Pragma("unroll") for (int n = 0; n < 2; ++n) _Pragma("unroll") for (int k = 0; k < 2; ++k) dst[n][k] = *(const PG8_LAS bf16x8*)(lds + PG8_SB(b, h) + boff + n * 2048 + k * 1024); } while (0)
; #define PG8_MMA(ai, bj, At, Bt) do { __builtin_amdgcn_s_setprio(1); _Pragma("unroll") for (int m = 0; m < 4; ++m) _Pragma("unroll") for (int n = 0; n < 2; ++n) _Pragma("unroll") for (int k = 0; k < 2; ++k) \
;         acc[ai][bj][m][n] = __builtin_amdgcn_mfma_f32_16x16x32_bf16(Bt[n][k], At[m][k], acc[ai][bj][m][n], 0, 0, 0); __builtin_amdgcn_s_setprio(0); } while (0)
; #define PG8_WAIT_V(n) asm volatile("s_waitcnt vmcnt(" #n ")" ::: "memory")
; #define PG8_WAIT_L(n) asm volatile("s_waitcnt lgkmcnt(" #n ")" ::: "memory")
; #define PG8_BAR __builtin_amdgcn_s_barrier()
; #define PG8_SCHED __builtin_amdgcn_sched_barrier(0)
; template <class Epi, class Sched, bool ALIGN_EPI = false, bool SP2 = false, bool DUAL = false>
; __device__ __forceinline__ void gemm_phase(PG8_LAS unsigned char* lds, const Gemm g, const Sched& S, const Epi& E) {
;     ...
;             PG8_LDB(B0, 1, 0); PG8_LDB(B1, 1, 1); PG8_SCHED; PG8_LDA(At, 1, 0); PG8_STAGE(PG8_SA(0, 1), a2 + hstep, voffA);
;             PG8_WAIT_V(8); PG8_WAIT_L(0); PG8_BAR; PG8_MMA(0, 0, At, B0); PG8_MMA(0, 1, At, B1); PG8_BAR; PG8_SCHED;
;             PG8_LDA(At, 1, 1); PG8_STAGE(PG8_SB(1, 0), b3, voffB); PG8_STAGE(PG8_SB(1, 1), b3 + hstep, voffB); PG8_STAGE(PG8_SA(1, 0), a3, voffA);
	s_setprio 0
	s_add_i32 s66, 0, 0x18000
	s_add_i32 s67, 0, 0x1c000
	v_add_u32_e32 v140, s66, v213
	v_add_u32_e32 v156, s67, v213
	ds_read_b128 v[128:131], v140
	ds_read_b128 v[132:135], v140 offset:1024
	ds_read_b128 v[136:139], v140 offset:2048
	ds_read_b128 v[140:143], v140 offset:3072
	ds_read_b128 v[144:147], v156
	ds_read_b128 v[148:151], v156 offset:1024
	ds_read_b128 v[152:155], v156 offset:2048
	ds_read_b128 v[156:159], v156 offset:3072
	s_add_u32 s26, s26, 0x80000
	s_addc_u32 s27, s27, 0
	s_mov_b32 m0, s43
	v_lshl_add_u64 v[238:239], s[26:27], 0, v[168:169]
	ds_read_b128 v[160:163], v217 offset:32768
	ds_read_b128 v[164:167], v217 offset:33792
	ds_read_b128 v[188:191], v217 offset:34816
	ds_read_b128 v[192:195], v217 offset:35840
	ds_read_b128 v[196:199], v217 offset:36864
	ds_read_b128 v[202:205], v217 offset:37888
	ds_read_b128 v[206:209], v217 offset:38912
	ds_read_b128 v[220:223], v217 offset:39936
	global_load_lds_dwordx4 v[238:239], off
	v_lshl_add_u64 v[238:239], s[26:27], 0, v[172:173]
	s_mov_b32 m0, s44
	s_nop 0
	global_load_lds_dwordx4 v[238:239], off
	s_waitcnt vmcnt(8)
	s_waitcnt lgkmcnt(0)
	s_setprio 1
	s_barrier
	v_mfma_f32_16x16x32_bf16 v[124:127], v[128:131], v[160:163], v[124:127]
	v_mfma_f32_16x16x32_bf16 v[124:127], v[132:135], v[164:167], v[124:127]
	v_mfma_f32_16x16x32_bf16 v[108:111], v[128:131], v[188:191], v[108:111]
	v_mfma_f32_16x16x32_bf16 v[108:111], v[132:135], v[192:195], v[108:111]
	v_mfma_f32_16x16x32_bf16 v[92:95], v[128:131], v[196:199], v[92:95]
	v_mfma_f32_16x16x32_bf16 v[92:95], v[132:135], v[202:205], v[92:95]
	v_mfma_f32_16x16x32_bf16 v[76:79], v[128:131], v[206:209], v[76:79]
	v_mfma_f32_16x16x32_bf16 v[76:79], v[132:135], v[220:223], v[76:79]
	v_mfma_f32_16x16x32_bf16 v[120:123], v[136:139], v[160:163], v[120:123]
	v_mfma_f32_16x16x32_bf16 v[120:123], v[140:143], v[164:167], v[120:123]
	v_mfma_f32_16x16x32_bf16 v[104:107], v[136:139], v[188:191], v[104:107]
	v_mfma_f32_16x16x32_bf16 v[104:107], v[140:143], v[192:195], v[104:107]
	v_mfma_f32_16x16x32_bf16 v[88:91], v[136:139], v[196:199], v[88:91]
	v_mfma_f32_16x16x32_bf16 v[88:91], v[140:143], v[202:205], v[88:91]
	v_mfma_f32_16x16x32_bf16 v[72:75], v[136:139], v[206:209], v[72:75]
	v_mfma_f32_16x16x32_bf16 v[72:75], v[140:143], v[220:223], v[72:75]
	s_setprio 0
	s_setprio 1
	v_mfma_f32_16x16x32_bf16 v[116:119], v[144:147], v[160:163], v[116:119]
	v_mfma_f32_16x16x32_bf16 v[116:119], v[148:151], v[164:167], v[116:119]
	v_mfma_f32_16x16x32_bf16 v[100:103], v[144:147], v[188:191], v[100:103]
	v_mfma_f32_16x16x32_bf16 v[100:103], v[148:151], v[192:195], v[100:103]
	v_mfma_f32_16x16x32_bf16 v[84:87], v[144:147], v[196:199], v[84:87]
	v_mfma_f32_16x16x32_bf16 v[84:87], v[148:151], v[202:205], v[84:87]
	v_mfma_f32_16x16x32_bf16 v[68:71], v[144:147], v[206:209], v[68:71]
	v_mfma_f32_16x16x32_bf16 v[68:71], v[148:151], v[220:223], v[68:71]
	v_mfma_f32_16x16x32_bf16 v[112:115], v[152:155], v[160:163], v[112:115]
	v_mfma_f32_16x16x32_bf16 v[112:115], v[156:159], v[164:167], v[112:115]
	v_mfma_f32_16x16x32_bf16 v[96:99], v[152:155], v[188:191], v[96:99]
	v_mfma_f32_16x16x32_bf16 v[96:99], v[156:159], v[192:195], v[96:99]
	v_mfma_f32_16x16x32_bf16 v[80:83], v[152:155], v[196:199], v[80:83]
	v_mfma_f32_16x16x32_bf16 v[80:83], v[156:159], v[202:205], v[80:83]
	v_mfma_f32_16x16x32_bf16 v[64:67], v[152:155], v[206:209], v[64:67]
	v_mfma_f32_16x16x32_bf16 v[64:67], v[156:159], v[220:223], v[64:67]
	s_barrier
	s_setprio 0
	s_add_i32 s26, s66, s34
	v_lshl_add_u64 v[228:229], v[228:229], 0, s[12:13]
	s_mov_b32 m0, s26
	ds_read_b128 v[160:163], v217 offset:49152
	ds_read_b128 v[164:167], v217 offset:50176
	ds_read_b128 v[188:191], v217 offset:51200
	ds_read_b128 v[192:195], v217 offset:52224
	ds_read_b128 v[196:199], v217 offset:53248
	ds_read_b128 v[202:205], v217 offset:54272
	ds_read_b128 v[206:209], v217 offset:55296
	ds_read_b128 v[220:223], v217 offset:56320
	global_load_lds_dwordx4 v[228:229], off
	s_add_i32 m0, s26, 0x2000
	s_add_u32 s14, s14, 0x80080
	v_lshl_add_u64 v[228:229], v[232:233], 0, s[12:13]
	s_addc_u32 s15, s15, 0
	s_add_i32 s26, s67, s34
	global_load_lds_dwordx4 v[228:229], off
	v_lshl_add_u64 v[228:229], s[14:15], 0, v[170:171]
	s_mov_b32 m0, s26
	s_nop 0
	global_load_lds_dwordx4 v[228:229], off
	v_lshl_add_u64 v[228:229], s[14:15], 0, v[174:175]
	s_add_i32 m0, s26, 0x2000
	s_nop 0
	global_load_lds_dwordx4 v[228:229], off
	v_lshl_add_u64 v[228:229], v[234:235], 0, s[12:13]
	s_mov_b32 m0, s47
	s_nop 0
	global_load_lds_dwordx4 v[228:229], off
	v_lshl_add_u64 v[228:229], v[236:237], 0, s[12:13]
	s_mov_b32 m0, s48
	s_nop 0
	global_load_lds_dwordx4 v[228:229], off
	s_waitcnt vmcnt(8)
	s_waitcnt lgkmcnt(0)
	s_setprio 1
	s_barrier
; #define PG8_STAGE(bufoff, gbase, voff) do { _Pragma("unroll") for (int _i = 0; _i < 2; ++_i) \
;         __builtin_amdgcn_global_load_lds((const unsigned*)((const char*)(gbase) + (voff)[_i]), (PG8_LAS unsigned*)(lds + (bufoff) + ldsw + _i * 8192), 16, 0, 0); } while (0)
; #define PG8_LDA(dst, b, h) do { _Pragma("unroll") for (int m = 0; m < 4; ++m) _Pragma("unroll") for (int k = 0; k < 2; ++k) dst[m][k] = *(const PG8_LAS bf16x8*)(lds + PG8_SA(b, h) + aoff + m * 2048 + k * 1024); } while (0)
; #define PG8_LDB(dst, b, h) do { _Pragma("unroll") for (int n = 0; n < 2; ++n) _Pragma("unroll") for (int k = 0; k < 2; ++k) dst[n][k] = *(const PG8_LAS bf16x8*)(lds + PG8_SB(b, h) + boff + n * 2048 + k * 1024); } while (0)
; #define PG8_MMA(ai, bj, At, Bt) do { __builtin_amdgcn_s_setprio(1); _Pragma("unroll") for (int m = 0; m < 4; ++m) _Pragma("unroll") for (int n = 0; n < 2; ++n) _Pragma("unroll") for (int k = 0; k < 2; ++k) \
;         acc[ai][bj][m][n] = __builtin_amdgcn_mfma_f32_16x16x32_bf16(Bt[n][k], At[m][k], acc[ai][bj][m][n], 0, 0, 0); __builtin_amdgcn_s_setprio(0); } while (0)
; #define PG8_BAR __builtin_amdgcn_s_barrier()
; template <class Epi, class Sched, bool ALIGN_EPI = false, bool SP2 = false, bool DUAL = false>
; __device__ __forceinline__ void gemm_phase(PG8_LAS unsigned char* lds, const Gemm g, const Sched& S, const Epi& E) {
;     ...
;             PG8_LDB(B0, 0, 0); PG8_LDB(B1, 0, 1); PG8_SCHED; PG8_LDA(At, 0, 0); PG8_STAGE(PG8_SA(1, 1), a1 + hstep, voffA);
;             PG8_WAIT_V(8); PG8_WAIT_L(0); PG8_BAR; PG8_MMA(0, 0, At, B0); PG8_MMA(0, 1, At, B1); PG8_BAR; PG8_SCHED;
;             PG8_LDA(At, 0, 1); PG8_STAGE(PG8_SB(0, 0), b2, voffB); PG8_STAGE(PG8_SB(0, 1), b2 + hstep, voffB); PG8_STAGE(PG8_SA(0, 0), a2, voffA);
;             PG8_WAIT_V(8); PG8_WAIT_L(0); PG8_BAR; PG8_MMA(1, 0, At, B0); PG8_MMA(1, 1, At, B1); PG8_BAR; PG8_SCHED;
;             PG8_LDB(B0, 1, 0); PG8_LDB(B1, 1, 1); PG8_SCHED; PG8_LDA(At, 1, 0); PG8_STAGE(PG8_SA(0, 1), a2 + hstep, voffA);
;             PG8_WAIT_V(8); PG8_WAIT_L(0); PG8_BAR; PG8_MMA(0, 0, At, B0); PG8_MMA(0, 1, At, B1); PG8_BAR; PG8_SCHED;
;             PG8_LDA(At, 1, 1); PG8_STAGE(PG8_SB(1, 0), b3, voffB); PG8_STAGE(PG8_SB(1, 1), b3 + hstep, voffB); PG8_STAGE(PG8_SA(1, 0), a3, voffA);
;             PG8_WAIT_V(8); PG8_WAIT_L(0); PG8_BAR; PG8_MMA(1, 0, At, B0); PG8_MMA(1, 1, At, B1); PG8_BAR; PG8_SCHED;
	v_mfma_f32_16x16x32_bf16 v[60:63], v[128:131], v[160:163], v[60:63]
	v_mfma_f32_16x16x32_bf16 v[60:63], v[132:135], v[164:167], v[60:63]
	v_mfma_f32_16x16x32_bf16 v[44:47], v[128:131], v[188:191], v[44:47]
	v_mfma_f32_16x16x32_bf16 v[44:47], v[132:135], v[192:195], v[44:47]
	v_mfma_f32_16x16x32_bf16 v[28:31], v[128:131], v[196:199], v[28:31]
	v_mfma_f32_16x16x32_bf16 v[28:31], v[132:135], v[202:205], v[28:31]
	v_mfma_f32_16x16x32_bf16 v[12:15], v[128:131], v[206:209], v[12:15]
	v_mfma_f32_16x16x32_bf16 v[12:15], v[132:135], v[220:223], v[12:15]
	v_mfma_f32_16x16x32_bf16 v[56:59], v[136:139], v[160:163], v[56:59]
	v_mfma_f32_16x16x32_bf16 v[56:59], v[140:143], v[164:167], v[56:59]
	v_mfma_f32_16x16x32_bf16 v[40:43], v[136:139], v[188:191], v[40:43]
	v_mfma_f32_16x16x32_bf16 v[40:43], v[140:143], v[192:195], v[40:43]
	v_mfma_f32_16x16x32_bf16 v[24:27], v[136:139], v[196:199], v[24:27]
	v_mfma_f32_16x16x32_bf16 v[24:27], v[140:143], v[202:205], v[24:27]
	v_mfma_f32_16x16x32_bf16 v[8:11], v[136:139], v[206:209], v[8:11]
	v_mfma_f32_16x16x32_bf16 v[8:11], v[140:143], v[220:223], v[8:11]
	s_setprio 0
	s_setprio 1
	v_mfma_f32_16x16x32_bf16 v[52:55], v[144:147], v[160:163], v[52:55]
	v_mfma_f32_16x16x32_bf16 v[52:55], v[148:151], v[164:167], v[52:55]
	v_mfma_f32_16x16x32_bf16 v[36:39], v[144:147], v[188:191], v[36:39]
	v_mfma_f32_16x16x32_bf16 v[36:39], v[148:151], v[192:195], v[36:39]
	v_mfma_f32_16x16x32_bf16 v[20:23], v[144:147], v[196:199], v[20:23]
	v_mfma_f32_16x16x32_bf16 v[20:23], v[148:151], v[202:205], v[20:23]
	v_mfma_f32_16x16x32_bf16 v[4:7], v[144:147], v[206:209], v[4:7]
	v_mfma_f32_16x16x32_bf16 v[4:7], v[148:151], v[220:223], v[4:7]
	v_mfma_f32_16x16x32_bf16 v[48:51], v[152:155], v[160:163], v[48:51]
	v_mfma_f32_16x16x32_bf16 v[48:51], v[156:159], v[164:167], v[48:51]
	v_mfma_f32_16x16x32_bf16 v[32:35], v[152:155], v[188:191], v[32:35]
	v_mfma_f32_16x16x32_bf16 v[32:35], v[156:159], v[192:195], v[32:35]
	v_mfma_f32_16x16x32_bf16 v[16:19], v[152:155], v[196:199], v[16:19]
	v_mfma_f32_16x16x32_bf16 v[16:19], v[156:159], v[202:205], v[16:19]
	v_mfma_f32_16x16x32_bf16 v[0:3], v[152:155], v[206:209], v[0:3]
	v_mfma_f32_16x16x32_bf16 v[0:3], v[156:159], v[220:223], v[0:3]
	s_barrier
	s_setprio 0
	s_add_i32 s65, s65, 2
	s_add_u32 s40, s40, 0x100
	s_addc_u32 s41, s41, 0
	s_add_u32 s63, s63, 0x100
	s_addc_u32 s64, s64, 0
.LBB0_992:
	ds_read_b128 v[128:131], v215
	ds_read_b128 v[132:135], v215 offset:1024
	ds_read_b128 v[136:139], v215 offset:2048
	ds_read_b128 v[140:143], v215 offset:3072
	ds_read_b128 v[144:147], v216
	ds_read_b128 v[148:151], v216 offset:1024
	ds_read_b128 v[152:155], v216 offset:2048
	ds_read_b128 v[156:159], v216 offset:3072
	s_add_u32 s14, s40, 0xfff80080
	s_addc_u32 s15, s41, -1
	s_cmp_eq_u32 s65, 28
	s_cselect_b32 s27, s25, s15
	s_cselect_b32 s26, s28, s14
	s_cselect_b32 s15, s23, s64
	s_cselect_b32 s14, s29, s63
	v_lshl_add_u64 v[228:229], s[40:41], 0, v[180:181]
	s_add_i32 m0, s39, 0xc000
	ds_read_b128 v[160:163], v217
	ds_read_b128 v[164:167], v217 offset:1024
	ds_read_b128 v[188:191], v217 offset:2048
	ds_read_b128 v[192:195], v217 offset:3072
	ds_read_b128 v[196:199], v217 offset:4096
	ds_read_b128 v[202:205], v217 offset:5120
	ds_read_b128 v[206:209], v217 offset:6144
	ds_read_b128 v[220:223], v217 offset:7168
	global_load_lds_dwordx4 v[228:229], off
	v_lshl_add_u64 v[228:229], s[40:41], 0, v[182:183]
	s_add_i32 m0, s39, 0xe000
	s_nop 0
	global_load_lds_dwordx4 v[228:229], off
	s_waitcnt vmcnt(8)
	s_waitcnt lgkmcnt(0)
	s_setprio 1
	s_barrier
	v_mfma_f32_16x16x32_bf16 v[124:127], v[128:131], v[160:163], v[124:127]
	v_mfma_f32_16x16x32_bf16 v[124:127], v[132:135], v[164:167], v[124:127]
	v_mfma_f32_16x16x32_bf16 v[108:111], v[128:131], v[188:191], v[108:111]
	v_mfma_f32_16x16x32_bf16 v[108:111], v[132:135], v[192:195], v[108:111]
	v_mfma_f32_16x16x32_bf16 v[92:95], v[128:131], v[196:199], v[92:95]
	v_mfma_f32_16x16x32_bf16 v[92:95], v[132:135], v[202:205], v[92:95]
	v_mfma_f32_16x16x32_bf16 v[76:79], v[128:131], v[206:209], v[76:79]
	v_mfma_f32_16x16x32_bf16 v[76:79], v[132:135], v[220:223], v[76:79]
	v_mfma_f32_16x16x32_bf16 v[120:123], v[136:139], v[160:163], v[120:123]
	v_mfma_f32_16x16x32_bf16 v[120:123], v[140:143], v[164:167], v[120:123]
	v_mfma_f32_16x16x32_bf16 v[104:107], v[136:139], v[188:191], v[104:107]
	v_mfma_f32_16x16x32_bf16 v[104:107], v[140:143], v[192:195], v[104:107]
	v_mfma_f32_16x16x32_bf16 v[88:91], v[136:139], v[196:199], v[88:91]
	v_mfma_f32_16x16x32_bf16 v[88:91], v[140:143], v[202:205], v[88:91]
	v_mfma_f32_16x16x32_bf16 v[72:75], v[136:139], v[206:209], v[72:75]
	v_mfma_f32_16x16x32_bf16 v[72:75], v[140:143], v[220:223], v[72:75]
	s_setprio 0
	s_setprio 1
	v_mfma_f32_16x16x32_bf16 v[116:119], v[144:147], v[160:163], v[116:119]
	v_mfma_f32_16x16x32_bf16 v[116:119], v[148:151], v[164:167], v[116:119]
	v_mfma_f32_16x16x32_bf16 v[100:103], v[144:147], v[188:191], v[100:103]
	v_mfma_f32_16x16x32_bf16 v[100:103], v[148:151], v[192:195], v[100:103]
	v_mfma_f32_16x16x32_bf16 v[84:87], v[144:147], v[196:199], v[84:87]
	v_mfma_f32_16x16x32_bf16 v[84:87], v[148:151], v[202:205], v[84:87]
	v_mfma_f32_16x16x32_bf16 v[68:71], v[144:147], v[206:209], v[68:71]
	v_mfma_f32_16x16x32_bf16 v[68:71], v[148:151], v[220:223], v[68:71]
	v_mfma_f32_16x16x32_bf16 v[112:115], v[152:155], v[160:163], v[112:115]
	v_mfma_f32_16x16x32_bf16 v[112:115], v[156:159], v[164:167], v[112:115]
	v_mfma_f32_16x16x32_bf16 v[96:99], v[152:155], v[188:191], v[96:99]
	v_mfma_f32_16x16x32_bf16 v[96:99], v[156:159], v[192:195], v[96:99]
	v_mfma_f32_16x16x32_bf16 v[80:83], v[152:155], v[196:199], v[80:83]
	v_mfma_f32_16x16x32_bf16 v[80:83], v[156:159], v[202:205], v[80:83]
	v_mfma_f32_16x16x32_bf16 v[64:67], v[152:155], v[206:209], v[64:67]
	v_mfma_f32_16x16x32_bf16 v[64:67], v[156:159], v[220:223], v[64:67]
	s_barrier
; #define PG8_STAGE(bufoff, gbase, voff) do { _Pragma("unroll") for (int _i = 0; _i < 2; ++_i) \
;         __builtin_amdgcn_global_load_lds((const unsigned*)((const char*)(gbase) + (voff)[_i]), (PG8_LAS unsigned*)(lds + (bufoff) + ldsw + _i * 8192), 16, 0, 0); } while (0)
; #define PG8_LDA(dst, b, h) do { _Pragma("unroll") for (int m = 0; m < 4; ++m) _Pragma("unroll") for (int k = 0; k < 2; ++k) dst[m][k] = *(const PG8_LAS bf16x8*)(lds + PG8_SA(b, h) + aoff + m * 2048 + k * 1024); } while (0)
; #define PG8_LDB(dst, b, h) do { _Pragma("unroll") for (int n = 0; n < 2; ++n) _Pragma("unroll") for (int k = 0; k < 2; ++k) dst[n][k] = *(const PG8_LAS bf16x8*)(lds + PG8_SB(b, h) + boff + n * 2048 + k * 1024); } while (0)
; #define PG8_MMA(ai, bj, At, Bt) do { __builtin_amdgcn_s_setprio(1); _Pragma("unroll") for (int m = 0; m < 4; ++m) _Pragma("unroll") for (int n = 0; n < 2; ++n) _Pragma("unroll") for (int k = 0; k < 2; ++k) \
;         acc[ai][bj][m][n] = __builtin_amdgcn_mfma_f32_16x16x32_bf16(Bt[n][k], At[m][k], acc[ai][bj][m][n], 0, 0, 0); __builtin_amdgcn_s_setprio(0); } while (0)
; #define PG8_WAIT_V(n) asm volatile("s_waitcnt vmcnt(" #n ")" ::: "memory")
; #define PG8_WAIT_L(n) asm volatile("s_waitcnt lgkmcnt(" #n ")" ::: "memory")
; #define PG8_BAR __builtin_amdgcn_s_barrier()
; #define PG8_SCHED __builtin_amdgcn_sched_barrier(0)
; template <class Epi, class Sched, bool ALIGN_EPI = false, bool SP2 = false, bool DUAL = false>
; __device__ __forceinline__ void gemm_phase(PG8_LAS unsigned char* lds, const Gemm g, const Sched& S, const Epi& E) {
;     ...
;             PG8_LDA(At, 0, 1); PG8_STAGE(PG8_SB(0, 0), b2, voffB); PG8_STAGE(PG8_SB(0, 1), b2 + hstep, voffB); PG8_STAGE(PG8_SA(0, 0), a2, voffA);
;             PG8_WAIT_V(8); PG8_WAIT_L(0); PG8_BAR; PG8_MMA(1, 0, At, B0); PG8_MMA(1, 1, At, B1); PG8_BAR; PG8_SCHED;
;             PG8_LDB(B0, 1, 0); PG8_LDB(B1, 1, 1); PG8_SCHED; PG8_LDA(At, 1, 0); PG8_STAGE(PG8_SA(0, 1), a2 + hstep, voffA);
;             PG8_WAIT_V(8); PG8_WAIT_L(0); PG8_BAR; PG8_MMA(0, 0, At, B0); PG8_MMA(0, 1, At, B1); PG8_BAR; PG8_SCHED;
	s_setprio 0
	s_add_i32 s66, s50, s34
	v_lshl_add_u64 v[228:229], s[14:15], 0, v[170:171]
	s_mov_b32 m0, s66
	ds_read_b128 v[160:163], v217 offset:16384
	ds_read_b128 v[164:167], v217 offset:17408
	ds_read_b128 v[188:191], v217 offset:18432
	ds_read_b128 v[192:195], v217 offset:19456
	ds_read_b128 v[196:199], v217 offset:20480
	ds_read_b128 v[202:205], v217 offset:21504
	ds_read_b128 v[206:209], v217 offset:22528
	ds_read_b128 v[220:223], v217 offset:23552
	global_load_lds_dwordx4 v[228:229], off
	s_add_i32 m0, s66, 0x2000
	s_add_u32 s66, s14, 0x80000
	v_lshl_add_u64 v[232:233], s[14:15], 0, v[174:175]
	s_addc_u32 s67, s15, 0
	s_add_i32 s68, s51, s34
	global_load_lds_dwordx4 v[232:233], off
	v_lshl_add_u64 v[234:235], s[66:67], 0, v[170:171]
	s_mov_b32 m0, s68
	v_lshl_add_u64 v[236:237], s[26:27], 0, v[172:173]
	global_load_lds_dwordx4 v[234:235], off
	v_lshl_add_u64 v[234:235], s[66:67], 0, v[174:175]
	s_add_i32 m0, s68, 0x2000
	s_nop 0
	global_load_lds_dwordx4 v[234:235], off
	v_lshl_add_u64 v[234:235], s[26:27], 0, v[168:169]
	s_mov_b32 m0, s39
	s_nop 0
	global_load_lds_dwordx4 v[234:235], off
	s_mov_b32 m0, s42
	s_nop 0
	global_load_lds_dwordx4 v[236:237], off
	s_waitcnt vmcnt(8)
	s_waitcnt lgkmcnt(0)
	s_setprio 1
	s_barrier
	v_mfma_f32_16x16x32_bf16 v[60:63], v[128:131], v[160:163], v[60:63]
	v_mfma_f32_16x16x32_bf16 v[60:63], v[132:135], v[164:167], v[60:63]
	v_mfma_f32_16x16x32_bf16 v[44:47], v[128:131], v[188:191], v[44:47]
	v_mfma_f32_16x16x32_bf16 v[44:47], v[132:135], v[192:195], v[44:47]
	v_mfma_f32_16x16x32_bf16 v[28:31], v[128:131], v[196:199], v[28:31]
	v_mfma_f32_16x16x32_bf16 v[28:31], v[132:135], v[202:205], v[28:31]
	v_mfma_f32_16x16x32_bf16 v[12:15], v[128:131], v[206:209], v[12:15]
	v_mfma_f32_16x16x32_bf16 v[12:15], v[132:135], v[220:223], v[12:15]
	v_mfma_f32_16x16x32_bf16 v[56:59], v[136:139], v[160:163], v[56:59]
	v_mfma_f32_16x16x32_bf16 v[56:59], v[140:143], v[164:167], v[56:59]
	v_mfma_f32_16x16x32_bf16 v[40:43], v[136:139], v[188:191], v[40:43]
	v_mfma_f32_16x16x32_bf16 v[40:43], v[140:143], v[192:195], v[40:43]
	v_mfma_f32_16x16x32_bf16 v[24:27], v[136:139], v[196:199], v[24:27]
	v_mfma_f32_16x16x32_bf16 v[24:27], v[140:143], v[202:205], v[24:27]
	v_mfma_f32_16x16x32_bf16 v[8:11], v[136:139], v[206:209], v[8:11]
	v_mfma_f32_16x16x32_bf16 v[8:11], v[140:143], v[220:223], v[8:11]
	s_setprio 0
	s_setprio 1
	v_mfma_f32_16x16x32_bf16 v[52:55], v[144:147], v[160:163], v[52:55]
	v_mfma_f32_16x16x32_bf16 v[52:55], v[148:151], v[164:167], v[52:55]
	v_mfma_f32_16x16x32_bf16 v[36:39], v[144:147], v[188:191], v[36:39]
	v_mfma_f32_16x16x32_bf16 v[36:39], v[148:151], v[192:195], v[36:39]
	v_mfma_f32_16x16x32_bf16 v[20:23], v[144:147], v[196:199], v[20:23]
	v_mfma_f32_16x16x32_bf16 v[20:23], v[148:151], v[202:205], v[20:23]
	v_mfma_f32_16x16x32_bf16 v[4:7], v[144:147], v[206:209], v[4:7]
	v_mfma_f32_16x16x32_bf16 v[4:7], v[148:151], v[220:223], v[4:7]
	v_mfma_f32_16x16x32_bf16 v[48:51], v[152:155], v[160:163], v[48:51]
	v_mfma_f32_16x16x32_bf16 v[48:51], v[156:159], v[164:167], v[48:51]
	v_mfma_f32_16x16x32_bf16 v[32:35], v[152:155], v[188:191], v[32:35]
	v_mfma_f32_16x16x32_bf16 v[32:35], v[156:159], v[192:195], v[32:35]
	v_mfma_f32_16x16x32_bf16 v[16:19], v[152:155], v[196:199], v[16:19]
	v_mfma_f32_16x16x32_bf16 v[16:19], v[156:159], v[202:205], v[16:19]
	v_mfma_f32_16x16x32_bf16 v[0:3], v[152:155], v[206:209], v[0:3]
	v_mfma_f32_16x16x32_bf16 v[0:3], v[156:159], v[220:223], v[0:3]
	s_barrier
	s_setprio 0
	s_add_i32 s66, 0, 0x18000
	s_add_i32 s67, 0, 0x1c000
	v_add_u32_e32 v140, s66, v213
	v_add_u32_e32 v156, s67, v213
	ds_read_b128 v[128:131], v140
	ds_read_b128 v[132:135], v140 offset:1024
	ds_read_b128 v[136:139], v140 offset:2048
	ds_read_b128 v[140:143], v140 offset:3072
	ds_read_b128 v[144:147], v156
	ds_read_b128 v[148:151], v156 offset:1024
	ds_read_b128 v[152:155], v156 offset:2048
	ds_read_b128 v[156:159], v156 offset:3072
	s_add_u32 s26, s26, 0x80000
	s_addc_u32 s27, s27, 0
	s_mov_b32 m0, s43
	v_lshl_add_u64 v[238:239], s[26:27], 0, v[168:169]
	ds_read_b128 v[160:163], v217 offset:32768
	ds_read_b128 v[164:167], v217 offset:33792
	ds_read_b128 v[188:191], v217 offset:34816
	ds_read_b128 v[192:195], v217 offset:35840
	ds_read_b128 v[196:199], v217 offset:36864
	ds_read_b128 v[202:205], v217 offset:37888
	ds_read_b128 v[206:209], v217 offset:38912
	ds_read_b128 v[220:223], v217 offset:39936
	global_load_lds_dwordx4 v[238:239], off
	v_lshl_add_u64 v[238:239], s[26:27], 0, v[172:173]
	s_mov_b32 m0, s44
	s_nop 0
	global_load_lds_dwordx4 v[238:239], off
	s_waitcnt vmcnt(8)
	s_waitcnt lgkmcnt(0)
	s_setprio 1
	s_barrier
; #define PG8_STAGE(bufoff, gbase, voff) do { _Pragma("unroll") for (int _i = 0; _i < 2; ++_i) \
;         __builtin_amdgcn_global_load_lds((const unsigned*)((const char*)(gbase) + (voff)[_i]), (PG8_LAS unsigned*)(lds + (bufoff) + ldsw + _i * 8192), 16, 0, 0); } while (0)
; #define PG8_LDA(dst, b, h) do { _Pragma("unroll") for (int m = 0; m < 4; ++m) _Pragma("unroll") for (int k = 0; k < 2; ++k) dst[m][k] = *(const PG8_LAS bf16x8*)(lds + PG8_SA(b, h) + aoff + m * 2048 + k * 1024); } while (0)
; #define PG8_MMA(ai, bj, At, Bt) do { __builtin_amdgcn_s_setprio(1); _Pragma("unroll") for (int m = 0; m < 4; ++m) _Pragma("unroll") for (int n = 0; n < 2; ++n) _Pragma("unroll") for (int k = 0; k < 2; ++k) \
;         acc[ai][bj][m][n] = __builtin_amdgcn_mfma_f32_16x16x32_bf16(Bt[n][k], At[m][k], acc[ai][bj][m][n], 0, 0, 0); __builtin_amdgcn_s_setprio(0); } while (0)
; #define PG8_WAIT_V(n) asm volatile("s_waitcnt vmcnt(" #n ")" ::: "memory")
; #define PG8_WAIT_L(n) asm volatile("s_waitcnt lgkmcnt(" #n ")" ::: "memory")
; #define PG8_BAR __builtin_amdgcn_s_barrier()
; #define PG8_SCHED __builtin_amdgcn_sched_barrier(0)
; template <class Epi, class Sched, bool ALIGN_EPI = false, bool SP2 = false, bool DUAL = false>
; __device__ __forceinline__ void gemm_phase(PG8_LAS unsigned char* lds, const Gemm g, const Sched& S, const Epi& E) {
;     ...
;             PG8_WAIT_V(8); PG8_WAIT_L(0); PG8_BAR; PG8_MMA(0, 0, At, B0); PG8_MMA(0, 1, At, B1); PG8_BAR; PG8_SCHED;
;             PG8_LDA(At, 1, 1); PG8_STAGE(PG8_SB(1, 0), b3, voffB); PG8_STAGE(PG8_SB(1, 1), b3 + hstep, voffB); PG8_STAGE(PG8_SA(1, 0), a3, voffA);
;             PG8_WAIT_V(8); PG8_WAIT_L(0); PG8_BAR; PG8_MMA(1, 0, At, B0); PG8_MMA(1, 1, At, B1); PG8_BAR; PG8_SCHED;
	v_mfma_f32_16x16x32_bf16 v[124:127], v[128:131], v[160:163], v[124:127]
	v_mfma_f32_16x16x32_bf16 v[124:127], v[132:135], v[164:167], v[124:127]
	v_mfma_f32_16x16x32_bf16 v[108:111], v[128:131], v[188:191], v[108:111]
	v_mfma_f32_16x16x32_bf16 v[108:111], v[132:135], v[192:195], v[108:111]
	v_mfma_f32_16x16x32_bf16 v[92:95], v[128:131], v[196:199], v[92:95]
	v_mfma_f32_16x16x32_bf16 v[92:95], v[132:135], v[202:205], v[92:95]
	v_mfma_f32_16x16x32_bf16 v[76:79], v[128:131], v[206:209], v[76:79]
	v_mfma_f32_16x16x32_bf16 v[76:79], v[132:135], v[220:223], v[76:79]
	v_mfma_f32_16x16x32_bf16 v[120:123], v[136:139], v[160:163], v[120:123]
	v_mfma_f32_16x16x32_bf16 v[120:123], v[140:143], v[164:167], v[120:123]
	v_mfma_f32_16x16x32_bf16 v[104:107], v[136:139], v[188:191], v[104:107]
	v_mfma_f32_16x16x32_bf16 v[104:107], v[140:143], v[192:195], v[104:107]
	v_mfma_f32_16x16x32_bf16 v[88:91], v[136:139], v[196:199], v[88:91]
	v_mfma_f32_16x16x32_bf16 v[88:91], v[140:143], v[202:205], v[88:91]
	v_mfma_f32_16x16x32_bf16 v[72:75], v[136:139], v[206:209], v[72:75]
	v_mfma_f32_16x16x32_bf16 v[72:75], v[140:143], v[220:223], v[72:75]
	s_setprio 0
	s_setprio 1
	v_mfma_f32_16x16x32_bf16 v[116:119], v[144:147], v[160:163], v[116:119]
	v_mfma_f32_16x16x32_bf16 v[116:119], v[148:151], v[164:167], v[116:119]
	v_mfma_f32_16x16x32_bf16 v[100:103], v[144:147], v[188:191], v[100:103]
	v_mfma_f32_16x16x32_bf16 v[100:103], v[148:151], v[192:195], v[100:103]
	v_mfma_f32_16x16x32_bf16 v[84:87], v[144:147], v[196:199], v[84:87]
	v_mfma_f32_16x16x32_bf16 v[84:87], v[148:151], v[202:205], v[84:87]
	v_mfma_f32_16x16x32_bf16 v[68:71], v[144:147], v[206:209], v[68:71]
	v_mfma_f32_16x16x32_bf16 v[68:71], v[148:151], v[220:223], v[68:71]
	v_mfma_f32_16x16x32_bf16 v[112:115], v[152:155], v[160:163], v[112:115]
	v_mfma_f32_16x16x32_bf16 v[112:115], v[156:159], v[164:167], v[112:115]
	v_mfma_f32_16x16x32_bf16 v[96:99], v[152:155], v[188:191], v[96:99]
	v_mfma_f32_16x16x32_bf16 v[96:99], v[156:159], v[192:195], v[96:99]
	v_mfma_f32_16x16x32_bf16 v[80:83], v[152:155], v[196:199], v[80:83]
	v_mfma_f32_16x16x32_bf16 v[80:83], v[156:159], v[202:205], v[80:83]
	v_mfma_f32_16x16x32_bf16 v[64:67], v[152:155], v[206:209], v[64:67]
	v_mfma_f32_16x16x32_bf16 v[64:67], v[156:159], v[220:223], v[64:67]
	s_barrier
	s_setprio 0
	s_add_i32 s26, s66, s34
	v_lshl_add_u64 v[228:229], v[228:229], 0, s[12:13]
	s_mov_b32 m0, s26
	ds_read_b128 v[160:163], v217 offset:49152
	ds_read_b128 v[164:167], v217 offset:50176
	ds_read_b128 v[188:191], v217 offset:51200
	ds_read_b128 v[192:195], v217 offset:52224
	ds_read_b128 v[196:199], v217 offset:53248
	ds_read_b128 v[202:205], v217 offset:54272
	ds_read_b128 v[206:209], v217 offset:55296
	ds_read_b128 v[220:223], v217 offset:56320
	global_load_lds_dwordx4 v[228:229], off
	s_add_i32 m0, s26, 0x2000
	s_add_u32 s14, s14, 0x80080
	v_lshl_add_u64 v[228:229], v[232:233], 0, s[12:13]
	s_addc_u32 s15, s15, 0
	s_add_i32 s26, s67, s34
	global_load_lds_dwordx4 v[228:229], off
	v_lshl_add_u64 v[228:229], s[14:15], 0, v[170:171]
	s_mov_b32 m0, s26
	s_nop 0
	global_load_lds_dwordx4 v[228:229], off
	v_lshl_add_u64 v[228:229], s[14:15], 0, v[174:175]
	s_add_i32 m0, s26, 0x2000
	s_nop 0
	global_load_lds_dwordx4 v[228:229], off
	v_lshl_add_u64 v[228:229], v[234:235], 0, s[12:13]
	s_mov_b32 m0, s47
	s_nop 0
	global_load_lds_dwordx4 v[228:229], off
	v_lshl_add_u64 v[228:229], v[236:237], 0, s[12:13]
	s_mov_b32 m0, s48
	s_nop 0
	global_load_lds_dwordx4 v[228:229], off
	s_waitcnt vmcnt(8)
	s_waitcnt lgkmcnt(0)
	s_setprio 1
	s_barrier
; #define PG8_MMA(ai, bj, At, Bt) do { __builtin_amdgcn_s_setprio(1); _Pragma("unroll") for (int m = 0; m < 4; ++m) _Pragma("unroll") for (int n = 0; n < 2; ++n) _Pragma("unroll") for (int k = 0; k < 2; ++k) \
;         acc[ai][bj][m][n] = __builtin_amdgcn_mfma_f32_16x16x32_bf16(Bt[n][k], At[m][k], acc[ai][bj][m][n], 0, 0, 0); __builtin_amdgcn_s_setprio(0); } while (0)
; #define PG8_WAIT_V(n) asm volatile("s_waitcnt vmcnt(" #n ")" ::: "memory")
; #define PG8_WAIT_L(n) asm volatile("s_waitcnt lgkmcnt(" #n ")" ::: "memory")
; #define PG8_BAR __builtin_amdgcn_s_barrier()
; #define PG8_SCHED __builtin_amdgcn_sched_barrier(0)
; template <class Epi, class Sched, bool ALIGN_EPI = false, bool SP2 = false, bool DUAL = false>
; __device__ __forceinline__ void gemm_phase(PG8_LAS unsigned char* lds, const Gemm g, const Sched& S, const Epi& E) {
;     ...
;             PG8_WAIT_V(8); PG8_WAIT_L(0); PG8_BAR; PG8_MMA(1, 0, At, B0); PG8_MMA(1, 1, At, B1); PG8_BAR; PG8_SCHED;
;     __device__ __forceinline__ void operator()(const f32x4 (&acc)[2][2][4][2], const Unit& u, int wr, int wc, int fr, int fq) const {
;         const int rowb = u.pm * BM + wr * 64 + fr, col = u.pn * HALF + wc * 32 + fq * 8;
;         f32x4 p[2][4][2];
; #pragma unroll
;         for (int ai = 0; ai < 2; ++ai)
; #pragma unroll
;             for (int m = 0; m < 4; ++m) { const float* sp = ss2 + (size_t)(rowb + ai * HALF + m * 16) * 32 + fq * 8; p[ai][m][0] = *(const f32x4*)sp; p[ai][m][1] = *(const f32x4*)(sp + 4); }
	v_mfma_f32_16x16x32_bf16 v[60:63], v[128:131], v[160:163], v[60:63]
	v_mfma_f32_16x16x32_bf16 v[60:63], v[132:135], v[164:167], v[60:63]
	v_mfma_f32_16x16x32_bf16 v[44:47], v[128:131], v[188:191], v[44:47]
	v_mfma_f32_16x16x32_bf16 v[44:47], v[132:135], v[192:195], v[44:47]
	v_mfma_f32_16x16x32_bf16 v[28:31], v[128:131], v[196:199], v[28:31]
	v_mfma_f32_16x16x32_bf16 v[28:31], v[132:135], v[202:205], v[28:31]
	v_mfma_f32_16x16x32_bf16 v[12:15], v[128:131], v[206:209], v[12:15]
	v_mfma_f32_16x16x32_bf16 v[12:15], v[132:135], v[220:223], v[12:15]
	v_mfma_f32_16x16x32_bf16 v[56:59], v[136:139], v[160:163], v[56:59]
	v_mfma_f32_16x16x32_bf16 v[56:59], v[140:143], v[164:167], v[56:59]
	v_mfma_f32_16x16x32_bf16 v[40:43], v[136:139], v[188:191], v[40:43]
	v_mfma_f32_16x16x32_bf16 v[40:43], v[140:143], v[192:195], v[40:43]
	v_mfma_f32_16x16x32_bf16 v[24:27], v[136:139], v[196:199], v[24:27]
	v_mfma_f32_16x16x32_bf16 v[24:27], v[140:143], v[202:205], v[24:27]
	v_mfma_f32_16x16x32_bf16 v[8:11], v[136:139], v[206:209], v[8:11]
	v_mfma_f32_16x16x32_bf16 v[8:11], v[140:143], v[220:223], v[8:11]
	s_setprio 0
	s_setprio 1
	v_mfma_f32_16x16x32_bf16 v[52:55], v[144:147], v[160:163], v[52:55]
	v_mfma_f32_16x16x32_bf16 v[52:55], v[148:151], v[164:167], v[52:55]
	v_mfma_f32_16x16x32_bf16 v[36:39], v[144:147], v[188:191], v[36:39]
	v_mfma_f32_16x16x32_bf16 v[36:39], v[148:151], v[192:195], v[36:39]
	v_mfma_f32_16x16x32_bf16 v[20:23], v[144:147], v[196:199], v[20:23]
	v_mfma_f32_16x16x32_bf16 v[20:23], v[148:151], v[202:205], v[20:23]
	v_mfma_f32_16x16x32_bf16 v[4:7], v[144:147], v[206:209], v[4:7]
	v_mfma_f32_16x16x32_bf16 v[4:7], v[148:151], v[220:223], v[4:7]
	v_mfma_f32_16x16x32_bf16 v[48:51], v[152:155], v[160:163], v[48:51]
	v_mfma_f32_16x16x32_bf16 v[48:51], v[156:159], v[164:167], v[48:51]
	v_mfma_f32_16x16x32_bf16 v[32:35], v[152:155], v[188:191], v[32:35]
	v_mfma_f32_16x16x32_bf16 v[32:35], v[156:159], v[192:195], v[32:35]
	v_mfma_f32_16x16x32_bf16 v[16:19], v[152:155], v[196:199], v[16:19]
	v_mfma_f32_16x16x32_bf16 v[16:19], v[156:159], v[202:205], v[16:19]
	v_mfma_f32_16x16x32_bf16 v[0:3], v[152:155], v[206:209], v[0:3]
	v_mfma_f32_16x16x32_bf16 v[0:3], v[156:159], v[220:223], v[0:3]
	s_barrier
	s_setprio 0
	s_add_i32 s65, s65, 2
	s_add_u32 s40, s40, 0x100
	s_addc_u32 s41, s41, 0
	s_add_u32 s63, s63, 0x100
	s_addc_u32 s64, s64, 0
	s_cmp_gt_u32 s65, 29
	s_cbranch_scc0 .LBB0_992
	v_lshl_add_u32 v144, s38, 8, v212
	v_ashrrev_i32_e32 v145, 31, v144
	v_or_b32_e32 v206, 16, v144
	v_lshlrev_b64 v[128:129], 7, v[144:145]
	v_ashrrev_i32_e32 v207, 31, v206
	v_lshl_add_u64 v[132:133], v[178:179], 0, v[128:129]
	v_lshlrev_b64 v[136:137], 7, v[206:207]
	global_load_dwordx4 v[128:131], v[132:133], off
	s_nop 0
	global_load_dwordx4 v[132:135], v[132:133], off offset:16
	v_lshl_add_u64 v[140:141], v[178:179], 0, v[136:137]
	global_load_dwordx4 v[136:139], v[140:141], off
	s_nop 0
	global_load_dwordx4 v[140:143], v[140:141], off offset:16
	v_readlane_b32 s64, v254, 20
	v_readlane_b32 s70, v254, 26
	v_readlane_b32 s71, v254, 27
	v_readlane_b32 s72, v254, 28
	v_readlane_b32 s73, v254, 29
	v_readlane_b32 s74, v254, 30
	v_readlane_b32 s75, v254, 31
	v_readlane_b32 s76, v254, 32
	v_readlane_b32 s77, v254, 33
	s_and_b64 vcc, exec, s[16:17]
	s_mov_b64 s[70:71], s[74:75]
	s_mov_b64 s[72:73], s[76:77]
	v_readlane_b32 s65, v254, 21
	v_readlane_b32 s66, v254, 22
	v_readlane_b32 s67, v254, 23
	v_readlane_b32 s68, v254, 24
	v_readlane_b32 s69, v254, 25
	v_readlane_b32 s78, v254, 34
	v_readlane_b32 s79, v254, 35
	s_cbranch_vccz .LBB0_995
	s_barrier

; #define PG8_STAGE(bufoff, gbase, voff) do { _Pragma("unroll") for (int _i = 0; _i < 2; ++_i) \
;         __builtin_amdgcn_global_load_lds((const unsigned*)((const char*)(gbase) + (voff)[_i]), (PG8_LAS unsigned*)(lds + (bufoff) + ldsw + _i * 8192), 16, 0, 0); } while (0)
; #define PG8_LDA(dst, b, h) do { _Pragma("unroll") for (int m = 0; m < 4; ++m) _Pragma("unroll") for (int k = 0; k < 2; ++k) dst[m][k] = *(const PG8_LAS bf16x8*)(lds + PG8_SA(b, h) + aoff + m * 2048 + k * 1024); } while (0)
; #define PG8_LDB(dst, b, h) do { _Pragma("unroll") for (int n = 0; n < 2; ++n) _Pragma("unroll") for (int k = 0; k < 2; ++k) dst[n][k] = *(const PG8_LAS bf16x8*)(lds + PG8_SB(b, h) + boff + n * 2048 + k * 1024); } while (0)
; #define PG8_MMA(ai, bj, At, Bt) do { __builtin_amdgcn_s_setprio(1); _Pragma("unroll") for (int m = 0; m < 4; ++m) _Pragma("unroll") for (int n = 0; n < 2; ++n) _Pragma("unroll") for (int k = 0; k < 2; ++k) \
;         acc[ai][bj][m][n] = __builtin_amdgcn_mfma_f32_16x16x32_bf16(Bt[n][k], At[m][k], acc[ai][bj][m][n], 0, 0, 0); __builtin_amdgcn_s_setprio(0); } while (0)
; #define PG8_WAIT_V(n) asm volatile("s_waitcnt vmcnt(" #n ")" ::: "memory")
; #define PG8_BAR __builtin_amdgcn_s_barrier()
; template <class Epi, class Sched, bool ALIGN_EPI = false, bool SP2 = false, bool DUAL = false>
; __device__ __forceinline__ void gemm_phase(PG8_LAS unsigned char* lds, const Gemm g, const Sched& S, const Epi& E) {
;     ...
;         for (int t = 0; t < nt; t += 2) {
;             const bool last = (t == nt - 2);
;             const char* a1 = cA + (size_t)(t + 1) * kstep;
;             const char* a2 = last ? nA : cA + (size_t)(t + 2) * kstep; const char* b2 = last ? nB : cB + (size_t)(t + 2) * kstep;
;             const char* a3 = a2 + kstep; const char* b3 = b2 + kstep;
;             if (last && has_next) S.a_ready(nxt);
;             if constexpr (SP2) {
;             PG8_LDB(B0, 0, 0); PG8_LDB(B1, 0, 1); PG8_SCHED; PG8_LDA(At, 0, 0); PG8_STAGE(PG8_SA(1, 1), a1 + hstep, voffA);
;             PG8_WAIT_V(8); PG8_WAIT_L(0); PG8_BAR; PG8_MMA(0, 0, At, B0); PG8_MMA(0, 1, At, B1); PG8_BAR; PG8_SCHED;
;             PG8_LDA(At, 0, 1); PG8_STAGE(PG8_SB(0, 0), b2, voffB); PG8_STAGE(PG8_SB(0, 1), b2 + hstep, voffB); PG8_STAGE(PG8_SA(0, 0), a2, voffA);
;             PG8_WAIT_V(8); PG8_WAIT_L(0); PG8_BAR; PG8_MMA(1, 0, At, B0); PG8_MMA(1, 1, At, B1); PG8_BAR; PG8_SCHED;
.LBB0_1192:
	s_add_u32 s24, s24, 0x160080
	s_addc_u32 s25, s25, 0
	s_add_u32 s46, s14, 0x100
	s_addc_u32 s47, s15, 0
	s_mov_b32 s48, -2
	s_add_u32 s14, s24, 0xffea0080
	s_addc_u32 s15, s25, -1
	s_cmpk_eq_i32 s48, 0x54
	s_cselect_b32 s27, s5, s15
	s_cselect_b32 s26, s4, s14
	s_cselect_b32 s15, s23, s47
	s_cselect_b32 s14, s22, s46
	s_waitcnt vmcnt(8)
	s_waitcnt lgkmcnt(0)
	s_setprio 1
	s_barrier
	v_mfma_f32_16x16x32_bf16 v[124:127], v[128:131], v[160:163], 0
	v_mfma_f32_16x16x32_bf16 v[124:127], v[132:135], v[182:185], v[124:127]
	v_mfma_f32_16x16x32_bf16 v[112:115], v[128:131], v[186:189], 0
	v_mfma_f32_16x16x32_bf16 v[112:115], v[132:135], v[190:193], v[112:115]
	v_mfma_f32_16x16x32_bf16 v[96:99], v[128:131], v[204:207], 0
	v_mfma_f32_16x16x32_bf16 v[96:99], v[132:135], v[208:211], v[96:99]
	v_mfma_f32_16x16x32_bf16 v[80:83], v[128:131], v[212:215], 0
	v_mfma_f32_16x16x32_bf16 v[80:83], v[132:135], v[216:219], v[80:83]
	v_mfma_f32_16x16x32_bf16 v[120:123], v[136:139], v[160:163], 0
	v_mfma_f32_16x16x32_bf16 v[120:123], v[140:143], v[182:185], v[120:123]
	v_mfma_f32_16x16x32_bf16 v[104:107], v[136:139], v[186:189], 0
	v_mfma_f32_16x16x32_bf16 v[104:107], v[140:143], v[190:193], v[104:107]
	v_mfma_f32_16x16x32_bf16 v[88:91], v[136:139], v[204:207], 0
	v_mfma_f32_16x16x32_bf16 v[88:91], v[140:143], v[208:211], v[88:91]
	v_mfma_f32_16x16x32_bf16 v[72:75], v[136:139], v[212:215], 0
	v_mfma_f32_16x16x32_bf16 v[72:75], v[140:143], v[216:219], v[72:75]
	s_setprio 0
	s_setprio 1
	v_mfma_f32_16x16x32_bf16 v[116:119], v[144:147], v[160:163], 0
	v_mfma_f32_16x16x32_bf16 v[116:119], v[148:151], v[182:185], v[116:119]
	v_mfma_f32_16x16x32_bf16 v[100:103], v[144:147], v[186:189], 0
	v_mfma_f32_16x16x32_bf16 v[100:103], v[148:151], v[190:193], v[100:103]
	v_mfma_f32_16x16x32_bf16 v[84:87], v[144:147], v[204:207], 0
	v_mfma_f32_16x16x32_bf16 v[84:87], v[148:151], v[208:211], v[84:87]
	v_mfma_f32_16x16x32_bf16 v[68:71], v[144:147], v[212:215], 0
	v_mfma_f32_16x16x32_bf16 v[68:71], v[148:151], v[216:219], v[68:71]
	v_mfma_f32_16x16x32_bf16 v[108:111], v[152:155], v[160:163], 0
	v_mfma_f32_16x16x32_bf16 v[108:111], v[156:159], v[182:185], v[108:111]
	v_mfma_f32_16x16x32_bf16 v[92:95], v[152:155], v[186:189], 0
	v_mfma_f32_16x16x32_bf16 v[92:95], v[156:159], v[190:193], v[92:95]
	v_mfma_f32_16x16x32_bf16 v[76:79], v[152:155], v[204:207], 0
	v_mfma_f32_16x16x32_bf16 v[76:79], v[156:159], v[208:211], v[76:79]
	v_mfma_f32_16x16x32_bf16 v[64:67], v[152:155], v[212:215], 0
	v_mfma_f32_16x16x32_bf16 v[64:67], v[156:159], v[216:219], v[64:67]
	s_barrier
	s_setprio 0
	v_lshl_add_u64 v[220:221], s[24:25], 0, v[172:173]
	s_add_i32 m0, s31, 0xc000
	s_nop 0
	global_load_lds_dwordx4 v[220:221], off
	v_lshl_add_u64 v[220:221], s[24:25], 0, v[174:175]
	s_add_i32 m0, s31, 0xe000
	s_nop 0
	global_load_lds_dwordx4 v[220:221], off
	s_add_i32 s49, s40, s30
	v_lshl_add_u64 v[220:221], s[14:15], 0, v[166:167]
	s_mov_b32 m0, s49
	ds_read_b128 v[160:163], v203 offset:16384
	ds_read_b128 v[182:185], v203 offset:17408
	ds_read_b128 v[186:189], v203 offset:18432
	ds_read_b128 v[190:193], v203 offset:19456
	ds_read_b128 v[204:207], v203 offset:20480
	ds_read_b128 v[208:211], v203 offset:21504
	ds_read_b128 v[212:215], v203 offset:22528
	ds_read_b128 v[216:219], v203 offset:23552
	global_load_lds_dwordx4 v[220:221], off
	s_add_i32 m0, s49, 0x2000
	s_add_u32 s50, s14, 0x160000
	v_lshl_add_u64 v[222:223], s[14:15], 0, v[170:171]
	s_addc_u32 s51, s15, 0
	s_add_i32 s49, s41, s30
	global_load_lds_dwordx4 v[222:223], off
	v_lshl_add_u64 v[224:225], s[50:51], 0, v[166:167]
	s_mov_b32 m0, s49
	v_lshl_add_u64 v[226:227], s[26:27], 0, v[168:169]
	global_load_lds_dwordx4 v[224:225], off
	v_lshl_add_u64 v[224:225], s[50:51], 0, v[170:171]
	s_add_i32 m0, s49, 0x2000
	s_nop 0
	global_load_lds_dwordx4 v[224:225], off
	v_lshl_add_u64 v[224:225], s[26:27], 0, v[164:165]
	s_mov_b32 m0, s31
	s_nop 0
	global_load_lds_dwordx4 v[224:225], off
	s_mov_b32 m0, s33
	s_nop 0
	global_load_lds_dwordx4 v[226:227], off
	s_waitcnt vmcnt(8)
	s_waitcnt lgkmcnt(0)
	s_setprio 1
	s_barrier
	v_mfma_f32_16x16x32_bf16 v[60:63], v[128:131], v[160:163], 0
	v_mfma_f32_16x16x32_bf16 v[60:63], v[132:135], v[182:185], v[60:63]
	v_mfma_f32_16x16x32_bf16 v[48:51], v[128:131], v[186:189], 0
	v_mfma_f32_16x16x32_bf16 v[48:51], v[132:135], v[190:193], v[48:51]
	v_mfma_f32_16x16x32_bf16 v[32:35], v[128:131], v[204:207], 0
	v_mfma_f32_16x16x32_bf16 v[32:35], v[132:135], v[208:211], v[32:35]
	v_mfma_f32_16x16x32_bf16 v[16:19], v[128:131], v[212:215], 0
	v_mfma_f32_16x16x32_bf16 v[16:19], v[132:135], v[216:219], v[16:19]
	v_mfma_f32_16x16x32_bf16 v[56:59], v[136:139], v[160:163], 0
	v_mfma_f32_16x16x32_bf16 v[56:59], v[140:143], v[182:185], v[56:59]
	v_mfma_f32_16x16x32_bf16 v[40:43], v[136:139], v[186:189], 0
	v_mfma_f32_16x16x32_bf16 v[40:43], v[140:143], v[190:193], v[40:43]
	v_mfma_f32_16x16x32_bf16 v[24:27], v[136:139], v[204:207], 0
	v_mfma_f32_16x16x32_bf16 v[24:27], v[140:143], v[208:211], v[24:27]
	v_mfma_f32_16x16x32_bf16 v[8:11], v[136:139], v[212:215], 0
	v_mfma_f32_16x16x32_bf16 v[8:11], v[140:143], v[216:219], v[8:11]
	s_setprio 0
	s_setprio 1
	v_mfma_f32_16x16x32_bf16 v[52:55], v[144:147], v[160:163], 0
	v_mfma_f32_16x16x32_bf16 v[52:55], v[148:151], v[182:185], v[52:55]
	v_mfma_f32_16x16x32_bf16 v[36:39], v[144:147], v[186:189], 0
	v_mfma_f32_16x16x32_bf16 v[36:39], v[148:151], v[190:193], v[36:39]
	v_mfma_f32_16x16x32_bf16 v[20:23], v[144:147], v[204:207], 0
	v_mfma_f32_16x16x32_bf16 v[20:23], v[148:151], v[208:211], v[20:23]
	v_mfma_f32_16x16x32_bf16 v[4:7], v[144:147], v[212:215], 0
	v_mfma_f32_16x16x32_bf16 v[4:7], v[148:151], v[216:219], v[4:7]
	v_mfma_f32_16x16x32_bf16 v[44:47], v[152:155], v[160:163], 0
	v_mfma_f32_16x16x32_bf16 v[44:47], v[156:159], v[182:185], v[44:47]
	v_mfma_f32_16x16x32_bf16 v[28:31], v[152:155], v[186:189], 0
	v_mfma_f32_16x16x32_bf16 v[28:31], v[156:159], v[190:193], v[28:31]
	v_mfma_f32_16x16x32_bf16 v[12:15], v[152:155], v[204:207], 0
	v_mfma_f32_16x16x32_bf16 v[12:15], v[156:159], v[208:211], v[12:15]
	v_mfma_f32_16x16x32_bf16 v[0:3], v[152:155], v[212:215], 0
	v_mfma_f32_16x16x32_bf16 v[0:3], v[156:159], v[216:219], v[0:3]
	s_barrier
; #define PG8_STAGE(bufoff, gbase, voff) do { _Pragma("unroll") for (int _i = 0; _i < 2; ++_i) \
;         __builtin_amdgcn_global_load_lds((const unsigned*)((const char*)(gbase) + (voff)[_i]), (PG8_LAS unsigned*)(lds + (bufoff) + ldsw + _i * 8192), 16, 0, 0); } while (0)
; #define PG8_LDA(dst, b, h) do { _Pragma("unroll") for (int m = 0; m < 4; ++m) _Pragma("unroll") for (int k = 0; k < 2; ++k) dst[m][k] = *(const PG8_LAS bf16x8*)(lds + PG8_SA(b, h) + aoff + m * 2048 + k * 1024); } while (0)
; #define PG8_LDB(dst, b, h) do { _Pragma("unroll") for (int n = 0; n < 2; ++n) _Pragma("unroll") for (int k = 0; k < 2; ++k) dst[n][k] = *(const PG8_LAS bf16x8*)(lds + PG8_SB(b, h) + boff + n * 2048 + k * 1024); } while (0)
; #define PG8_MMA(ai, bj, At, Bt) do { __builtin_amdgcn_s_setprio(1); _Pragma("unroll") for (int m = 0; m < 4; ++m) _Pragma("unroll") for (int n = 0; n < 2; ++n) _Pragma("unroll") for (int k = 0; k < 2; ++k) \
;         acc[ai][bj][m][n] = __builtin_amdgcn_mfma_f32_16x16x32_bf16(Bt[n][k], At[m][k], acc[ai][bj][m][n], 0, 0, 0); __builtin_amdgcn_s_setprio(0); } while (0)
; #define PG8_WAIT_V(n) asm volatile("s_waitcnt vmcnt(" #n ")" ::: "memory")
; #define PG8_WAIT_L(n) asm volatile("s_waitcnt lgkmcnt(" #n ")" ::: "memory")
; #define PG8_BAR __builtin_amdgcn_s_barrier()
; #define PG8_SCHED __builtin_amdgcn_sched_barrier(0)
; template <class Epi, class Sched, bool ALIGN_EPI = false, bool SP2 = false, bool DUAL = false>
; __device__ __forceinline__ void gemm_phase(PG8_LAS unsigned char* lds, const Gemm g, const Sched& S, const Epi& E) {
;     ...
;             PG8_LDB(B0, 1, 0); PG8_LDB(B1, 1, 1); PG8_SCHED; PG8_LDA(At, 1, 0); PG8_STAGE(PG8_SA(0, 1), a2 + hstep, voffA);
;             PG8_WAIT_V(8); PG8_WAIT_L(0); PG8_BAR; PG8_MMA(0, 0, At, B0); PG8_MMA(0, 1, At, B1); PG8_BAR; PG8_SCHED;
;             PG8_LDA(At, 1, 1); PG8_STAGE(PG8_SB(1, 0), b3, voffB); PG8_STAGE(PG8_SB(1, 1), b3 + hstep, voffB); PG8_STAGE(PG8_SA(1, 0), a3, voffA);
;             PG8_WAIT_V(8); PG8_WAIT_L(0); PG8_BAR; PG8_MMA(1, 0, At, B0); PG8_MMA(1, 1, At, B1); PG8_BAR; PG8_SCHED;
	s_setprio 0
	s_add_i32 s49, 0, 0x18000
	s_add_i32 s50, 0, 0x1c000
	v_add_u32_e32 v140, s49, v198
	v_add_u32_e32 v156, s50, v198
	ds_read_b128 v[128:131], v140
	ds_read_b128 v[132:135], v140 offset:1024
	ds_read_b128 v[136:139], v140 offset:2048
	ds_read_b128 v[140:143], v140 offset:3072
	ds_read_b128 v[144:147], v156
	ds_read_b128 v[148:151], v156 offset:1024
	ds_read_b128 v[152:155], v156 offset:2048
	ds_read_b128 v[156:159], v156 offset:3072
	s_add_u32 s26, s26, 0x160000
	s_addc_u32 s27, s27, 0
	s_mov_b32 m0, s34
	v_lshl_add_u64 v[228:229], s[26:27], 0, v[164:165]
	ds_read_b128 v[160:163], v203 offset:32768
	ds_read_b128 v[182:185], v203 offset:33792
	ds_read_b128 v[186:189], v203 offset:34816
	ds_read_b128 v[190:193], v203 offset:35840
	ds_read_b128 v[204:207], v203 offset:36864
	ds_read_b128 v[208:211], v203 offset:37888
	ds_read_b128 v[212:215], v203 offset:38912
	ds_read_b128 v[216:219], v203 offset:39936
	global_load_lds_dwordx4 v[228:229], off
	v_lshl_add_u64 v[228:229], s[26:27], 0, v[168:169]
	s_mov_b32 m0, s35
	s_nop 0
	global_load_lds_dwordx4 v[228:229], off
	s_waitcnt vmcnt(8)
	s_waitcnt lgkmcnt(0)
	s_setprio 1
	s_barrier
	v_mfma_f32_16x16x32_bf16 v[124:127], v[128:131], v[160:163], v[124:127]
	v_mfma_f32_16x16x32_bf16 v[124:127], v[132:135], v[182:185], v[124:127]
	v_mfma_f32_16x16x32_bf16 v[112:115], v[128:131], v[186:189], v[112:115]
	v_mfma_f32_16x16x32_bf16 v[112:115], v[132:135], v[190:193], v[112:115]
	v_mfma_f32_16x16x32_bf16 v[96:99], v[128:131], v[204:207], v[96:99]
	v_mfma_f32_16x16x32_bf16 v[96:99], v[132:135], v[208:211], v[96:99]
	v_mfma_f32_16x16x32_bf16 v[80:83], v[128:131], v[212:215], v[80:83]
	v_mfma_f32_16x16x32_bf16 v[80:83], v[132:135], v[216:219], v[80:83]
	v_mfma_f32_16x16x32_bf16 v[120:123], v[136:139], v[160:163], v[120:123]
	v_mfma_f32_16x16x32_bf16 v[120:123], v[140:143], v[182:185], v[120:123]
	v_mfma_f32_16x16x32_bf16 v[104:107], v[136:139], v[186:189], v[104:107]
	v_mfma_f32_16x16x32_bf16 v[104:107], v[140:143], v[190:193], v[104:107]
	v_mfma_f32_16x16x32_bf16 v[88:91], v[136:139], v[204:207], v[88:91]
	v_mfma_f32_16x16x32_bf16 v[88:91], v[140:143], v[208:211], v[88:91]
	v_mfma_f32_16x16x32_bf16 v[72:75], v[136:139], v[212:215], v[72:75]
	v_mfma_f32_16x16x32_bf16 v[72:75], v[140:143], v[216:219], v[72:75]
	s_setprio 0
	s_setprio 1
	v_mfma_f32_16x16x32_bf16 v[116:119], v[144:147], v[160:163], v[116:119]
	v_mfma_f32_16x16x32_bf16 v[116:119], v[148:151], v[182:185], v[116:119]
	v_mfma_f32_16x16x32_bf16 v[100:103], v[144:147], v[186:189], v[100:103]
	v_mfma_f32_16x16x32_bf16 v[100:103], v[148:151], v[190:193], v[100:103]
	v_mfma_f32_16x16x32_bf16 v[84:87], v[144:147], v[204:207], v[84:87]
	v_mfma_f32_16x16x32_bf16 v[84:87], v[148:151], v[208:211], v[84:87]
	v_mfma_f32_16x16x32_bf16 v[68:71], v[144:147], v[212:215], v[68:71]
	v_mfma_f32_16x16x32_bf16 v[68:71], v[148:151], v[216:219], v[68:71]
	v_mfma_f32_16x16x32_bf16 v[108:111], v[152:155], v[160:163], v[108:111]
	v_mfma_f32_16x16x32_bf16 v[108:111], v[156:159], v[182:185], v[108:111]
	v_mfma_f32_16x16x32_bf16 v[92:95], v[152:155], v[186:189], v[92:95]
	v_mfma_f32_16x16x32_bf16 v[92:95], v[156:159], v[190:193], v[92:95]
	v_mfma_f32_16x16x32_bf16 v[76:79], v[152:155], v[204:207], v[76:79]
	v_mfma_f32_16x16x32_bf16 v[76:79], v[156:159], v[208:211], v[76:79]
	v_mfma_f32_16x16x32_bf16 v[64:67], v[152:155], v[212:215], v[64:67]
	v_mfma_f32_16x16x32_bf16 v[64:67], v[156:159], v[216:219], v[64:67]
	s_barrier
	s_setprio 0
	s_add_i32 s26, s49, s30
	v_lshl_add_u64 v[220:221], v[220:221], 0, s[18:19]
	s_mov_b32 m0, s26
	ds_read_b128 v[160:163], v203 offset:49152
	ds_read_b128 v[182:185], v203 offset:50176
	ds_read_b128 v[186:189], v203 offset:51200
	ds_read_b128 v[190:193], v203 offset:52224
	ds_read_b128 v[204:207], v203 offset:53248
	ds_read_b128 v[208:211], v203 offset:54272
	ds_read_b128 v[212:215], v203 offset:55296
	ds_read_b128 v[216:219], v203 offset:56320
	global_load_lds_dwordx4 v[220:221], off
	s_add_i32 m0, s26, 0x2000
	s_add_u32 s14, s14, 0x160080
	v_lshl_add_u64 v[220:221], v[222:223], 0, s[18:19]
	s_addc_u32 s15, s15, 0
	s_add_i32 s26, s50, s30
	global_load_lds_dwordx4 v[220:221], off
	v_lshl_add_u64 v[220:221], s[14:15], 0, v[166:167]
	s_mov_b32 m0, s26
	s_nop 0
	global_load_lds_dwordx4 v[220:221], off
	v_lshl_add_u64 v[220:221], s[14:15], 0, v[170:171]
	s_add_i32 m0, s26, 0x2000
	s_nop 0
	global_load_lds_dwordx4 v[220:221], off
	v_lshl_add_u64 v[220:221], v[224:225], 0, s[18:19]
	s_mov_b32 m0, s37
	s_nop 0
	global_load_lds_dwordx4 v[220:221], off
	v_lshl_add_u64 v[220:221], v[226:227], 0, s[18:19]
	s_mov_b32 m0, s38
	s_nop 0
	global_load_lds_dwordx4 v[220:221], off
	s_waitcnt vmcnt(8)
	s_waitcnt lgkmcnt(0)
	s_setprio 1
	s_barrier
; #define PG8_STAGE(bufoff, gbase, voff) do { _Pragma("unroll") for (int _i = 0; _i < 2; ++_i) \
;         __builtin_amdgcn_global_load_lds((const unsigned*)((const char*)(gbase) + (voff)[_i]), (PG8_LAS unsigned*)(lds + (bufoff) + ldsw + _i * 8192), 16, 0, 0); } while (0)
; #define PG8_LDA(dst, b, h) do { _Pragma("unroll") for (int m = 0; m < 4; ++m) _Pragma("unroll") for (int k = 0; k < 2; ++k) dst[m][k] = *(const PG8_LAS bf16x8*)(lds + PG8_SA(b, h) + aoff + m * 2048 + k * 1024); } while (0)
; #define PG8_LDB(dst, b, h) do { _Pragma("unroll") for (int n = 0; n < 2; ++n) _Pragma("unroll") for (int k = 0; k < 2; ++k) dst[n][k] = *(const PG8_LAS bf16x8*)(lds + PG8_SB(b, h) + boff + n * 2048 + k * 1024); } while (0)
; #define PG8_WAIT_V(n) asm volatile("s_waitcnt vmcnt(" #n ")" ::: "memory")
; #define PG8_BAR __builtin_amdgcn_s_barrier()
; template <class Epi, class Sched, bool ALIGN_EPI = false, bool SP2 = false, bool DUAL = false>
; __device__ __forceinline__ void gemm_phase(PG8_LAS unsigned char* lds, const Gemm g, const Sched& S, const Epi& E) {
;     ...
;             const char* a2 = last ? nA : cA + (size_t)(t + 2) * kstep; const char* b2 = last ? nB : cB + (size_t)(t + 2) * kstep;
;             const char* a3 = a2 + kstep; const char* b3 = b2 + kstep;
;             if (last && has_next) S.a_ready(nxt);
;             if constexpr (SP2) {
;             PG8_LDB(B0, 0, 0); PG8_LDB(B1, 0, 1); PG8_SCHED; PG8_LDA(At, 0, 0); PG8_STAGE(PG8_SA(1, 1), a1 + hstep, voffA);
;             PG8_WAIT_V(8); PG8_WAIT_L(0); PG8_BAR; PG8_MMA(0, 0, At, B0); PG8_MMA(0, 1, At, B1); PG8_BAR; PG8_SCHED;
;             PG8_LDA(At, 0, 1); PG8_STAGE(PG8_SB(0, 0), b2, voffB); PG8_STAGE(PG8_SB(0, 1), b2 + hstep, voffB); PG8_STAGE(PG8_SA(0, 0), a2, voffA);
;             PG8_WAIT_V(8); PG8_WAIT_L(0); PG8_BAR; PG8_MMA(1, 0, At, B0); PG8_MMA(1, 1, At, B1); PG8_BAR; PG8_SCHED;
;             PG8_LDB(B0, 1, 0); PG8_LDB(B1, 1, 1); PG8_SCHED; PG8_LDA(At, 1, 0); PG8_STAGE(PG8_SA(0, 1), a2 + hstep, voffA);
;             PG8_WAIT_V(8); PG8_WAIT_L(0); PG8_BAR; PG8_MMA(0, 0, At, B0); PG8_MMA(0, 1, At, B1); PG8_BAR; PG8_SCHED;
;             PG8_LDA(At, 1, 1); PG8_STAGE(PG8_SB(1, 0), b3, voffB); PG8_STAGE(PG8_SB(1, 1), b3 + hstep, voffB); PG8_STAGE(PG8_SA(1, 0), a3, voffA);
;             PG8_WAIT_V(8); PG8_WAIT_L(0); PG8_BAR; PG8_MMA(1, 0, At, B0); PG8_MMA(1, 1, At, B1); PG8_BAR; PG8_SCHED;
	v_mfma_f32_16x16x32_bf16 v[60:63], v[128:131], v[160:163], v[60:63]
	v_mfma_f32_16x16x32_bf16 v[60:63], v[132:135], v[182:185], v[60:63]
	v_mfma_f32_16x16x32_bf16 v[48:51], v[128:131], v[186:189], v[48:51]
	v_mfma_f32_16x16x32_bf16 v[48:51], v[132:135], v[190:193], v[48:51]
	v_mfma_f32_16x16x32_bf16 v[32:35], v[128:131], v[204:207], v[32:35]
	v_mfma_f32_16x16x32_bf16 v[32:35], v[132:135], v[208:211], v[32:35]
	v_mfma_f32_16x16x32_bf16 v[16:19], v[128:131], v[212:215], v[16:19]
	v_mfma_f32_16x16x32_bf16 v[16:19], v[132:135], v[216:219], v[16:19]
	v_mfma_f32_16x16x32_bf16 v[56:59], v[136:139], v[160:163], v[56:59]
	v_mfma_f32_16x16x32_bf16 v[56:59], v[140:143], v[182:185], v[56:59]
	v_mfma_f32_16x16x32_bf16 v[40:43], v[136:139], v[186:189], v[40:43]
	v_mfma_f32_16x16x32_bf16 v[40:43], v[140:143], v[190:193], v[40:43]
	v_mfma_f32_16x16x32_bf16 v[24:27], v[136:139], v[204:207], v[24:27]
	v_mfma_f32_16x16x32_bf16 v[24:27], v[140:143], v[208:211], v[24:27]
	v_mfma_f32_16x16x32_bf16 v[8:11], v[136:139], v[212:215], v[8:11]
	v_mfma_f32_16x16x32_bf16 v[8:11], v[140:143], v[216:219], v[8:11]
	s_setprio 0
	s_setprio 1
	v_mfma_f32_16x16x32_bf16 v[52:55], v[144:147], v[160:163], v[52:55]
	v_mfma_f32_16x16x32_bf16 v[52:55], v[148:151], v[182:185], v[52:55]
	v_mfma_f32_16x16x32_bf16 v[36:39], v[144:147], v[186:189], v[36:39]
	v_mfma_f32_16x16x32_bf16 v[36:39], v[148:151], v[190:193], v[36:39]
	v_mfma_f32_16x16x32_bf16 v[20:23], v[144:147], v[204:207], v[20:23]
	v_mfma_f32_16x16x32_bf16 v[20:23], v[148:151], v[208:211], v[20:23]
	v_mfma_f32_16x16x32_bf16 v[4:7], v[144:147], v[212:215], v[4:7]
	v_mfma_f32_16x16x32_bf16 v[4:7], v[148:151], v[216:219], v[4:7]
	v_mfma_f32_16x16x32_bf16 v[44:47], v[152:155], v[160:163], v[44:47]
	v_mfma_f32_16x16x32_bf16 v[44:47], v[156:159], v[182:185], v[44:47]
	v_mfma_f32_16x16x32_bf16 v[28:31], v[152:155], v[186:189], v[28:31]
	v_mfma_f32_16x16x32_bf16 v[28:31], v[156:159], v[190:193], v[28:31]
	v_mfma_f32_16x16x32_bf16 v[12:15], v[152:155], v[204:207], v[12:15]
	v_mfma_f32_16x16x32_bf16 v[12:15], v[156:159], v[208:211], v[12:15]
	v_mfma_f32_16x16x32_bf16 v[0:3], v[152:155], v[212:215], v[0:3]
	v_mfma_f32_16x16x32_bf16 v[0:3], v[156:159], v[216:219], v[0:3]
	s_barrier
	s_setprio 0
	s_add_i32 s48, s48, 2
	s_add_u32 s24, s24, 0x100
	s_addc_u32 s25, s25, 0
	s_add_u32 s46, s46, 0x100
	s_addc_u32 s47, s47, 0
.LBB0_1193:
	ds_read_b128 v[128:131], v201
	ds_read_b128 v[132:135], v201 offset:1024
	ds_read_b128 v[136:139], v201 offset:2048
	ds_read_b128 v[140:143], v201 offset:3072
	ds_read_b128 v[144:147], v202
	ds_read_b128 v[148:151], v202 offset:1024
	ds_read_b128 v[152:155], v202 offset:2048
	ds_read_b128 v[156:159], v202 offset:3072
	s_add_u32 s14, s24, 0xffea0080
	s_addc_u32 s15, s25, -1
	s_cmpk_eq_i32 s48, 0x54
	s_cselect_b32 s27, s5, s15
	s_cselect_b32 s26, s4, s14
	s_cselect_b32 s15, s23, s47
	s_cselect_b32 s14, s22, s46
	v_lshl_add_u64 v[220:221], s[24:25], 0, v[172:173]
	s_add_i32 m0, s31, 0xc000
	ds_read_b128 v[160:163], v203
	ds_read_b128 v[182:185], v203 offset:1024
	ds_read_b128 v[186:189], v203 offset:2048
	ds_read_b128 v[190:193], v203 offset:3072
	ds_read_b128 v[204:207], v203 offset:4096
	ds_read_b128 v[208:211], v203 offset:5120
	ds_read_b128 v[212:215], v203 offset:6144
	ds_read_b128 v[216:219], v203 offset:7168
	global_load_lds_dwordx4 v[220:221], off
	v_lshl_add_u64 v[220:221], s[24:25], 0, v[174:175]
	s_add_i32 m0, s31, 0xe000
	s_nop 0
	global_load_lds_dwordx4 v[220:221], off
	s_waitcnt vmcnt(8)
	s_waitcnt lgkmcnt(0)
	s_setprio 1
	s_barrier
	v_mfma_f32_16x16x32_bf16 v[124:127], v[128:131], v[160:163], v[124:127]
	v_mfma_f32_16x16x32_bf16 v[124:127], v[132:135], v[182:185], v[124:127]
	v_mfma_f32_16x16x32_bf16 v[112:115], v[128:131], v[186:189], v[112:115]
	v_mfma_f32_16x16x32_bf16 v[112:115], v[132:135], v[190:193], v[112:115]
	v_mfma_f32_16x16x32_bf16 v[96:99], v[128:131], v[204:207], v[96:99]
	v_mfma_f32_16x16x32_bf16 v[96:99], v[132:135], v[208:211], v[96:99]
	v_mfma_f32_16x16x32_bf16 v[80:83], v[128:131], v[212:215], v[80:83]
	v_mfma_f32_16x16x32_bf16 v[80:83], v[132:135], v[216:219], v[80:83]
	v_mfma_f32_16x16x32_bf16 v[120:123], v[136:139], v[160:163], v[120:123]
	v_mfma_f32_16x16x32_bf16 v[120:123], v[140:143], v[182:185], v[120:123]
	v_mfma_f32_16x16x32_bf16 v[104:107], v[136:139], v[186:189], v[104:107]
	v_mfma_f32_16x16x32_bf16 v[104:107], v[140:143], v[190:193], v[104:107]
	v_mfma_f32_16x16x32_bf16 v[88:91], v[136:139], v[204:207], v[88:91]
	v_mfma_f32_16x16x32_bf16 v[88:91], v[140:143], v[208:211], v[88:91]
	v_mfma_f32_16x16x32_bf16 v[72:75], v[136:139], v[212:215], v[72:75]
	v_mfma_f32_16x16x32_bf16 v[72:75], v[140:143], v[216:219], v[72:75]
	s_setprio 0
	s_setprio 1
	v_mfma_f32_16x16x32_bf16 v[116:119], v[144:147], v[160:163], v[116:119]
	v_mfma_f32_16x16x32_bf16 v[116:119], v[148:151], v[182:185], v[116:119]
	v_mfma_f32_16x16x32_bf16 v[100:103], v[144:147], v[186:189], v[100:103]
	v_mfma_f32_16x16x32_bf16 v[100:103], v[148:151], v[190:193], v[100:103]
	v_mfma_f32_16x16x32_bf16 v[84:87], v[144:147], v[204:207], v[84:87]
	v_mfma_f32_16x16x32_bf16 v[84:87], v[148:151], v[208:211], v[84:87]
	v_mfma_f32_16x16x32_bf16 v[68:71], v[144:147], v[212:215], v[68:71]
	v_mfma_f32_16x16x32_bf16 v[68:71], v[148:151], v[216:219], v[68:71]
	v_mfma_f32_16x16x32_bf16 v[108:111], v[152:155], v[160:163], v[108:111]
	v_mfma_f32_16x16x32_bf16 v[108:111], v[156:159], v[182:185], v[108:111]
	v_mfma_f32_16x16x32_bf16 v[92:95], v[152:155], v[186:189], v[92:95]
	v_mfma_f32_16x16x32_bf16 v[92:95], v[156:159], v[190:193], v[92:95]
	v_mfma_f32_16x16x32_bf16 v[76:79], v[152:155], v[204:207], v[76:79]
	v_mfma_f32_16x16x32_bf16 v[76:79], v[156:159], v[208:211], v[76:79]
	v_mfma_f32_16x16x32_bf16 v[64:67], v[152:155], v[212:215], v[64:67]
	v_mfma_f32_16x16x32_bf16 v[64:67], v[156:159], v[216:219], v[64:67]
	s_barrier
; #define PG8_STAGE(bufoff, gbase, voff) do { _Pragma("unroll") for (int _i = 0; _i < 2; ++_i) \
;         __builtin_amdgcn_global_load_lds((const unsigned*)((const char*)(gbase) + (voff)[_i]), (PG8_LAS unsigned*)(lds + (bufoff) + ldsw + _i * 8192), 16, 0, 0); } while (0)
; #define PG8_LDA(dst, b, h) do { _Pragma("unroll") for (int m = 0; m < 4; ++m) _Pragma("unroll") for (int k = 0; k < 2; ++k) dst[m][k] = *(const PG8_LAS bf16x8*)(lds + PG8_SA(b, h) + aoff + m * 2048 + k * 1024); } while (0)
; #define PG8_LDB(dst, b, h) do { _Pragma("unroll") for (int n = 0; n < 2; ++n) _Pragma("unroll") for (int k = 0; k < 2; ++k) dst[n][k] = *(const PG8_LAS bf16x8*)(lds + PG8_SB(b, h) + boff + n * 2048 + k * 1024); } while (0)
; #define PG8_MMA(ai, bj, At, Bt) do { __builtin_amdgcn_s_setprio(1); _Pragma("unroll") for (int m = 0; m < 4; ++m) _Pragma("unroll") for (int n = 0; n < 2; ++n) _Pragma("unroll") for (int k = 0; k < 2; ++k) \
;         acc[ai][bj][m][n] = __builtin_amdgcn_mfma_f32_16x16x32_bf16(Bt[n][k], At[m][k], acc[ai][bj][m][n], 0, 0, 0); __builtin_amdgcn_s_setprio(0); } while (0)
; #define PG8_WAIT_V(n) asm volatile("s_waitcnt vmcnt(" #n ")" ::: "memory")
; #define PG8_WAIT_L(n) asm volatile("s_waitcnt lgkmcnt(" #n ")" ::: "memory")
; #define PG8_BAR __builtin_amdgcn_s_barrier()
; #define PG8_SCHED __builtin_amdgcn_sched_barrier(0)
; template <class Epi, class Sched, bool ALIGN_EPI = false, bool SP2 = false, bool DUAL = false>
; __device__ __forceinline__ void gemm_phase(PG8_LAS unsigned char* lds, const Gemm g, const Sched& S, const Epi& E) {
;     ...
;             PG8_LDA(At, 0, 1); PG8_STAGE(PG8_SB(0, 0), b2, voffB); PG8_STAGE(PG8_SB(0, 1), b2 + hstep, voffB); PG8_STAGE(PG8_SA(0, 0), a2, voffA);
;             PG8_WAIT_V(8); PG8_WAIT_L(0); PG8_BAR; PG8_MMA(1, 0, At, B0); PG8_MMA(1, 1, At, B1); PG8_BAR; PG8_SCHED;
;             PG8_LDB(B0, 1, 0); PG8_LDB(B1, 1, 1); PG8_SCHED; PG8_LDA(At, 1, 0); PG8_STAGE(PG8_SA(0, 1), a2 + hstep, voffA);
;             PG8_WAIT_V(8); PG8_WAIT_L(0); PG8_BAR; PG8_MMA(0, 0, At, B0); PG8_MMA(0, 1, At, B1); PG8_BAR; PG8_SCHED;
	s_setprio 0
	s_add_i32 s49, s40, s30
	v_lshl_add_u64 v[220:221], s[14:15], 0, v[166:167]
	s_mov_b32 m0, s49
	ds_read_b128 v[160:163], v203 offset:16384
	ds_read_b128 v[182:185], v203 offset:17408
	ds_read_b128 v[186:189], v203 offset:18432
	ds_read_b128 v[190:193], v203 offset:19456
	ds_read_b128 v[204:207], v203 offset:20480
	ds_read_b128 v[208:211], v203 offset:21504
	ds_read_b128 v[212:215], v203 offset:22528
	ds_read_b128 v[216:219], v203 offset:23552
	global_load_lds_dwordx4 v[220:221], off
	s_add_i32 m0, s49, 0x2000
	s_add_u32 s50, s14, 0x160000
	v_lshl_add_u64 v[222:223], s[14:15], 0, v[170:171]
	s_addc_u32 s51, s15, 0
	s_add_i32 s49, s41, s30
	global_load_lds_dwordx4 v[222:223], off
	v_lshl_add_u64 v[224:225], s[50:51], 0, v[166:167]
	s_mov_b32 m0, s49
	v_lshl_add_u64 v[226:227], s[26:27], 0, v[168:169]
	global_load_lds_dwordx4 v[224:225], off
	v_lshl_add_u64 v[224:225], s[50:51], 0, v[170:171]
	s_add_i32 m0, s49, 0x2000
	s_nop 0
	global_load_lds_dwordx4 v[224:225], off
	v_lshl_add_u64 v[224:225], s[26:27], 0, v[164:165]
	s_mov_b32 m0, s31
	s_nop 0
	global_load_lds_dwordx4 v[224:225], off
	s_mov_b32 m0, s33
	s_nop 0
	global_load_lds_dwordx4 v[226:227], off
	s_waitcnt vmcnt(8)
	s_waitcnt lgkmcnt(0)
	s_setprio 1
	s_barrier
	v_mfma_f32_16x16x32_bf16 v[60:63], v[128:131], v[160:163], v[60:63]
	v_mfma_f32_16x16x32_bf16 v[60:63], v[132:135], v[182:185], v[60:63]
	v_mfma_f32_16x16x32_bf16 v[48:51], v[128:131], v[186:189], v[48:51]
	v_mfma_f32_16x16x32_bf16 v[48:51], v[132:135], v[190:193], v[48:51]
	v_mfma_f32_16x16x32_bf16 v[32:35], v[128:131], v[204:207], v[32:35]
	v_mfma_f32_16x16x32_bf16 v[32:35], v[132:135], v[208:211], v[32:35]
	v_mfma_f32_16x16x32_bf16 v[16:19], v[128:131], v[212:215], v[16:19]
	v_mfma_f32_16x16x32_bf16 v[16:19], v[132:135], v[216:219], v[16:19]
	v_mfma_f32_16x16x32_bf16 v[56:59], v[136:139], v[160:163], v[56:59]
	v_mfma_f32_16x16x32_bf16 v[56:59], v[140:143], v[182:185], v[56:59]
	v_mfma_f32_16x16x32_bf16 v[40:43], v[136:139], v[186:189], v[40:43]
	v_mfma_f32_16x16x32_bf16 v[40:43], v[140:143], v[190:193], v[40:43]
	v_mfma_f32_16x16x32_bf16 v[24:27], v[136:139], v[204:207], v[24:27]
	v_mfma_f32_16x16x32_bf16 v[24:27], v[140:143], v[208:211], v[24:27]
	v_mfma_f32_16x16x32_bf16 v[8:11], v[136:139], v[212:215], v[8:11]
	v_mfma_f32_16x16x32_bf16 v[8:11], v[140:143], v[216:219], v[8:11]
	s_setprio 0
	s_setprio 1
	v_mfma_f32_16x16x32_bf16 v[52:55], v[144:147], v[160:163], v[52:55]
	v_mfma_f32_16x16x32_bf16 v[52:55], v[148:151], v[182:185], v[52:55]
	v_mfma_f32_16x16x32_bf16 v[36:39], v[144:147], v[186:189], v[36:39]
	v_mfma_f32_16x16x32_bf16 v[36:39], v[148:151], v[190:193], v[36:39]
	v_mfma_f32_16x16x32_bf16 v[20:23], v[144:147], v[204:207], v[20:23]
	v_mfma_f32_16x16x32_bf16 v[20:23], v[148:151], v[208:211], v[20:23]
	v_mfma_f32_16x16x32_bf16 v[4:7], v[144:147], v[212:215], v[4:7]
	v_mfma_f32_16x16x32_bf16 v[4:7], v[148:151], v[216:219], v[4:7]
	v_mfma_f32_16x16x32_bf16 v[44:47], v[152:155], v[160:163], v[44:47]
	v_mfma_f32_16x16x32_bf16 v[44:47], v[156:159], v[182:185], v[44:47]
	v_mfma_f32_16x16x32_bf16 v[28:31], v[152:155], v[186:189], v[28:31]
	v_mfma_f32_16x16x32_bf16 v[28:31], v[156:159], v[190:193], v[28:31]
	v_mfma_f32_16x16x32_bf16 v[12:15], v[152:155], v[204:207], v[12:15]
	v_mfma_f32_16x16x32_bf16 v[12:15], v[156:159], v[208:211], v[12:15]
	v_mfma_f32_16x16x32_bf16 v[0:3], v[152:155], v[212:215], v[0:3]
	v_mfma_f32_16x16x32_bf16 v[0:3], v[156:159], v[216:219], v[0:3]
	s_barrier
	s_setprio 0
	s_add_i32 s49, 0, 0x18000
	s_add_i32 s50, 0, 0x1c000
	v_add_u32_e32 v140, s49, v198
	v_add_u32_e32 v156, s50, v198
	ds_read_b128 v[128:131], v140
	ds_read_b128 v[132:135], v140 offset:1024
	ds_read_b128 v[136:139], v140 offset:2048
	ds_read_b128 v[140:143], v140 offset:3072
	ds_read_b128 v[144:147], v156
	ds_read_b128 v[148:151], v156 offset:1024
	ds_read_b128 v[152:155], v156 offset:2048
	ds_read_b128 v[156:159], v156 offset:3072
	s_add_u32 s26, s26, 0x160000
	s_addc_u32 s27, s27, 0
	s_mov_b32 m0, s34
	v_lshl_add_u64 v[228:229], s[26:27], 0, v[164:165]
	ds_read_b128 v[160:163], v203 offset:32768
	ds_read_b128 v[182:185], v203 offset:33792
	ds_read_b128 v[186:189], v203 offset:34816
	ds_read_b128 v[190:193], v203 offset:35840
	ds_read_b128 v[204:207], v203 offset:36864
	ds_read_b128 v[208:211], v203 offset:37888
	ds_read_b128 v[212:215], v203 offset:38912
	ds_read_b128 v[216:219], v203 offset:39936
	global_load_lds_dwordx4 v[228:229], off
	v_lshl_add_u64 v[228:229], s[26:27], 0, v[168:169]
	s_mov_b32 m0, s35
	s_nop 0
	global_load_lds_dwordx4 v[228:229], off
	s_waitcnt vmcnt(8)
	s_waitcnt lgkmcnt(0)
	s_setprio 1
	s_barrier
; #define PG8_STAGE(bufoff, gbase, voff) do { _Pragma("unroll") for (int _i = 0; _i < 2; ++_i) \
;         __builtin_amdgcn_global_load_lds((const unsigned*)((const char*)(gbase) + (voff)[_i]), (PG8_LAS unsigned*)(lds + (bufoff) + ldsw + _i * 8192), 16, 0, 0); } while (0)
; #define PG8_LDA(dst, b, h) do { _Pragma("unroll") for (int m = 0; m < 4; ++m) _Pragma("unroll") for (int k = 0; k < 2; ++k) dst[m][k] = *(const PG8_LAS bf16x8*)(lds + PG8_SA(b, h) + aoff + m * 2048 + k * 1024); } while (0)
; #define PG8_MMA(ai, bj, At, Bt) do { __builtin_amdgcn_s_setprio(1); _Pragma("unroll") for (int m = 0; m < 4; ++m) _Pragma("unroll") for (int n = 0; n < 2; ++n) _Pragma("unroll") for (int k = 0; k < 2; ++k) \
;         acc[ai][bj][m][n] = __builtin_amdgcn_mfma_f32_16x16x32_bf16(Bt[n][k], At[m][k], acc[ai][bj][m][n], 0, 0, 0); __builtin_amdgcn_s_setprio(0); } while (0)
; #define PG8_WAIT_V(n) asm volatile("s_waitcnt vmcnt(" #n ")" ::: "memory")
; #define PG8_WAIT_L(n) asm volatile("s_waitcnt lgkmcnt(" #n ")" ::: "memory")
; #define PG8_BAR __builtin_amdgcn_s_barrier()
; #define PG8_SCHED __builtin_amdgcn_sched_barrier(0)
; template <class Epi, class Sched, bool ALIGN_EPI = false, bool SP2 = false, bool DUAL = false>
; __device__ __forceinline__ void gemm_phase(PG8_LAS unsigned char* lds, const Gemm g, const Sched& S, const Epi& E) {
;     ...
;             PG8_WAIT_V(8); PG8_WAIT_L(0); PG8_BAR; PG8_MMA(0, 0, At, B0); PG8_MMA(0, 1, At, B1); PG8_BAR; PG8_SCHED;
;             PG8_LDA(At, 1, 1); PG8_STAGE(PG8_SB(1, 0), b3, voffB); PG8_STAGE(PG8_SB(1, 1), b3 + hstep, voffB); PG8_STAGE(PG8_SA(1, 0), a3, voffA);
;             PG8_WAIT_V(8); PG8_WAIT_L(0); PG8_BAR; PG8_MMA(1, 0, At, B0); PG8_MMA(1, 1, At, B1); PG8_BAR; PG8_SCHED;
	v_mfma_f32_16x16x32_bf16 v[124:127], v[128:131], v[160:163], v[124:127]
	v_mfma_f32_16x16x32_bf16 v[124:127], v[132:135], v[182:185], v[124:127]
	v_mfma_f32_16x16x32_bf16 v[112:115], v[128:131], v[186:189], v[112:115]
	v_mfma_f32_16x16x32_bf16 v[112:115], v[132:135], v[190:193], v[112:115]
	v_mfma_f32_16x16x32_bf16 v[96:99], v[128:131], v[204:207], v[96:99]
	v_mfma_f32_16x16x32_bf16 v[96:99], v[132:135], v[208:211], v[96:99]
	v_mfma_f32_16x16x32_bf16 v[80:83], v[128:131], v[212:215], v[80:83]
	v_mfma_f32_16x16x32_bf16 v[80:83], v[132:135], v[216:219], v[80:83]
	v_mfma_f32_16x16x32_bf16 v[120:123], v[136:139], v[160:163], v[120:123]
	v_mfma_f32_16x16x32_bf16 v[120:123], v[140:143], v[182:185], v[120:123]
	v_mfma_f32_16x16x32_bf16 v[104:107], v[136:139], v[186:189], v[104:107]
	v_mfma_f32_16x16x32_bf16 v[104:107], v[140:143], v[190:193], v[104:107]
	v_mfma_f32_16x16x32_bf16 v[88:91], v[136:139], v[204:207], v[88:91]
	v_mfma_f32_16x16x32_bf16 v[88:91], v[140:143], v[208:211], v[88:91]
	v_mfma_f32_16x16x32_bf16 v[72:75], v[136:139], v[212:215], v[72:75]
	v_mfma_f32_16x16x32_bf16 v[72:75], v[140:143], v[216:219], v[72:75]
	s_setprio 0
	s_setprio 1
	v_mfma_f32_16x16x32_bf16 v[116:119], v[144:147], v[160:163], v[116:119]
	v_mfma_f32_16x16x32_bf16 v[116:119], v[148:151], v[182:185], v[116:119]
	v_mfma_f32_16x16x32_bf16 v[100:103], v[144:147], v[186:189], v[100:103]
	v_mfma_f32_16x16x32_bf16 v[100:103], v[148:151], v[190:193], v[100:103]
	v_mfma_f32_16x16x32_bf16 v[84:87], v[144:147], v[204:207], v[84:87]
	v_mfma_f32_16x16x32_bf16 v[84:87], v[148:151], v[208:211], v[84:87]
	v_mfma_f32_16x16x32_bf16 v[68:71], v[144:147], v[212:215], v[68:71]
	v_mfma_f32_16x16x32_bf16 v[68:71], v[148:151], v[216:219], v[68:71]
	v_mfma_f32_16x16x32_bf16 v[108:111], v[152:155], v[160:163], v[108:111]
	v_mfma_f32_16x16x32_bf16 v[108:111], v[156:159], v[182:185], v[108:111]
	v_mfma_f32_16x16x32_bf16 v[92:95], v[152:155], v[186:189], v[92:95]
	v_mfma_f32_16x16x32_bf16 v[92:95], v[156:159], v[190:193], v[92:95]
	v_mfma_f32_16x16x32_bf16 v[76:79], v[152:155], v[204:207], v[76:79]
	v_mfma_f32_16x16x32_bf16 v[76:79], v[156:159], v[208:211], v[76:79]
	v_mfma_f32_16x16x32_bf16 v[64:67], v[152:155], v[212:215], v[64:67]
	v_mfma_f32_16x16x32_bf16 v[64:67], v[156:159], v[216:219], v[64:67]
	s_barrier
	s_setprio 0
	s_add_i32 s26, s49, s30
	v_lshl_add_u64 v[220:221], v[220:221], 0, s[18:19]
	s_mov_b32 m0, s26
	ds_read_b128 v[160:163], v203 offset:49152
	ds_read_b128 v[182:185], v203 offset:50176
	ds_read_b128 v[186:189], v203 offset:51200
	ds_read_b128 v[190:193], v203 offset:52224
	ds_read_b128 v[204:207], v203 offset:53248
	ds_read_b128 v[208:211], v203 offset:54272
	ds_read_b128 v[212:215], v203 offset:55296
	ds_read_b128 v[216:219], v203 offset:56320
	global_load_lds_dwordx4 v[220:221], off
	s_add_i32 m0, s26, 0x2000
	s_add_u32 s14, s14, 0x160080
	v_lshl_add_u64 v[220:221], v[222:223], 0, s[18:19]
	s_addc_u32 s15, s15, 0
	s_add_i32 s26, s50, s30
	global_load_lds_dwordx4 v[220:221], off
	v_lshl_add_u64 v[220:221], s[14:15], 0, v[166:167]
	s_mov_b32 m0, s26
	s_nop 0
	global_load_lds_dwordx4 v[220:221], off
	v_lshl_add_u64 v[220:221], s[14:15], 0, v[170:171]
	s_add_i32 m0, s26, 0x2000
	s_nop 0
	global_load_lds_dwordx4 v[220:221], off
	v_lshl_add_u64 v[220:221], v[224:225], 0, s[18:19]
	s_mov_b32 m0, s37
	s_nop 0
	global_load_lds_dwordx4 v[220:221], off
	v_lshl_add_u64 v[220:221], v[226:227], 0, s[18:19]
	s_mov_b32 m0, s38
	s_nop 0
	global_load_lds_dwordx4 v[220:221], off
	s_waitcnt vmcnt(8)
	s_waitcnt lgkmcnt(0)
	s_setprio 1
	s_barrier
	v_mfma_f32_16x16x32_bf16 v[60:63], v[128:131], v[160:163], v[60:63]
	v_mfma_f32_16x16x32_bf16 v[60:63], v[132:135], v[182:185], v[60:63]
	v_mfma_f32_16x16x32_bf16 v[48:51], v[128:131], v[186:189], v[48:51]
	v_mfma_f32_16x16x32_bf16 v[48:51], v[132:135], v[190:193], v[48:51]
	v_mfma_f32_16x16x32_bf16 v[32:35], v[128:131], v[204:207], v[32:35]
	v_mfma_f32_16x16x32_bf16 v[32:35], v[132:135], v[208:211], v[32:35]
	v_mfma_f32_16x16x32_bf16 v[16:19], v[128:131], v[212:215], v[16:19]
	v_mfma_f32_16x16x32_bf16 v[16:19], v[132:135], v[216:219], v[16:19]
	v_mfma_f32_16x16x32_bf16 v[56:59], v[136:139], v[160:163], v[56:59]
	v_mfma_f32_16x16x32_bf16 v[56:59], v[140:143], v[182:185], v[56:59]
	v_mfma_f32_16x16x32_bf16 v[40:43], v[136:139], v[186:189], v[40:43]
	v_mfma_f32_16x16x32_bf16 v[40:43], v[140:143], v[190:193], v[40:43]
	v_mfma_f32_16x16x32_bf16 v[24:27], v[136:139], v[204:207], v[24:27]
	v_mfma_f32_16x16x32_bf16 v[24:27], v[140:143], v[208:211], v[24:27]
	v_mfma_f32_16x16x32_bf16 v[8:11], v[136:139], v[212:215], v[8:11]
	v_mfma_f32_16x16x32_bf16 v[8:11], v[140:143], v[216:219], v[8:11]
	s_setprio 0
	s_setprio 1
	v_mfma_f32_16x16x32_bf16 v[52:55], v[144:147], v[160:163], v[52:55]
	v_mfma_f32_16x16x32_bf16 v[52:55], v[148:151], v[182:185], v[52:55]
	v_mfma_f32_16x16x32_bf16 v[36:39], v[144:147], v[186:189], v[36:39]
	v_mfma_f32_16x16x32_bf16 v[36:39], v[148:151], v[190:193], v[36:39]
	v_mfma_f32_16x16x32_bf16 v[20:23], v[144:147], v[204:207], v[20:23]
	v_mfma_f32_16x16x32_bf16 v[20:23], v[148:151], v[208:211], v[20:23]
	v_mfma_f32_16x16x32_bf16 v[4:7], v[144:147], v[212:215], v[4:7]
	v_mfma_f32_16x16x32_bf16 v[4:7], v[148:151], v[216:219], v[4:7]
	v_mfma_f32_16x16x32_bf16 v[44:47], v[152:155], v[160:163], v[44:47]
	v_mfma_f32_16x16x32_bf16 v[44:47], v[156:159], v[182:185], v[44:47]
	v_mfma_f32_16x16x32_bf16 v[28:31], v[152:155], v[186:189], v[28:31]
	v_mfma_f32_16x16x32_bf16 v[28:31], v[156:159], v[190:193], v[28:31]
	v_mfma_f32_16x16x32_bf16 v[12:15], v[152:155], v[204:207], v[12:15]
	v_mfma_f32_16x16x32_bf16 v[12:15], v[156:159], v[208:211], v[12:15]
	v_mfma_f32_16x16x32_bf16 v[0:3], v[152:155], v[212:215], v[0:3]
	v_mfma_f32_16x16x32_bf16 v[0:3], v[156:159], v[216:219], v[0:3]
	s_barrier
	s_setprio 0
	s_add_i32 s48, s48, 2
	s_add_u32 s24, s24, 0x100
	s_addc_u32 s25, s25, 0
	s_add_u32 s46, s46, 0x100
	s_addc_u32 s47, s47, 0
	s_cmpk_gt_u32 s48, 0x55
	s_cbranch_scc0 .LBB0_1193
	s_and_b64 vcc, exec, s[20:21]
	s_cbranch_vccz .LBB0_1196
	s_barrier
